# v16 + all per-phase s_setprio flips deleted from GEMM mainloops (both halves at prio 0)
# baseline (speedup 1.0000x reference)
.LBB0_543:
	s_ashr_i32 s23, s22, 31
	s_lshl_b64 s[24:25], s[22:23], 19
	ds_read_b128 v[0:3], v165
	ds_read_b128 v[4:7], v165 offset:1024
	ds_read_b128 v[8:11], v165 offset:2048
	ds_read_b128 v[12:15], v165 offset:3072
	ds_read_b128 v[16:19], v166
	ds_read_b128 v[20:23], v166 offset:1024
	ds_read_b128 v[24:27], v166 offset:2048
	ds_read_b128 v[28:31], v166 offset:3072
	s_add_u32 s7, s40, s24
	s_addc_u32 s23, s41, s25
	s_ashr_i32 s21, s20, 31
	s_lshl_b64 s[24:25], s[20:21], 9
	s_add_u32 s24, s7, s24
	s_addc_u32 s25, s23, s25
	s_and_b64 s[26:27], s[4:5], exec
	s_cselect_b32 s37, s25, s29
	s_cselect_b32 s36, s24, s28
	s_lshl_b64 s[26:27], s[20:21], 17
	s_add_u32 s26, s38, s26
	s_addc_u32 s27, s39, s27
	s_and_b64 s[34:35], s[4:5], exec
	s_cselect_b32 s35, s27, s31
	s_cselect_b32 s34, s26, s30
	s_add_u32 s58, s28, 0x40080
	s_addc_u32 s59, s29, 0
	s_add_i32 s60, s43, 0xc000
	v_lshl_add_u64 v[64:65], s[58:59], 0, v[146:147]
	s_mov_b32 m0, s60
	s_add_i32 s7, s43, 0xe000
	ds_read_b128 v[32:35], v167
	ds_read_b128 v[36:39], v167 offset:1024
	ds_read_b128 v[40:43], v167 offset:2048
	ds_read_b128 v[44:47], v167 offset:3072
	ds_read_b128 v[48:51], v167 offset:4096
	ds_read_b128 v[52:55], v167 offset:5120
	ds_read_b128 v[56:59], v167 offset:6144
	ds_read_b128 v[60:63], v167 offset:7168
	global_load_lds_dwordx4 v[64:65], off
	v_lshl_add_u64 v[64:65], s[58:59], 0, v[142:143]
	s_mov_b32 m0, s7
	s_nop 0
	global_load_lds_dwordx4 v[64:65], off
	s_waitcnt vmcnt(8)
	s_waitcnt lgkmcnt(0)
	s_barrier
	s_waitcnt lgkmcnt(0)
	v_mfma_f32_16x16x32_bf16 v[64:67], v[0:3], v[32:35], 0
	v_mfma_f32_16x16x32_bf16 v[68:71], v[8:11], v[32:35], 0
	v_mfma_f32_16x16x32_bf16 v[72:75], v[0:3], v[40:43], 0
	v_mfma_f32_16x16x32_bf16 v[76:79], v[8:11], v[40:43], 0
	v_mfma_f32_16x16x32_bf16 v[80:83], v[0:3], v[48:51], 0
	v_mfma_f32_16x16x32_bf16 v[84:87], v[8:11], v[48:51], 0
	v_mfma_f32_16x16x32_bf16 v[88:91], v[0:3], v[56:59], 0
	v_mfma_f32_16x16x32_bf16 v[92:95], v[8:11], v[56:59], 0
	v_mfma_f32_16x16x32_bf16 v[64:67], v[4:7], v[36:39], v[64:67]
	v_mfma_f32_16x16x32_bf16 v[68:71], v[12:15], v[36:39], v[68:71]
	v_mfma_f32_16x16x32_bf16 v[72:75], v[4:7], v[44:47], v[72:75]
	v_mfma_f32_16x16x32_bf16 v[76:79], v[12:15], v[44:47], v[76:79]
	v_mfma_f32_16x16x32_bf16 v[80:83], v[4:7], v[52:55], v[80:83]
	v_mfma_f32_16x16x32_bf16 v[84:87], v[12:15], v[52:55], v[84:87]
	v_mfma_f32_16x16x32_bf16 v[88:91], v[4:7], v[60:63], v[88:91]
	v_mfma_f32_16x16x32_bf16 v[92:95], v[12:15], v[60:63], v[92:95]
	v_mfma_f32_16x16x32_bf16 v[96:99], v[16:19], v[32:35], 0
	v_mfma_f32_16x16x32_bf16 v[32:35], v[24:27], v[32:35], 0
	v_mfma_f32_16x16x32_bf16 v[96:99], v[20:23], v[36:39], v[96:99]
	v_mfma_f32_16x16x32_bf16 v[32:35], v[28:31], v[36:39], v[32:35]
	v_mfma_f32_16x16x32_bf16 v[36:39], v[16:19], v[40:43], 0
	v_mfma_f32_16x16x32_bf16 v[40:43], v[24:27], v[40:43], 0
	v_mfma_f32_16x16x32_bf16 v[36:39], v[20:23], v[44:47], v[36:39]
	v_mfma_f32_16x16x32_bf16 v[40:43], v[28:31], v[44:47], v[40:43]
	v_mfma_f32_16x16x32_bf16 v[44:47], v[16:19], v[48:51], 0
	v_mfma_f32_16x16x32_bf16 v[48:51], v[24:27], v[48:51], 0
	v_mfma_f32_16x16x32_bf16 v[44:47], v[20:23], v[52:55], v[44:47]
	v_mfma_f32_16x16x32_bf16 v[48:51], v[28:31], v[52:55], v[48:51]
	v_mfma_f32_16x16x32_bf16 v[52:55], v[16:19], v[56:59], 0
	v_mfma_f32_16x16x32_bf16 v[56:59], v[24:27], v[56:59], 0
	v_mfma_f32_16x16x32_bf16 v[52:55], v[20:23], v[60:63], v[52:55]
	v_mfma_f32_16x16x32_bf16 v[56:59], v[28:31], v[60:63], v[56:59]
	s_barrier
	s_add_i32 s58, s54, s42
	v_lshl_add_u64 v[150:151], s[30:31], 0, v[144:145]
	s_add_i32 s21, s58, 0x2000
	v_lshl_add_u64 v[128:129], v[150:151], 0, s[16:17]
	s_mov_b32 m0, s58
	v_lshl_add_u64 v[152:153], s[30:31], 0, v[140:141]
	s_add_u32 s62, s30, 0x10100
	ds_read_b128 v[60:63], v167 offset:16384
	ds_read_b128 v[100:103], v167 offset:17408
	ds_read_b128 v[104:107], v167 offset:18432
	ds_read_b128 v[108:111], v167 offset:19456
	ds_read_b128 v[112:115], v167 offset:20480
	ds_read_b128 v[116:119], v167 offset:21504
	ds_read_b128 v[120:123], v167 offset:22528
	ds_read_b128 v[124:127], v167 offset:23552
	global_load_lds_dwordx4 v[128:129], off
	v_lshl_add_u64 v[128:129], v[152:153], 0, s[16:17]
	s_mov_b32 m0, s21
	s_addc_u32 s63, s31, 0
	s_add_i32 s23, s55, s42
	global_load_lds_dwordx4 v[128:129], off
	v_lshl_add_u64 v[128:129], s[62:63], 0, v[144:145]
	s_mov_b32 m0, s23
	s_add_i32 s57, s23, 0x2000
	global_load_lds_dwordx4 v[128:129], off
	v_lshl_add_u64 v[128:129], s[62:63], 0, v[140:141]
	s_mov_b32 m0, s57
	v_lshl_add_u64 v[162:163], s[28:29], 0, v[146:147]
	global_load_lds_dwordx4 v[128:129], off
	v_lshl_add_u64 v[128:129], v[162:163], 0, s[16:17]
	s_mov_b32 m0, s43
	v_lshl_add_u64 v[176:177], s[28:29], 0, v[142:143]
	global_load_lds_dwordx4 v[128:129], off
	v_lshl_add_u64 v[128:129], v[176:177], 0, s[16:17]
	s_mov_b32 m0, s44
	s_nop 0
	global_load_lds_dwordx4 v[128:129], off
	s_waitcnt vmcnt(8)
	s_waitcnt lgkmcnt(0)
	s_barrier
	s_waitcnt lgkmcnt(0)
	v_mfma_f32_16x16x32_bf16 v[128:131], v[0:3], v[60:63], 0
	v_mfma_f32_16x16x32_bf16 v[136:139], v[0:3], v[104:107], 0
	v_mfma_f32_16x16x32_bf16 v[158:161], v[0:3], v[112:115], 0
	v_mfma_f32_16x16x32_bf16 v[0:3], v[0:3], v[120:123], 0
	v_mfma_f32_16x16x32_bf16 v[128:131], v[4:7], v[100:103], v[128:131]
	v_mfma_f32_16x16x32_bf16 v[136:139], v[4:7], v[108:111], v[136:139]
	v_mfma_f32_16x16x32_bf16 v[158:161], v[4:7], v[116:119], v[158:161]
	v_mfma_f32_16x16x32_bf16 v[0:3], v[4:7], v[124:127], v[0:3]
	v_mfma_f32_16x16x32_bf16 v[4:7], v[8:11], v[120:123], 0
	v_mfma_f32_16x16x32_bf16 v[132:135], v[8:11], v[60:63], 0
	v_mfma_f32_16x16x32_bf16 v[154:157], v[8:11], v[104:107], 0
	v_mfma_f32_16x16x32_bf16 v[168:171], v[8:11], v[112:115], 0
	v_mfma_f32_16x16x32_bf16 v[4:7], v[12:15], v[124:127], v[4:7]
	v_mfma_f32_16x16x32_bf16 v[132:135], v[12:15], v[100:103], v[132:135]
	v_mfma_f32_16x16x32_bf16 v[154:157], v[12:15], v[108:111], v[154:157]
	v_mfma_f32_16x16x32_bf16 v[168:171], v[12:15], v[116:119], v[168:171]
	v_mfma_f32_16x16x32_bf16 v[8:11], v[16:19], v[60:63], 0
	v_mfma_f32_16x16x32_bf16 v[12:15], v[24:27], v[60:63], 0
	v_mfma_f32_16x16x32_bf16 v[8:11], v[20:23], v[100:103], v[8:11]
	v_mfma_f32_16x16x32_bf16 v[12:15], v[28:31], v[100:103], v[12:15]
	v_mfma_f32_16x16x32_bf16 v[60:63], v[16:19], v[104:107], 0
	v_mfma_f32_16x16x32_bf16 v[100:103], v[24:27], v[104:107], 0
	v_mfma_f32_16x16x32_bf16 v[104:107], v[16:19], v[112:115], 0
	v_mfma_f32_16x16x32_bf16 v[16:19], v[16:19], v[120:123], 0
	v_mfma_f32_16x16x32_bf16 v[60:63], v[20:23], v[108:111], v[60:63]
	v_mfma_f32_16x16x32_bf16 v[100:103], v[28:31], v[108:111], v[100:103]
	v_mfma_f32_16x16x32_bf16 v[104:107], v[20:23], v[116:119], v[104:107]
	v_mfma_f32_16x16x32_bf16 v[108:111], v[24:27], v[112:115], 0
	v_mfma_f32_16x16x32_bf16 v[16:19], v[20:23], v[124:127], v[16:19]
	v_mfma_f32_16x16x32_bf16 v[20:23], v[24:27], v[120:123], 0
	v_mfma_f32_16x16x32_bf16 v[108:111], v[28:31], v[116:119], v[108:111]
	v_mfma_f32_16x16x32_bf16 v[20:23], v[28:31], v[124:127], v[20:23]
	s_barrier
	s_add_i32 s61, 0, 0x18000
	s_add_i32 s64, 0, 0x1c000
	v_add_u32_e32 v148, s61, v164
	v_add_u32_e32 v238, s64, v164
	ds_read_b128 v[24:27], v148
	ds_read_b128 v[28:31], v148 offset:1024
	ds_read_b128 v[112:115], v148 offset:2048
	ds_read_b128 v[116:119], v148 offset:3072
	ds_read_b128 v[120:123], v238
	ds_read_b128 v[124:127], v238 offset:1024
	ds_read_b128 v[172:175], v238 offset:2048
	ds_read_b128 v[180:183], v238 offset:3072
	s_add_u32 s62, s28, 0x40100
	s_addc_u32 s63, s29, 0
	s_mov_b32 m0, s45
	v_lshl_add_u64 v[178:179], s[62:63], 0, v[146:147]
	ds_read_b128 v[184:187], v167 offset:32768
	ds_read_b128 v[188:191], v167 offset:33792
	ds_read_b128 v[192:195], v167 offset:34816
	ds_read_b128 v[196:199], v167 offset:35840
	ds_read_b128 v[200:203], v167 offset:36864
	ds_read_b128 v[204:207], v167 offset:37888
	ds_read_b128 v[214:217], v167 offset:38912
	ds_read_b128 v[218:221], v167 offset:39936
	global_load_lds_dwordx4 v[178:179], off
	v_lshl_add_u64 v[178:179], s[62:63], 0, v[142:143]
	s_mov_b32 m0, s46
	s_nop 0
	global_load_lds_dwordx4 v[178:179], off
	s_waitcnt vmcnt(8)
	s_waitcnt lgkmcnt(0)
	s_barrier
	s_waitcnt lgkmcnt(0)
	v_mfma_f32_16x16x32_bf16 v[64:67], v[24:27], v[184:187], v[64:67]
	v_mfma_f32_16x16x32_bf16 v[68:71], v[112:115], v[184:187], v[68:71]
	v_mfma_f32_16x16x32_bf16 v[72:75], v[24:27], v[192:195], v[72:75]
	v_mfma_f32_16x16x32_bf16 v[76:79], v[112:115], v[192:195], v[76:79]
	v_mfma_f32_16x16x32_bf16 v[80:83], v[24:27], v[200:203], v[80:83]
	v_mfma_f32_16x16x32_bf16 v[84:87], v[112:115], v[200:203], v[84:87]
	v_mfma_f32_16x16x32_bf16 v[88:91], v[24:27], v[214:217], v[88:91]
	v_mfma_f32_16x16x32_bf16 v[92:95], v[112:115], v[214:217], v[92:95]
	v_mfma_f32_16x16x32_bf16 v[64:67], v[28:31], v[188:191], v[64:67]
	v_mfma_f32_16x16x32_bf16 v[68:71], v[116:119], v[188:191], v[68:71]
	v_mfma_f32_16x16x32_bf16 v[72:75], v[28:31], v[196:199], v[72:75]
	v_mfma_f32_16x16x32_bf16 v[76:79], v[116:119], v[196:199], v[76:79]
	v_mfma_f32_16x16x32_bf16 v[80:83], v[28:31], v[204:207], v[80:83]
	v_mfma_f32_16x16x32_bf16 v[84:87], v[116:119], v[204:207], v[84:87]
	v_mfma_f32_16x16x32_bf16 v[88:91], v[28:31], v[218:221], v[88:91]
	v_mfma_f32_16x16x32_bf16 v[92:95], v[116:119], v[218:221], v[92:95]
	v_mfma_f32_16x16x32_bf16 v[96:99], v[120:123], v[184:187], v[96:99]
	v_mfma_f32_16x16x32_bf16 v[32:35], v[172:175], v[184:187], v[32:35]
	v_mfma_f32_16x16x32_bf16 v[36:39], v[120:123], v[192:195], v[36:39]
	v_mfma_f32_16x16x32_bf16 v[40:43], v[172:175], v[192:195], v[40:43]
	v_mfma_f32_16x16x32_bf16 v[44:47], v[120:123], v[200:203], v[44:47]
	v_mfma_f32_16x16x32_bf16 v[48:51], v[172:175], v[200:203], v[48:51]
	v_mfma_f32_16x16x32_bf16 v[52:55], v[120:123], v[214:217], v[52:55]
	v_mfma_f32_16x16x32_bf16 v[56:59], v[172:175], v[214:217], v[56:59]
	v_mfma_f32_16x16x32_bf16 v[96:99], v[124:127], v[188:191], v[96:99]
	v_mfma_f32_16x16x32_bf16 v[32:35], v[180:183], v[188:191], v[32:35]
	v_mfma_f32_16x16x32_bf16 v[36:39], v[124:127], v[196:199], v[36:39]
	v_mfma_f32_16x16x32_bf16 v[40:43], v[180:183], v[196:199], v[40:43]
	v_mfma_f32_16x16x32_bf16 v[44:47], v[124:127], v[204:207], v[44:47]
	v_mfma_f32_16x16x32_bf16 v[48:51], v[180:183], v[204:207], v[48:51]
	v_mfma_f32_16x16x32_bf16 v[52:55], v[124:127], v[218:221], v[52:55]
	v_mfma_f32_16x16x32_bf16 v[56:59], v[180:183], v[218:221], v[56:59]
	s_barrier
	s_add_i32 s61, s61, s42
	s_add_i32 s59, s61, 0x2000
	v_lshl_add_u64 v[150:151], v[150:151], 0, s[18:19]
	s_mov_b32 m0, s61
	s_add_u32 s62, s30, 0x10180
	ds_read_b128 v[184:187], v167 offset:49152
	ds_read_b128 v[188:191], v167 offset:50176
	ds_read_b128 v[192:195], v167 offset:51200
	ds_read_b128 v[196:199], v167 offset:52224
	ds_read_b128 v[200:203], v167 offset:53248
	ds_read_b128 v[204:207], v167 offset:54272
	ds_read_b128 v[214:217], v167 offset:55296
	ds_read_b128 v[218:221], v167 offset:56320
	global_load_lds_dwordx4 v[150:151], off
	v_lshl_add_u64 v[150:151], v[152:153], 0, s[18:19]
	s_mov_b32 m0, s59
	s_addc_u32 s63, s31, 0
	s_add_i32 s30, s64, s42
	global_load_lds_dwordx4 v[150:151], off
	v_lshl_add_u64 v[150:151], s[62:63], 0, v[144:145]
	s_mov_b32 m0, s30
	s_add_i32 s31, s30, 0x2000
	global_load_lds_dwordx4 v[150:151], off
	v_lshl_add_u64 v[150:151], s[62:63], 0, v[140:141]
	s_mov_b32 m0, s31
	s_nop 0
	global_load_lds_dwordx4 v[150:151], off
	v_lshl_add_u64 v[150:151], v[162:163], 0, s[18:19]
	s_mov_b32 m0, s50
	s_nop 0
	global_load_lds_dwordx4 v[150:151], off
	v_lshl_add_u64 v[150:151], v[176:177], 0, s[18:19]
	s_mov_b32 m0, s51
	s_nop 0
	global_load_lds_dwordx4 v[150:151], off
	s_waitcnt vmcnt(8)
	s_waitcnt lgkmcnt(0)
	s_barrier
	s_waitcnt lgkmcnt(0)
	v_mfma_f32_16x16x32_bf16 v[128:131], v[24:27], v[184:187], v[128:131]
	v_mfma_f32_16x16x32_bf16 v[0:3], v[24:27], v[214:217], v[0:3]
	v_mfma_f32_16x16x32_bf16 v[4:7], v[112:115], v[214:217], v[4:7]
	v_mfma_f32_16x16x32_bf16 v[128:131], v[28:31], v[188:191], v[128:131]
	v_mfma_f32_16x16x32_bf16 v[132:135], v[112:115], v[184:187], v[132:135]
	v_mfma_f32_16x16x32_bf16 v[136:139], v[24:27], v[192:195], v[136:139]
	v_mfma_f32_16x16x32_bf16 v[154:157], v[112:115], v[192:195], v[154:157]
	v_mfma_f32_16x16x32_bf16 v[158:161], v[24:27], v[200:203], v[158:161]
	v_mfma_f32_16x16x32_bf16 v[168:171], v[112:115], v[200:203], v[168:171]
	v_mfma_f32_16x16x32_bf16 v[0:3], v[28:31], v[218:221], v[0:3]
	v_mfma_f32_16x16x32_bf16 v[4:7], v[116:119], v[218:221], v[4:7]
	v_mfma_f32_16x16x32_bf16 v[132:135], v[116:119], v[188:191], v[132:135]
	v_mfma_f32_16x16x32_bf16 v[136:139], v[28:31], v[196:199], v[136:139]
	v_mfma_f32_16x16x32_bf16 v[154:157], v[116:119], v[196:199], v[154:157]
	v_mfma_f32_16x16x32_bf16 v[158:161], v[28:31], v[204:207], v[158:161]
	v_mfma_f32_16x16x32_bf16 v[168:171], v[116:119], v[204:207], v[168:171]
	v_mfma_f32_16x16x32_bf16 v[8:11], v[120:123], v[184:187], v[8:11]
	v_mfma_f32_16x16x32_bf16 v[12:15], v[172:175], v[184:187], v[12:15]
	v_mfma_f32_16x16x32_bf16 v[24:27], v[120:123], v[192:195], v[60:63]
	v_mfma_f32_16x16x32_bf16 v[28:31], v[172:175], v[192:195], v[100:103]
	v_mfma_f32_16x16x32_bf16 v[60:63], v[120:123], v[200:203], v[104:107]
	v_mfma_f32_16x16x32_bf16 v[100:103], v[172:175], v[200:203], v[108:111]
	v_mfma_f32_16x16x32_bf16 v[16:19], v[120:123], v[214:217], v[16:19]
	v_mfma_f32_16x16x32_bf16 v[20:23], v[172:175], v[214:217], v[20:23]
	v_mfma_f32_16x16x32_bf16 v[8:11], v[124:127], v[188:191], v[8:11]
	v_mfma_f32_16x16x32_bf16 v[12:15], v[180:183], v[188:191], v[12:15]
	v_mfma_f32_16x16x32_bf16 v[24:27], v[124:127], v[196:199], v[24:27]
	v_mfma_f32_16x16x32_bf16 v[28:31], v[180:183], v[196:199], v[28:31]
	v_mfma_f32_16x16x32_bf16 v[60:63], v[124:127], v[204:207], v[60:63]
	v_mfma_f32_16x16x32_bf16 v[100:103], v[180:183], v[204:207], v[100:103]
	v_mfma_f32_16x16x32_bf16 v[16:19], v[124:127], v[218:221], v[16:19]
	v_mfma_f32_16x16x32_bf16 v[20:23], v[180:183], v[218:221], v[20:23]
	s_barrier
	ds_read_b128 v[104:107], v165
	ds_read_b128 v[108:111], v165 offset:1024
	ds_read_b128 v[112:115], v165 offset:2048
	ds_read_b128 v[116:119], v165 offset:3072
	ds_read_b128 v[120:123], v166
	ds_read_b128 v[124:127], v166 offset:1024
	ds_read_b128 v[172:175], v166 offset:2048
	ds_read_b128 v[180:183], v166 offset:3072
	s_add_u32 s28, s28, 0x40180
	s_addc_u32 s29, s29, 0
	s_mov_b32 m0, s60
	v_lshl_add_u64 v[150:151], s[28:29], 0, v[146:147]
	ds_read_b128 v[184:187], v167
	ds_read_b128 v[188:191], v167 offset:1024
	ds_read_b128 v[192:195], v167 offset:2048
	ds_read_b128 v[196:199], v167 offset:3072
	ds_read_b128 v[200:203], v167 offset:4096
	ds_read_b128 v[204:207], v167 offset:5120
	ds_read_b128 v[214:217], v167 offset:6144
	ds_read_b128 v[218:221], v167 offset:7168
	global_load_lds_dwordx4 v[150:151], off
	v_lshl_add_u64 v[150:151], s[28:29], 0, v[142:143]
	s_mov_b32 m0, s7
	s_nop 0
	global_load_lds_dwordx4 v[150:151], off
	s_waitcnt vmcnt(8)
	s_waitcnt lgkmcnt(0)
	s_barrier
	s_waitcnt lgkmcnt(0)
	v_mfma_f32_16x16x32_bf16 v[64:67], v[104:107], v[184:187], v[64:67]
	v_mfma_f32_16x16x32_bf16 v[68:71], v[112:115], v[184:187], v[68:71]
	v_mfma_f32_16x16x32_bf16 v[72:75], v[104:107], v[192:195], v[72:75]
	v_mfma_f32_16x16x32_bf16 v[76:79], v[112:115], v[192:195], v[76:79]
	v_mfma_f32_16x16x32_bf16 v[80:83], v[104:107], v[200:203], v[80:83]
	v_mfma_f32_16x16x32_bf16 v[84:87], v[112:115], v[200:203], v[84:87]
	v_mfma_f32_16x16x32_bf16 v[88:91], v[104:107], v[214:217], v[88:91]
	v_mfma_f32_16x16x32_bf16 v[64:67], v[108:111], v[188:191], v[64:67]
	v_mfma_f32_16x16x32_bf16 v[68:71], v[116:119], v[188:191], v[68:71]
	v_mfma_f32_16x16x32_bf16 v[72:75], v[108:111], v[196:199], v[72:75]
	v_mfma_f32_16x16x32_bf16 v[76:79], v[116:119], v[196:199], v[76:79]
	v_mfma_f32_16x16x32_bf16 v[80:83], v[108:111], v[204:207], v[80:83]
	v_mfma_f32_16x16x32_bf16 v[84:87], v[116:119], v[204:207], v[84:87]
	v_mfma_f32_16x16x32_bf16 v[222:225], v[108:111], v[218:221], v[88:91]
	v_mfma_f32_16x16x32_bf16 v[88:91], v[112:115], v[214:217], v[92:95]
	v_mfma_f32_16x16x32_bf16 v[226:229], v[116:119], v[218:221], v[88:91]
	v_mfma_f32_16x16x32_bf16 v[88:91], v[120:123], v[184:187], v[96:99]
	v_mfma_f32_16x16x32_bf16 v[32:35], v[172:175], v[184:187], v[32:35]
	v_mfma_f32_16x16x32_bf16 v[36:39], v[120:123], v[192:195], v[36:39]
	v_mfma_f32_16x16x32_bf16 v[40:43], v[172:175], v[192:195], v[40:43]
	v_mfma_f32_16x16x32_bf16 v[44:47], v[120:123], v[200:203], v[44:47]
	v_mfma_f32_16x16x32_bf16 v[48:51], v[172:175], v[200:203], v[48:51]
	v_mfma_f32_16x16x32_bf16 v[52:55], v[120:123], v[214:217], v[52:55]
	v_mfma_f32_16x16x32_bf16 v[56:59], v[172:175], v[214:217], v[56:59]
	v_mfma_f32_16x16x32_bf16 v[96:99], v[124:127], v[188:191], v[88:91]
	v_mfma_f32_16x16x32_bf16 v[32:35], v[180:183], v[188:191], v[32:35]
	v_mfma_f32_16x16x32_bf16 v[36:39], v[124:127], v[196:199], v[36:39]
	v_mfma_f32_16x16x32_bf16 v[40:43], v[180:183], v[196:199], v[40:43]
	v_mfma_f32_16x16x32_bf16 v[44:47], v[124:127], v[204:207], v[44:47]
	v_mfma_f32_16x16x32_bf16 v[48:51], v[180:183], v[204:207], v[48:51]
	v_mfma_f32_16x16x32_bf16 v[52:55], v[124:127], v[218:221], v[52:55]
	v_mfma_f32_16x16x32_bf16 v[56:59], v[180:183], v[218:221], v[56:59]
	s_barrier
	s_mov_b32 m0, s58
	v_lshl_add_u64 v[162:163], s[34:35], 0, v[144:145]
	s_add_u32 s28, s34, 0x10000
	ds_read_b128 v[88:91], v167 offset:16384
	ds_read_b128 v[92:95], v167 offset:17408
	ds_read_b128 v[184:187], v167 offset:18432
	ds_read_b128 v[188:191], v167 offset:19456
	ds_read_b128 v[192:195], v167 offset:20480
	ds_read_b128 v[196:199], v167 offset:21504
	ds_read_b128 v[200:203], v167 offset:22528
	ds_read_b128 v[204:207], v167 offset:23552
	global_load_lds_dwordx4 v[162:163], off
	v_lshl_add_u64 v[210:211], s[34:35], 0, v[140:141]
	s_mov_b32 m0, s21
	s_addc_u32 s29, s35, 0
	global_load_lds_dwordx4 v[210:211], off
	v_lshl_add_u64 v[150:151], s[28:29], 0, v[144:145]
	s_mov_b32 m0, s23
	v_lshl_add_u64 v[250:251], s[36:37], 0, v[146:147]
	global_load_lds_dwordx4 v[150:151], off
	v_lshl_add_u64 v[150:151], s[28:29], 0, v[140:141]
	s_mov_b32 m0, s57
	v_lshl_add_u64 v[212:213], s[36:37], 0, v[142:143]
	global_load_lds_dwordx4 v[150:151], off
	s_mov_b32 m0, s43
	s_nop 0
	global_load_lds_dwordx4 v[250:251], off
	s_mov_b32 m0, s44
	s_nop 0
	global_load_lds_dwordx4 v[212:213], off
	s_waitcnt vmcnt(8)
	s_waitcnt lgkmcnt(0)
	s_barrier
	s_waitcnt lgkmcnt(0)
	v_mfma_f32_16x16x32_bf16 v[128:131], v[104:107], v[88:91], v[128:131]
	v_mfma_f32_16x16x32_bf16 v[214:217], v[108:111], v[92:95], v[128:131]
	v_mfma_f32_16x16x32_bf16 v[128:131], v[112:115], v[88:91], v[132:135]
	v_mfma_f32_16x16x32_bf16 v[132:135], v[116:119], v[92:95], v[128:131]
	v_mfma_f32_16x16x32_bf16 v[128:131], v[104:107], v[184:187], v[136:139]
	v_mfma_f32_16x16x32_bf16 v[136:139], v[108:111], v[188:191], v[128:131]
	v_mfma_f32_16x16x32_bf16 v[128:131], v[112:115], v[184:187], v[154:157]
	v_mfma_f32_16x16x32_bf16 v[154:157], v[116:119], v[188:191], v[128:131]
	v_mfma_f32_16x16x32_bf16 v[128:131], v[104:107], v[192:195], v[158:161]
	v_mfma_f32_16x16x32_bf16 v[0:3], v[104:107], v[200:203], v[0:3]
	v_mfma_f32_16x16x32_bf16 v[4:7], v[112:115], v[200:203], v[4:7]
	v_mfma_f32_16x16x32_bf16 v[158:161], v[108:111], v[196:199], v[128:131]
	v_mfma_f32_16x16x32_bf16 v[128:131], v[112:115], v[192:195], v[168:171]
	v_mfma_f32_16x16x32_bf16 v[0:3], v[108:111], v[204:207], v[0:3]
	v_mfma_f32_16x16x32_bf16 v[4:7], v[116:119], v[204:207], v[4:7]
	v_mfma_f32_16x16x32_bf16 v[168:171], v[116:119], v[196:199], v[128:131]
	v_mfma_f32_16x16x32_bf16 v[8:11], v[120:123], v[88:91], v[8:11]
	v_mfma_f32_16x16x32_bf16 v[218:221], v[124:127], v[92:95], v[8:11]
	v_mfma_f32_16x16x32_bf16 v[8:11], v[172:175], v[88:91], v[12:15]
	v_mfma_f32_16x16x32_bf16 v[230:233], v[180:183], v[92:95], v[8:11]
	v_mfma_f32_16x16x32_bf16 v[8:11], v[120:123], v[184:187], v[24:27]
	v_mfma_f32_16x16x32_bf16 v[234:237], v[124:127], v[188:191], v[8:11]
	v_mfma_f32_16x16x32_bf16 v[8:11], v[172:175], v[184:187], v[28:31]
	v_mfma_f32_16x16x32_bf16 v[184:187], v[180:183], v[188:191], v[8:11]
	v_mfma_f32_16x16x32_bf16 v[8:11], v[120:123], v[192:195], v[60:63]
	v_mfma_f32_16x16x32_bf16 v[188:191], v[124:127], v[196:199], v[8:11]
	v_mfma_f32_16x16x32_bf16 v[8:11], v[172:175], v[192:195], v[100:103]
	v_mfma_f32_16x16x32_bf16 v[192:195], v[180:183], v[196:199], v[8:11]
	v_mfma_f32_16x16x32_bf16 v[8:11], v[120:123], v[200:203], v[16:19]
	v_mfma_f32_16x16x32_bf16 v[124:127], v[124:127], v[204:207], v[8:11]
	v_mfma_f32_16x16x32_bf16 v[8:11], v[172:175], v[200:203], v[20:23]
	v_mfma_f32_16x16x32_bf16 v[172:175], v[180:183], v[204:207], v[8:11]
	s_barrier
	s_nop 4
	ds_read_b128 v[8:11], v148
	ds_read_b128 v[12:15], v148 offset:1024
	ds_read_b128 v[16:19], v148 offset:2048
	ds_read_b128 v[20:23], v148 offset:3072
	ds_read_b128 v[180:183], v238
	ds_read_b128 v[196:199], v238 offset:1024
	ds_read_b128 v[200:203], v238 offset:2048
	ds_read_b128 v[204:207], v238 offset:3072
	s_add_u32 s28, s36, 0x40000
	s_addc_u32 s29, s37, 0
	s_mov_b32 m0, s45
	v_lshl_add_u64 v[88:89], s[28:29], 0, v[146:147]
	ds_read_b128 v[24:27], v167 offset:32768
	ds_read_b128 v[28:31], v167 offset:33792
	ds_read_b128 v[60:63], v167 offset:34816
	ds_read_b128 v[238:241], v167 offset:35840
	ds_read_b128 v[242:245], v167 offset:36864
	ds_read_b128 v[246:249], v167 offset:37888
	ds_read_b128 v[176:179], v167 offset:38912
	ds_read_b128 v[150:153], v167 offset:39936
	global_load_lds_dwordx4 v[88:89], off
	v_lshl_add_u64 v[88:89], s[28:29], 0, v[142:143]
	s_mov_b32 m0, s46
	s_nop 0
	global_load_lds_dwordx4 v[88:89], off
	s_waitcnt vmcnt(8)
	s_waitcnt lgkmcnt(0)
	s_barrier
	s_waitcnt lgkmcnt(0)
	v_mfma_f32_16x16x32_bf16 v[64:67], v[8:11], v[24:27], v[64:67]
	v_mfma_f32_16x16x32_bf16 v[128:131], v[12:15], v[28:31], v[64:67]
	v_mfma_f32_16x16x32_bf16 v[64:67], v[16:19], v[24:27], v[68:71]
	v_mfma_f32_16x16x32_bf16 v[120:123], v[20:23], v[28:31], v[64:67]
	v_mfma_f32_16x16x32_bf16 v[64:67], v[8:11], v[60:63], v[72:75]
	v_mfma_f32_16x16x32_bf16 v[108:111], v[12:15], v[238:241], v[64:67]
	v_mfma_f32_16x16x32_bf16 v[64:67], v[16:19], v[60:63], v[76:79]
	v_mfma_f32_16x16x32_bf16 v[104:107], v[20:23], v[238:241], v[64:67]
	v_mfma_f32_16x16x32_bf16 v[64:67], v[8:11], v[242:245], v[80:83]
	v_mfma_f32_16x16x32_bf16 v[92:95], v[12:15], v[246:249], v[64:67]
	v_mfma_f32_16x16x32_bf16 v[64:67], v[16:19], v[242:245], v[84:87]
	v_mfma_f32_16x16x32_bf16 v[88:91], v[20:23], v[246:249], v[64:67]
	v_mfma_f32_16x16x32_bf16 v[64:67], v[8:11], v[176:179], v[222:225]
	v_mfma_f32_16x16x32_bf16 v[76:79], v[12:15], v[150:153], v[64:67]
	v_mfma_f32_16x16x32_bf16 v[64:67], v[16:19], v[176:179], v[226:229]
	v_mfma_f32_16x16x32_bf16 v[72:75], v[20:23], v[150:153], v[64:67]
	v_mfma_f32_16x16x32_bf16 v[64:67], v[180:183], v[24:27], v[96:99]
	v_mfma_f32_16x16x32_bf16 v[24:27], v[200:203], v[24:27], v[32:35]
	v_mfma_f32_16x16x32_bf16 v[112:115], v[204:207], v[28:31], v[24:27]
	v_mfma_f32_16x16x32_bf16 v[24:27], v[180:183], v[60:63], v[36:39]
	v_mfma_f32_16x16x32_bf16 v[100:103], v[196:199], v[238:241], v[24:27]
	v_mfma_f32_16x16x32_bf16 v[24:27], v[200:203], v[60:63], v[40:43]
	v_mfma_f32_16x16x32_bf16 v[96:99], v[204:207], v[238:241], v[24:27]
	v_mfma_f32_16x16x32_bf16 v[24:27], v[180:183], v[242:245], v[44:47]
	v_mfma_f32_16x16x32_bf16 v[84:87], v[196:199], v[246:249], v[24:27]
	v_mfma_f32_16x16x32_bf16 v[24:27], v[200:203], v[242:245], v[48:51]
	v_mfma_f32_16x16x32_bf16 v[80:83], v[204:207], v[246:249], v[24:27]
	v_mfma_f32_16x16x32_bf16 v[24:27], v[180:183], v[176:179], v[52:55]
	v_mfma_f32_16x16x32_bf16 v[68:71], v[196:199], v[150:153], v[24:27]
	v_mfma_f32_16x16x32_bf16 v[24:27], v[200:203], v[176:179], v[56:59]
	v_mfma_f32_16x16x32_bf16 v[116:119], v[196:199], v[28:31], v[64:67]
	v_mfma_f32_16x16x32_bf16 v[64:67], v[204:207], v[150:153], v[24:27]
	s_barrier
	s_mov_b32 m0, s61
	s_nop 2
	v_lshl_add_u64 v[24:25], v[162:163], 0, s[10:11]
	s_add_u32 s28, s34, 0x10080
	ds_read_b128 v[32:35], v167 offset:49152
	ds_read_b128 v[36:39], v167 offset:50176
	ds_read_b128 v[150:153], v167 offset:51200
	ds_read_b128 v[176:179], v167 offset:52224
	ds_read_b128 v[222:225], v167 offset:53248
	ds_read_b128 v[226:229], v167 offset:54272
	ds_read_b128 v[238:241], v167 offset:55296
	ds_read_b128 v[242:245], v167 offset:56320
	global_load_lds_dwordx4 v[24:25], off
	v_lshl_add_u64 v[24:25], v[210:211], 0, s[10:11]
	s_mov_b32 m0, s59
	s_addc_u32 s29, s35, 0
	global_load_lds_dwordx4 v[24:25], off
	v_lshl_add_u64 v[24:25], s[28:29], 0, v[144:145]
	s_mov_b32 m0, s30
	s_nop 0
	global_load_lds_dwordx4 v[24:25], off
	v_lshl_add_u64 v[24:25], s[28:29], 0, v[140:141]
	s_mov_b32 m0, s31
	s_nop 0
	global_load_lds_dwordx4 v[24:25], off
	v_lshl_add_u64 v[24:25], v[250:251], 0, s[10:11]
	s_mov_b32 m0, s50
	s_nop 0
	global_load_lds_dwordx4 v[24:25], off
	v_lshl_add_u64 v[24:25], v[212:213], 0, s[10:11]
	s_mov_b32 m0, s51
	s_nop 0
	global_load_lds_dwordx4 v[24:25], off
	s_waitcnt vmcnt(8)
	s_waitcnt lgkmcnt(0)
	s_barrier
	s_waitcnt lgkmcnt(0)
	v_mfma_f32_16x16x32_bf16 v[24:27], v[8:11], v[32:35], v[214:217]
	v_mfma_f32_16x16x32_bf16 v[60:63], v[12:15], v[36:39], v[24:27]
	v_mfma_f32_16x16x32_bf16 v[24:27], v[16:19], v[32:35], v[132:135]
	v_mfma_f32_16x16x32_bf16 v[56:59], v[20:23], v[36:39], v[24:27]
	v_mfma_f32_16x16x32_bf16 v[24:27], v[8:11], v[150:153], v[136:139]
	v_mfma_f32_16x16x32_bf16 v[44:47], v[12:15], v[176:179], v[24:27]
	v_mfma_f32_16x16x32_bf16 v[24:27], v[16:19], v[150:153], v[154:157]
	v_mfma_f32_16x16x32_bf16 v[40:43], v[20:23], v[176:179], v[24:27]
	v_mfma_f32_16x16x32_bf16 v[24:27], v[8:11], v[222:225], v[158:161]
	v_mfma_f32_16x16x32_bf16 v[0:3], v[8:11], v[238:241], v[0:3]
	v_mfma_f32_16x16x32_bf16 v[28:31], v[12:15], v[226:229], v[24:27]
	v_mfma_f32_16x16x32_bf16 v[24:27], v[16:19], v[222:225], v[168:171]
	v_mfma_f32_16x16x32_bf16 v[12:15], v[12:15], v[242:245], v[0:3]
	v_mfma_f32_16x16x32_bf16 v[0:3], v[16:19], v[238:241], v[4:7]
	v_mfma_f32_16x16x32_bf16 v[24:27], v[20:23], v[226:229], v[24:27]
	v_mfma_f32_16x16x32_bf16 v[8:11], v[20:23], v[242:245], v[0:3]
	v_mfma_f32_16x16x32_bf16 v[0:3], v[180:183], v[32:35], v[218:221]
	v_mfma_f32_16x16x32_bf16 v[52:55], v[196:199], v[36:39], v[0:3]
	v_mfma_f32_16x16x32_bf16 v[0:3], v[200:203], v[32:35], v[230:233]
	v_mfma_f32_16x16x32_bf16 v[48:51], v[204:207], v[36:39], v[0:3]
	v_mfma_f32_16x16x32_bf16 v[0:3], v[180:183], v[150:153], v[234:237]
	v_mfma_f32_16x16x32_bf16 v[36:39], v[196:199], v[176:179], v[0:3]
	v_mfma_f32_16x16x32_bf16 v[0:3], v[200:203], v[150:153], v[184:187]
	v_mfma_f32_16x16x32_bf16 v[32:35], v[204:207], v[176:179], v[0:3]
	v_mfma_f32_16x16x32_bf16 v[0:3], v[180:183], v[222:225], v[188:191]
	v_mfma_f32_16x16x32_bf16 v[20:23], v[196:199], v[226:229], v[0:3]
	v_mfma_f32_16x16x32_bf16 v[0:3], v[200:203], v[222:225], v[192:195]
	v_mfma_f32_16x16x32_bf16 v[16:19], v[204:207], v[226:229], v[0:3]
	v_mfma_f32_16x16x32_bf16 v[0:3], v[180:183], v[238:241], v[124:127]
	v_mfma_f32_16x16x32_bf16 v[4:7], v[196:199], v[242:245], v[0:3]
	v_mfma_f32_16x16x32_bf16 v[0:3], v[200:203], v[238:241], v[172:175]
	v_mfma_f32_16x16x32_bf16 v[0:3], v[204:207], v[242:245], v[0:3]
	s_barrier
	s_andn2_b64 vcc, exec, s[12:13]
	s_cbranch_vccnz .LBB0_545
	s_barrier

.LBB0_620:
	s_add_u32 s4, s2, 0xfffc0080
	s_addc_u32 s5, s3, -1
	s_add_i32 s55, 0, 0x10000
	s_cmp_eq_u32 s54, 12
	s_cselect_b32 s9, s11, s5
	s_cselect_b32 s8, s25, s4
	v_add_u32_e32 v0, s55, v167
	s_cselect_b32 s5, s23, s53
	s_cselect_b32 s4, s51, s52
	s_add_i32 s58, 0, 0x14000
	ds_read_b128 v[106:109], v0
	ds_read_b128 v[110:113], v0 offset:1024
	ds_read_b128 v[114:117], v0 offset:2048
	ds_read_b128 v[118:121], v0 offset:3072
	v_add_u32_e32 v0, s58, v167
	ds_read_b128 v[146:149], v0
	ds_read_b128 v[150:153], v0 offset:1024
	ds_read_b128 v[170:173], v0 offset:2048
	ds_read_b128 v[174:177], v0 offset:3072
	v_lshl_add_u64 v[194:195], s[2:3], 0, v[162:163]
	s_add_i32 m0, s37, 0xc000
	ds_read_b128 v[178:181], v169
	ds_read_b128 v[182:185], v169 offset:1024
	ds_read_b128 v[186:189], v169 offset:2048
	ds_read_b128 v[190:193], v169 offset:3072
	ds_read_b128 v[202:205], v169 offset:4096
	ds_read_b128 v[214:217], v169 offset:5120
	ds_read_b128 v[224:227], v169 offset:6144
	ds_read_b128 v[228:231], v169 offset:7168
	global_load_lds_dwordx4 v[194:195], off
	v_lshl_add_u64 v[194:195], s[2:3], 0, v[164:165]
	s_add_i32 m0, s37, 0xe000
	s_nop 0
	global_load_lds_dwordx4 v[194:195], off
	s_waitcnt vmcnt(8)
	s_waitcnt lgkmcnt(0)
	s_barrier
	s_waitcnt lgkmcnt(0)
	v_mfma_f32_16x16x32_bf16 v[62:65], v[106:109], v[178:181], v[62:65]
	v_mfma_f32_16x16x32_bf16 v[58:61], v[114:117], v[178:181], v[58:61]
	v_mfma_f32_16x16x32_bf16 v[54:57], v[106:109], v[186:189], v[54:57]
	v_mfma_f32_16x16x32_bf16 v[50:53], v[114:117], v[186:189], v[50:53]
	v_mfma_f32_16x16x32_bf16 v[46:49], v[106:109], v[202:205], v[46:49]
	v_mfma_f32_16x16x32_bf16 v[42:45], v[114:117], v[202:205], v[42:45]
	v_mfma_f32_16x16x32_bf16 v[38:41], v[106:109], v[224:227], v[38:41]
	v_mfma_f32_16x16x32_bf16 v[34:37], v[114:117], v[224:227], v[34:37]
	v_mfma_f32_16x16x32_bf16 v[62:65], v[110:113], v[182:185], v[62:65]
	v_mfma_f32_16x16x32_bf16 v[58:61], v[118:121], v[182:185], v[58:61]
	v_mfma_f32_16x16x32_bf16 v[54:57], v[110:113], v[190:193], v[54:57]
	v_mfma_f32_16x16x32_bf16 v[50:53], v[118:121], v[190:193], v[50:53]
	v_mfma_f32_16x16x32_bf16 v[46:49], v[110:113], v[214:217], v[46:49]
	v_mfma_f32_16x16x32_bf16 v[42:45], v[118:121], v[214:217], v[42:45]
	v_mfma_f32_16x16x32_bf16 v[38:41], v[110:113], v[228:231], v[38:41]
	v_mfma_f32_16x16x32_bf16 v[34:37], v[118:121], v[228:231], v[34:37]
	v_mfma_f32_16x16x32_bf16 v[142:145], v[146:149], v[178:181], v[142:145]
	v_mfma_f32_16x16x32_bf16 v[138:141], v[170:173], v[178:181], v[138:141]
	v_mfma_f32_16x16x32_bf16 v[134:137], v[146:149], v[186:189], v[134:137]
	v_mfma_f32_16x16x32_bf16 v[130:133], v[170:173], v[186:189], v[130:133]
	v_mfma_f32_16x16x32_bf16 v[126:129], v[146:149], v[202:205], v[126:129]
	v_mfma_f32_16x16x32_bf16 v[122:125], v[170:173], v[202:205], v[122:125]
	v_mfma_f32_16x16x32_bf16 v[102:105], v[146:149], v[224:227], v[102:105]
	v_mfma_f32_16x16x32_bf16 v[98:101], v[170:173], v[224:227], v[98:101]
	v_mfma_f32_16x16x32_bf16 v[142:145], v[150:153], v[182:185], v[142:145]
	v_mfma_f32_16x16x32_bf16 v[138:141], v[174:177], v[182:185], v[138:141]
	v_mfma_f32_16x16x32_bf16 v[134:137], v[150:153], v[190:193], v[134:137]
	v_mfma_f32_16x16x32_bf16 v[130:133], v[174:177], v[190:193], v[130:133]
	v_mfma_f32_16x16x32_bf16 v[126:129], v[150:153], v[214:217], v[126:129]
	v_mfma_f32_16x16x32_bf16 v[122:125], v[174:177], v[214:217], v[122:125]
	v_mfma_f32_16x16x32_bf16 v[102:105], v[150:153], v[228:231], v[102:105]
	v_mfma_f32_16x16x32_bf16 v[98:101], v[174:177], v[228:231], v[98:101]
	s_barrier
	s_add_i32 s55, s55, s36
	v_lshl_add_u64 v[194:195], s[4:5], 0, v[158:159]
	s_mov_b32 m0, s55
	ds_read_b128 v[178:181], v169 offset:16384
	ds_read_b128 v[182:185], v169 offset:17408
	ds_read_b128 v[186:189], v169 offset:18432
	ds_read_b128 v[190:193], v169 offset:19456
	ds_read_b128 v[202:205], v169 offset:20480
	ds_read_b128 v[214:217], v169 offset:21504
	ds_read_b128 v[224:227], v169 offset:22528
	ds_read_b128 v[228:231], v169 offset:23552
	global_load_lds_dwordx4 v[194:195], off
	s_add_i32 m0, s55, 0x2000
	s_add_u32 s56, s4, 0x40000
	v_lshl_add_u64 v[196:197], s[4:5], 0, v[154:155]
	s_addc_u32 s57, s5, 0
	s_add_i32 s55, s58, s36
	global_load_lds_dwordx4 v[196:197], off
	v_lshl_add_u64 v[198:199], s[56:57], 0, v[158:159]
	s_mov_b32 m0, s55
	v_lshl_add_u64 v[200:201], s[8:9], 0, v[156:157]
	global_load_lds_dwordx4 v[198:199], off
	v_lshl_add_u64 v[198:199], s[56:57], 0, v[154:155]
	s_add_i32 m0, s55, 0x2000
	s_nop 0
	global_load_lds_dwordx4 v[198:199], off
	v_lshl_add_u64 v[198:199], s[8:9], 0, v[160:161]
	s_mov_b32 m0, s37
	s_nop 0
	global_load_lds_dwordx4 v[198:199], off
	s_mov_b32 m0, s38
	s_nop 0
	global_load_lds_dwordx4 v[200:201], off
	s_waitcnt vmcnt(8)
	s_waitcnt lgkmcnt(0)
	s_barrier
	s_waitcnt lgkmcnt(0)
	v_mfma_f32_16x16x32_bf16 v[30:33], v[106:109], v[178:181], v[30:33]
	v_mfma_f32_16x16x32_bf16 v[26:29], v[114:117], v[178:181], v[26:29]
	v_mfma_f32_16x16x32_bf16 v[22:25], v[106:109], v[186:189], v[22:25]
	v_mfma_f32_16x16x32_bf16 v[18:21], v[114:117], v[186:189], v[18:21]
	v_mfma_f32_16x16x32_bf16 v[14:17], v[106:109], v[202:205], v[14:17]
	v_mfma_f32_16x16x32_bf16 v[10:13], v[114:117], v[202:205], v[10:13]
	v_mfma_f32_16x16x32_bf16 v[6:9], v[106:109], v[224:227], v[6:9]
	v_mfma_f32_16x16x32_bf16 v[2:5], v[114:117], v[224:227], v[2:5]
	v_mfma_f32_16x16x32_bf16 v[30:33], v[110:113], v[182:185], v[30:33]
	v_mfma_f32_16x16x32_bf16 v[26:29], v[118:121], v[182:185], v[26:29]
	v_mfma_f32_16x16x32_bf16 v[22:25], v[110:113], v[190:193], v[22:25]
	v_mfma_f32_16x16x32_bf16 v[18:21], v[118:121], v[190:193], v[18:21]
	v_mfma_f32_16x16x32_bf16 v[14:17], v[110:113], v[214:217], v[14:17]
	v_mfma_f32_16x16x32_bf16 v[10:13], v[118:121], v[214:217], v[10:13]
	v_mfma_f32_16x16x32_bf16 v[6:9], v[110:113], v[228:231], v[6:9]
	v_mfma_f32_16x16x32_bf16 v[2:5], v[118:121], v[228:231], v[2:5]
	v_mfma_f32_16x16x32_bf16 v[94:97], v[146:149], v[178:181], v[94:97]
	v_mfma_f32_16x16x32_bf16 v[90:93], v[170:173], v[178:181], v[90:93]
	v_mfma_f32_16x16x32_bf16 v[86:89], v[146:149], v[186:189], v[86:89]
	v_mfma_f32_16x16x32_bf16 v[82:85], v[170:173], v[186:189], v[82:85]
	v_mfma_f32_16x16x32_bf16 v[78:81], v[146:149], v[202:205], v[78:81]
	v_mfma_f32_16x16x32_bf16 v[74:77], v[170:173], v[202:205], v[74:77]
	v_mfma_f32_16x16x32_bf16 v[70:73], v[146:149], v[224:227], v[70:73]
	v_mfma_f32_16x16x32_bf16 v[66:69], v[170:173], v[224:227], v[66:69]
	v_mfma_f32_16x16x32_bf16 v[94:97], v[150:153], v[182:185], v[94:97]
	v_mfma_f32_16x16x32_bf16 v[90:93], v[174:177], v[182:185], v[90:93]
	v_mfma_f32_16x16x32_bf16 v[86:89], v[150:153], v[190:193], v[86:89]
	v_mfma_f32_16x16x32_bf16 v[82:85], v[174:177], v[190:193], v[82:85]
	v_mfma_f32_16x16x32_bf16 v[78:81], v[150:153], v[214:217], v[78:81]
	v_mfma_f32_16x16x32_bf16 v[74:77], v[174:177], v[214:217], v[74:77]
	v_mfma_f32_16x16x32_bf16 v[70:73], v[150:153], v[228:231], v[70:73]
	v_mfma_f32_16x16x32_bf16 v[66:69], v[174:177], v[228:231], v[66:69]
	s_barrier
	s_add_i32 s55, 0, 0x18000
	v_add_u32_e32 v0, s55, v167
	s_add_i32 s56, 0, 0x1c000
	ds_read_b128 v[106:109], v0
	ds_read_b128 v[110:113], v0 offset:1024
	ds_read_b128 v[114:117], v0 offset:2048
	ds_read_b128 v[118:121], v0 offset:3072
	v_add_u32_e32 v0, s56, v167
	ds_read_b128 v[146:149], v0
	ds_read_b128 v[150:153], v0 offset:1024
	ds_read_b128 v[170:173], v0 offset:2048
	ds_read_b128 v[174:177], v0 offset:3072
	s_add_u32 s8, s8, 0x40000
	s_addc_u32 s9, s9, 0
	s_mov_b32 m0, s39
	v_lshl_add_u64 v[206:207], s[8:9], 0, v[160:161]
	ds_read_b128 v[178:181], v169 offset:32768
	ds_read_b128 v[182:185], v169 offset:33792
	ds_read_b128 v[186:189], v169 offset:34816
	ds_read_b128 v[190:193], v169 offset:35840
	ds_read_b128 v[202:205], v169 offset:36864
	ds_read_b128 v[214:217], v169 offset:37888
	ds_read_b128 v[224:227], v169 offset:38912
	ds_read_b128 v[228:231], v169 offset:39936
	global_load_lds_dwordx4 v[206:207], off
	v_lshl_add_u64 v[206:207], s[8:9], 0, v[156:157]
	s_mov_b32 m0, s40
	s_nop 0
	global_load_lds_dwordx4 v[206:207], off
	s_waitcnt vmcnt(8)
	s_waitcnt lgkmcnt(0)
	s_barrier
	s_waitcnt lgkmcnt(0)
	v_mfma_f32_16x16x32_bf16 v[62:65], v[106:109], v[178:181], v[62:65]
	v_mfma_f32_16x16x32_bf16 v[58:61], v[114:117], v[178:181], v[58:61]
	v_mfma_f32_16x16x32_bf16 v[54:57], v[106:109], v[186:189], v[54:57]
	v_mfma_f32_16x16x32_bf16 v[50:53], v[114:117], v[186:189], v[50:53]
	v_mfma_f32_16x16x32_bf16 v[46:49], v[106:109], v[202:205], v[46:49]
	v_mfma_f32_16x16x32_bf16 v[42:45], v[114:117], v[202:205], v[42:45]
	v_mfma_f32_16x16x32_bf16 v[38:41], v[106:109], v[224:227], v[38:41]
	v_mfma_f32_16x16x32_bf16 v[34:37], v[114:117], v[224:227], v[34:37]
	v_mfma_f32_16x16x32_bf16 v[62:65], v[110:113], v[182:185], v[62:65]
	v_mfma_f32_16x16x32_bf16 v[58:61], v[118:121], v[182:185], v[58:61]
	v_mfma_f32_16x16x32_bf16 v[54:57], v[110:113], v[190:193], v[54:57]
	v_mfma_f32_16x16x32_bf16 v[50:53], v[118:121], v[190:193], v[50:53]
	v_mfma_f32_16x16x32_bf16 v[46:49], v[110:113], v[214:217], v[46:49]
	v_mfma_f32_16x16x32_bf16 v[42:45], v[118:121], v[214:217], v[42:45]
	v_mfma_f32_16x16x32_bf16 v[38:41], v[110:113], v[228:231], v[38:41]
	v_mfma_f32_16x16x32_bf16 v[34:37], v[118:121], v[228:231], v[34:37]
	v_mfma_f32_16x16x32_bf16 v[142:145], v[146:149], v[178:181], v[142:145]
	v_mfma_f32_16x16x32_bf16 v[138:141], v[170:173], v[178:181], v[138:141]
	v_mfma_f32_16x16x32_bf16 v[134:137], v[146:149], v[186:189], v[134:137]
	v_mfma_f32_16x16x32_bf16 v[130:133], v[170:173], v[186:189], v[130:133]
	v_mfma_f32_16x16x32_bf16 v[126:129], v[146:149], v[202:205], v[126:129]
	v_mfma_f32_16x16x32_bf16 v[122:125], v[170:173], v[202:205], v[122:125]
	v_mfma_f32_16x16x32_bf16 v[102:105], v[146:149], v[224:227], v[102:105]
	v_mfma_f32_16x16x32_bf16 v[98:101], v[170:173], v[224:227], v[98:101]
	v_mfma_f32_16x16x32_bf16 v[142:145], v[150:153], v[182:185], v[142:145]
	v_mfma_f32_16x16x32_bf16 v[138:141], v[174:177], v[182:185], v[138:141]
	v_mfma_f32_16x16x32_bf16 v[134:137], v[150:153], v[190:193], v[134:137]
	v_mfma_f32_16x16x32_bf16 v[130:133], v[174:177], v[190:193], v[130:133]
	v_mfma_f32_16x16x32_bf16 v[126:129], v[150:153], v[214:217], v[126:129]
	v_mfma_f32_16x16x32_bf16 v[122:125], v[174:177], v[214:217], v[122:125]
	v_mfma_f32_16x16x32_bf16 v[102:105], v[150:153], v[228:231], v[102:105]
	v_mfma_f32_16x16x32_bf16 v[98:101], v[174:177], v[228:231], v[98:101]
	s_barrier
	s_add_i32 s8, s55, s36
	v_lshl_add_u64 v[194:195], v[194:195], 0, s[94:95]
	s_mov_b32 m0, s8
	ds_read_b128 v[178:181], v169 offset:49152
	ds_read_b128 v[182:185], v169 offset:50176
	ds_read_b128 v[186:189], v169 offset:51200
	ds_read_b128 v[190:193], v169 offset:52224
	ds_read_b128 v[202:205], v169 offset:53248
	ds_read_b128 v[214:217], v169 offset:54272
	ds_read_b128 v[224:227], v169 offset:55296
	ds_read_b128 v[228:231], v169 offset:56320
	global_load_lds_dwordx4 v[194:195], off
	s_add_i32 m0, s8, 0x2000
	s_add_u32 s4, s4, 0x40080
	v_lshl_add_u64 v[194:195], v[196:197], 0, s[94:95]
	s_addc_u32 s5, s5, 0
	s_add_i32 s8, s56, s36
	global_load_lds_dwordx4 v[194:195], off
	v_lshl_add_u64 v[194:195], s[4:5], 0, v[158:159]
	s_mov_b32 m0, s8
	s_nop 0
	global_load_lds_dwordx4 v[194:195], off
	v_lshl_add_u64 v[194:195], s[4:5], 0, v[154:155]
	s_add_i32 m0, s8, 0x2000
	s_nop 0
	global_load_lds_dwordx4 v[194:195], off
	v_lshl_add_u64 v[194:195], v[198:199], 0, s[94:95]
	s_mov_b32 m0, s46
	s_nop 0
	global_load_lds_dwordx4 v[194:195], off
	v_lshl_add_u64 v[194:195], v[200:201], 0, s[94:95]
	s_mov_b32 m0, s47
	s_nop 0
	global_load_lds_dwordx4 v[194:195], off
	s_waitcnt vmcnt(8)
	s_waitcnt lgkmcnt(0)
	s_barrier
	s_waitcnt lgkmcnt(0)
	v_mfma_f32_16x16x32_bf16 v[30:33], v[106:109], v[178:181], v[30:33]
	v_mfma_f32_16x16x32_bf16 v[26:29], v[114:117], v[178:181], v[26:29]
	v_mfma_f32_16x16x32_bf16 v[22:25], v[106:109], v[186:189], v[22:25]
	v_mfma_f32_16x16x32_bf16 v[18:21], v[114:117], v[186:189], v[18:21]
	v_mfma_f32_16x16x32_bf16 v[14:17], v[106:109], v[202:205], v[14:17]
	v_mfma_f32_16x16x32_bf16 v[10:13], v[114:117], v[202:205], v[10:13]
	v_mfma_f32_16x16x32_bf16 v[6:9], v[106:109], v[224:227], v[6:9]
	v_mfma_f32_16x16x32_bf16 v[2:5], v[114:117], v[224:227], v[2:5]
	v_mfma_f32_16x16x32_bf16 v[30:33], v[110:113], v[182:185], v[30:33]
	v_mfma_f32_16x16x32_bf16 v[26:29], v[118:121], v[182:185], v[26:29]
	v_mfma_f32_16x16x32_bf16 v[22:25], v[110:113], v[190:193], v[22:25]
	v_mfma_f32_16x16x32_bf16 v[18:21], v[118:121], v[190:193], v[18:21]
	v_mfma_f32_16x16x32_bf16 v[14:17], v[110:113], v[214:217], v[14:17]
	v_mfma_f32_16x16x32_bf16 v[10:13], v[118:121], v[214:217], v[10:13]
	v_mfma_f32_16x16x32_bf16 v[6:9], v[110:113], v[228:231], v[6:9]
	v_mfma_f32_16x16x32_bf16 v[2:5], v[118:121], v[228:231], v[2:5]
	v_mfma_f32_16x16x32_bf16 v[94:97], v[146:149], v[178:181], v[94:97]
	v_mfma_f32_16x16x32_bf16 v[90:93], v[170:173], v[178:181], v[90:93]
	v_mfma_f32_16x16x32_bf16 v[86:89], v[146:149], v[186:189], v[86:89]
	v_mfma_f32_16x16x32_bf16 v[82:85], v[170:173], v[186:189], v[82:85]
	v_mfma_f32_16x16x32_bf16 v[78:81], v[146:149], v[202:205], v[78:81]
	v_mfma_f32_16x16x32_bf16 v[74:77], v[170:173], v[202:205], v[74:77]
	v_mfma_f32_16x16x32_bf16 v[70:73], v[146:149], v[224:227], v[70:73]
	v_mfma_f32_16x16x32_bf16 v[66:69], v[170:173], v[224:227], v[66:69]
	v_mfma_f32_16x16x32_bf16 v[94:97], v[150:153], v[182:185], v[94:97]
	v_mfma_f32_16x16x32_bf16 v[90:93], v[174:177], v[182:185], v[90:93]
	v_mfma_f32_16x16x32_bf16 v[86:89], v[150:153], v[190:193], v[86:89]
	v_mfma_f32_16x16x32_bf16 v[82:85], v[174:177], v[190:193], v[82:85]
	v_mfma_f32_16x16x32_bf16 v[78:81], v[150:153], v[214:217], v[78:81]
	v_mfma_f32_16x16x32_bf16 v[74:77], v[174:177], v[214:217], v[74:77]
	v_mfma_f32_16x16x32_bf16 v[70:73], v[150:153], v[228:231], v[70:73]
	v_mfma_f32_16x16x32_bf16 v[66:69], v[174:177], v[228:231], v[66:69]
	s_barrier
	s_add_i32 s54, s54, 2
	s_add_u32 s2, s2, 0x100
	s_addc_u32 s3, s3, 0
	s_add_u32 s52, s52, 0x100
	s_addc_u32 s53, s53, 0
	s_cmp_gt_u32 s54, 13
	s_cbranch_scc0 .LBB0_620
	s_and_b64 vcc, exec, s[18:19]
	s_cbranch_vccz .LBB0_623
	s_barrier

.Lp8_j0:
	s_waitcnt lgkmcnt(0)
	s_barrier
	s_waitcnt lgkmcnt(0)
	v_mfma_f32_16x16x32_bf16 v[126:129], v[136:139], v[172:175], v[126:129]
	v_mfma_f32_16x16x32_bf16 v[122:125], v[144:147], v[172:175], v[122:125]
	v_mfma_f32_16x16x32_bf16 v[114:117], v[136:139], v[180:183], v[114:117]
	v_mfma_f32_16x16x32_bf16 v[106:109], v[144:147], v[180:183], v[106:109]
	v_mfma_f32_16x16x32_bf16 v[98:101], v[136:139], v[188:191], v[98:101]
	v_mfma_f32_16x16x32_bf16 v[90:93], v[144:147], v[188:191], v[90:93]
	v_mfma_f32_16x16x32_bf16 v[82:85], v[136:139], v[202:205], v[82:85]
	v_mfma_f32_16x16x32_bf16 v[74:77], v[144:147], v[202:205], v[74:77]
	v_mfma_f32_16x16x32_bf16 v[126:129], v[140:143], v[176:179], v[126:129]
	v_mfma_f32_16x16x32_bf16 v[122:125], v[148:151], v[176:179], v[122:125]
	v_mfma_f32_16x16x32_bf16 v[114:117], v[140:143], v[184:187], v[114:117]
	v_mfma_f32_16x16x32_bf16 v[106:109], v[148:151], v[184:187], v[106:109]
	v_mfma_f32_16x16x32_bf16 v[98:101], v[140:143], v[192:195], v[98:101]
	v_mfma_f32_16x16x32_bf16 v[90:93], v[148:151], v[192:195], v[90:93]
	v_mfma_f32_16x16x32_bf16 v[82:85], v[140:143], v[214:217], v[82:85]
	v_mfma_f32_16x16x32_bf16 v[74:77], v[148:151], v[214:217], v[74:77]
	v_mfma_f32_16x16x32_bf16 v[118:121], v[152:155], v[172:175], v[118:121]
	v_mfma_f32_16x16x32_bf16 v[110:113], v[160:163], v[172:175], v[110:113]
	v_mfma_f32_16x16x32_bf16 v[102:105], v[152:155], v[180:183], v[102:105]
	v_mfma_f32_16x16x32_bf16 v[94:97], v[160:163], v[180:183], v[94:97]
	v_mfma_f32_16x16x32_bf16 v[86:89], v[152:155], v[188:191], v[86:89]
	v_mfma_f32_16x16x32_bf16 v[78:81], v[160:163], v[188:191], v[78:81]
	v_mfma_f32_16x16x32_bf16 v[70:73], v[152:155], v[202:205], v[70:73]
	v_mfma_f32_16x16x32_bf16 v[66:69], v[160:163], v[202:205], v[66:69]
	v_mfma_f32_16x16x32_bf16 v[118:121], v[156:159], v[176:179], v[118:121]
	v_mfma_f32_16x16x32_bf16 v[110:113], v[168:171], v[176:179], v[110:113]
	v_mfma_f32_16x16x32_bf16 v[102:105], v[156:159], v[184:187], v[102:105]
	v_mfma_f32_16x16x32_bf16 v[94:97], v[168:171], v[184:187], v[94:97]
	v_mfma_f32_16x16x32_bf16 v[86:89], v[156:159], v[192:195], v[86:89]
	v_mfma_f32_16x16x32_bf16 v[78:81], v[168:171], v[192:195], v[78:81]
	v_mfma_f32_16x16x32_bf16 v[70:73], v[156:159], v[214:217], v[70:73]
	v_mfma_f32_16x16x32_bf16 v[66:69], v[168:171], v[214:217], v[66:69]
	s_barrier
	s_add_i32 s49, s49, s28
	v_lshl_add_u64 v[164:165], s[20:21], 0, v[0:1]
	s_mov_b32 m0, s49
	ds_read_b128 v[172:175], v167 offset:16384
	ds_read_b128 v[176:179], v167 offset:17408
	ds_read_b128 v[180:183], v167 offset:18432
	ds_read_b128 v[184:187], v167 offset:19456
	ds_read_b128 v[188:191], v167 offset:20480
	ds_read_b128 v[192:195], v167 offset:21504
	ds_read_b128 v[202:205], v167 offset:22528
	ds_read_b128 v[214:217], v167 offset:23552
	global_load_lds_dwordx4 v[164:165], off
	s_add_i32 m0, s49, 0x2000
	s_add_u32 s50, s20, 0x40000
	v_lshl_add_u64 v[196:197], s[20:21], 0, v[130:131]
	s_addc_u32 s51, s21, 0
	s_add_i32 s49, s52, s28
	global_load_lds_dwordx4 v[196:197], off
	v_lshl_add_u64 v[198:199], s[50:51], 0, v[0:1]
	s_mov_b32 m0, s49
	v_lshl_add_u64 v[200:201], s[22:23], 0, v[130:131]
	global_load_lds_dwordx4 v[198:199], off
	v_lshl_add_u64 v[198:199], s[50:51], 0, v[130:131]
	s_add_i32 m0, s49, 0x2000
	s_nop 0
	global_load_lds_dwordx4 v[198:199], off
	v_lshl_add_u64 v[198:199], s[22:23], 0, v[0:1]
	s_mov_b32 m0, s29
	s_nop 0
	global_load_lds_dwordx4 v[198:199], off
	s_mov_b32 m0, s30
	s_nop 0
	global_load_lds_dwordx4 v[200:201], off
	s_cmp_eq_u32 s48, -2
	s_cbranch_scc1 .Lp8_f1
	s_waitcnt vmcnt(8)
	s_branch .Lp8_j1

.Lp8_j1:
	s_waitcnt lgkmcnt(0)
	s_barrier
	s_waitcnt lgkmcnt(0)
	v_mfma_f32_16x16x32_bf16 v[62:65], v[136:139], v[172:175], v[62:65]
	v_mfma_f32_16x16x32_bf16 v[58:61], v[144:147], v[172:175], v[58:61]
	v_mfma_f32_16x16x32_bf16 v[50:53], v[136:139], v[180:183], v[50:53]
	v_mfma_f32_16x16x32_bf16 v[42:45], v[144:147], v[180:183], v[42:45]
	v_mfma_f32_16x16x32_bf16 v[34:37], v[136:139], v[188:191], v[34:37]
	v_mfma_f32_16x16x32_bf16 v[26:29], v[144:147], v[188:191], v[26:29]
	v_mfma_f32_16x16x32_bf16 v[18:21], v[136:139], v[202:205], v[18:21]
	v_mfma_f32_16x16x32_bf16 v[10:13], v[144:147], v[202:205], v[10:13]
	v_mfma_f32_16x16x32_bf16 v[62:65], v[140:143], v[176:179], v[62:65]
	v_mfma_f32_16x16x32_bf16 v[58:61], v[148:151], v[176:179], v[58:61]
	v_mfma_f32_16x16x32_bf16 v[50:53], v[140:143], v[184:187], v[50:53]
	v_mfma_f32_16x16x32_bf16 v[42:45], v[148:151], v[184:187], v[42:45]
	v_mfma_f32_16x16x32_bf16 v[34:37], v[140:143], v[192:195], v[34:37]
	v_mfma_f32_16x16x32_bf16 v[26:29], v[148:151], v[192:195], v[26:29]
	v_mfma_f32_16x16x32_bf16 v[18:21], v[140:143], v[214:217], v[18:21]
	v_mfma_f32_16x16x32_bf16 v[10:13], v[148:151], v[214:217], v[10:13]
	v_mfma_f32_16x16x32_bf16 v[54:57], v[152:155], v[172:175], v[54:57]
	v_mfma_f32_16x16x32_bf16 v[46:49], v[160:163], v[172:175], v[46:49]
	v_mfma_f32_16x16x32_bf16 v[38:41], v[152:155], v[180:183], v[38:41]
	v_mfma_f32_16x16x32_bf16 v[30:33], v[160:163], v[180:183], v[30:33]
	v_mfma_f32_16x16x32_bf16 v[22:25], v[152:155], v[188:191], v[22:25]
	v_mfma_f32_16x16x32_bf16 v[14:17], v[160:163], v[188:191], v[14:17]
	v_mfma_f32_16x16x32_bf16 v[6:9], v[152:155], v[202:205], v[6:9]
	v_mfma_f32_16x16x32_bf16 v[2:5], v[160:163], v[202:205], v[2:5]
	v_mfma_f32_16x16x32_bf16 v[54:57], v[156:159], v[176:179], v[54:57]
	v_mfma_f32_16x16x32_bf16 v[46:49], v[168:171], v[176:179], v[46:49]
	v_mfma_f32_16x16x32_bf16 v[38:41], v[156:159], v[184:187], v[38:41]
	v_mfma_f32_16x16x32_bf16 v[30:33], v[168:171], v[184:187], v[30:33]
	v_mfma_f32_16x16x32_bf16 v[22:25], v[156:159], v[192:195], v[22:25]
	v_mfma_f32_16x16x32_bf16 v[14:17], v[168:171], v[192:195], v[14:17]
	v_mfma_f32_16x16x32_bf16 v[6:9], v[156:159], v[214:217], v[6:9]
	v_mfma_f32_16x16x32_bf16 v[2:5], v[168:171], v[214:217], v[2:5]
	s_barrier
	s_add_i32 s49, 0, 0x18000
	s_add_i32 s50, 0, 0x1c000
	v_add_u32_e32 v148, s49, v166
	v_add_u32_e32 v168, s50, v166
	ds_read_b128 v[136:139], v148
	ds_read_b128 v[140:143], v148 offset:1024
	ds_read_b128 v[144:147], v148 offset:2048
	ds_read_b128 v[148:151], v148 offset:3072
	ds_read_b128 v[152:155], v168
	ds_read_b128 v[156:159], v168 offset:1024
	ds_read_b128 v[160:163], v168 offset:2048
	ds_read_b128 v[168:171], v168 offset:3072
	s_add_u32 s22, s22, 0x40000
	s_addc_u32 s23, s23, 0
	s_mov_b32 m0, s31
	v_lshl_add_u64 v[206:207], s[22:23], 0, v[0:1]
	ds_read_b128 v[172:175], v167 offset:32768
	ds_read_b128 v[176:179], v167 offset:33792
	ds_read_b128 v[180:183], v167 offset:34816
	ds_read_b128 v[184:187], v167 offset:35840
	ds_read_b128 v[188:191], v167 offset:36864
	ds_read_b128 v[192:195], v167 offset:37888
	ds_read_b128 v[202:205], v167 offset:38912
	ds_read_b128 v[214:217], v167 offset:39936
	global_load_lds_dwordx4 v[206:207], off
	v_lshl_add_u64 v[206:207], s[22:23], 0, v[130:131]
	s_mov_b32 m0, s34
	s_nop 0
	global_load_lds_dwordx4 v[206:207], off
	s_waitcnt vmcnt(8)
	s_waitcnt lgkmcnt(0)
	s_barrier
	s_waitcnt lgkmcnt(0)
	v_mfma_f32_16x16x32_bf16 v[126:129], v[136:139], v[172:175], v[126:129]
	v_mfma_f32_16x16x32_bf16 v[122:125], v[144:147], v[172:175], v[122:125]
	v_mfma_f32_16x16x32_bf16 v[114:117], v[136:139], v[180:183], v[114:117]
	v_mfma_f32_16x16x32_bf16 v[106:109], v[144:147], v[180:183], v[106:109]
	v_mfma_f32_16x16x32_bf16 v[98:101], v[136:139], v[188:191], v[98:101]
	v_mfma_f32_16x16x32_bf16 v[90:93], v[144:147], v[188:191], v[90:93]
	v_mfma_f32_16x16x32_bf16 v[82:85], v[136:139], v[202:205], v[82:85]
	v_mfma_f32_16x16x32_bf16 v[74:77], v[144:147], v[202:205], v[74:77]
	v_mfma_f32_16x16x32_bf16 v[126:129], v[140:143], v[176:179], v[126:129]
	v_mfma_f32_16x16x32_bf16 v[122:125], v[148:151], v[176:179], v[122:125]
	v_mfma_f32_16x16x32_bf16 v[114:117], v[140:143], v[184:187], v[114:117]
	v_mfma_f32_16x16x32_bf16 v[106:109], v[148:151], v[184:187], v[106:109]
	v_mfma_f32_16x16x32_bf16 v[98:101], v[140:143], v[192:195], v[98:101]
	v_mfma_f32_16x16x32_bf16 v[90:93], v[148:151], v[192:195], v[90:93]
	v_mfma_f32_16x16x32_bf16 v[82:85], v[140:143], v[214:217], v[82:85]
	v_mfma_f32_16x16x32_bf16 v[74:77], v[148:151], v[214:217], v[74:77]
	v_mfma_f32_16x16x32_bf16 v[118:121], v[152:155], v[172:175], v[118:121]
	v_mfma_f32_16x16x32_bf16 v[110:113], v[160:163], v[172:175], v[110:113]
	v_mfma_f32_16x16x32_bf16 v[102:105], v[152:155], v[180:183], v[102:105]
	v_mfma_f32_16x16x32_bf16 v[94:97], v[160:163], v[180:183], v[94:97]
	v_mfma_f32_16x16x32_bf16 v[86:89], v[152:155], v[188:191], v[86:89]
	v_mfma_f32_16x16x32_bf16 v[78:81], v[160:163], v[188:191], v[78:81]
	v_mfma_f32_16x16x32_bf16 v[70:73], v[152:155], v[202:205], v[70:73]
	v_mfma_f32_16x16x32_bf16 v[66:69], v[160:163], v[202:205], v[66:69]
	v_mfma_f32_16x16x32_bf16 v[118:121], v[156:159], v[176:179], v[118:121]
	v_mfma_f32_16x16x32_bf16 v[110:113], v[168:171], v[176:179], v[110:113]
	v_mfma_f32_16x16x32_bf16 v[102:105], v[156:159], v[184:187], v[102:105]
	v_mfma_f32_16x16x32_bf16 v[94:97], v[168:171], v[184:187], v[94:97]
	v_mfma_f32_16x16x32_bf16 v[86:89], v[156:159], v[192:195], v[86:89]
	v_mfma_f32_16x16x32_bf16 v[78:81], v[168:171], v[192:195], v[78:81]
	v_mfma_f32_16x16x32_bf16 v[70:73], v[156:159], v[214:217], v[70:73]
	v_mfma_f32_16x16x32_bf16 v[66:69], v[168:171], v[214:217], v[66:69]
	s_barrier
	s_add_i32 s22, s49, s28
	v_lshl_add_u64 v[164:165], v[164:165], 0, s[94:95]
	s_mov_b32 m0, s22
	ds_read_b128 v[172:175], v167 offset:49152
	ds_read_b128 v[176:179], v167 offset:50176
	ds_read_b128 v[180:183], v167 offset:51200
	ds_read_b128 v[184:187], v167 offset:52224
	ds_read_b128 v[188:191], v167 offset:53248
	ds_read_b128 v[192:195], v167 offset:54272
	ds_read_b128 v[202:205], v167 offset:55296
	ds_read_b128 v[214:217], v167 offset:56320
	global_load_lds_dwordx4 v[164:165], off
	s_add_i32 m0, s22, 0x2000
	s_add_u32 s20, s20, 0x40080
	v_lshl_add_u64 v[164:165], v[196:197], 0, s[94:95]
	s_addc_u32 s21, s21, 0
	s_add_i32 s22, s50, s28
	global_load_lds_dwordx4 v[164:165], off
	v_lshl_add_u64 v[164:165], s[20:21], 0, v[0:1]
	s_mov_b32 m0, s22
	s_nop 0
	global_load_lds_dwordx4 v[164:165], off
	v_lshl_add_u64 v[164:165], s[20:21], 0, v[130:131]
	s_add_i32 m0, s22, 0x2000
	s_nop 0
	global_load_lds_dwordx4 v[164:165], off
	v_lshl_add_u64 v[164:165], v[198:199], 0, s[94:95]
	s_mov_b32 m0, s37
	s_nop 0
	global_load_lds_dwordx4 v[164:165], off
	v_lshl_add_u64 v[164:165], v[200:201], 0, s[94:95]
	s_mov_b32 m0, s38
	s_nop 0
	global_load_lds_dwordx4 v[164:165], off
	s_waitcnt vmcnt(8)
	s_waitcnt lgkmcnt(0)
	s_barrier
	s_waitcnt lgkmcnt(0)
	v_mfma_f32_16x16x32_bf16 v[62:65], v[136:139], v[172:175], v[62:65]
	v_mfma_f32_16x16x32_bf16 v[58:61], v[144:147], v[172:175], v[58:61]
	v_mfma_f32_16x16x32_bf16 v[50:53], v[136:139], v[180:183], v[50:53]
	v_mfma_f32_16x16x32_bf16 v[42:45], v[144:147], v[180:183], v[42:45]
	v_mfma_f32_16x16x32_bf16 v[34:37], v[136:139], v[188:191], v[34:37]
	v_mfma_f32_16x16x32_bf16 v[26:29], v[144:147], v[188:191], v[26:29]
	v_mfma_f32_16x16x32_bf16 v[18:21], v[136:139], v[202:205], v[18:21]
	v_mfma_f32_16x16x32_bf16 v[10:13], v[144:147], v[202:205], v[10:13]
	v_mfma_f32_16x16x32_bf16 v[62:65], v[140:143], v[176:179], v[62:65]
	v_mfma_f32_16x16x32_bf16 v[58:61], v[148:151], v[176:179], v[58:61]
	v_mfma_f32_16x16x32_bf16 v[50:53], v[140:143], v[184:187], v[50:53]
	v_mfma_f32_16x16x32_bf16 v[42:45], v[148:151], v[184:187], v[42:45]
	v_mfma_f32_16x16x32_bf16 v[34:37], v[140:143], v[192:195], v[34:37]
	v_mfma_f32_16x16x32_bf16 v[26:29], v[148:151], v[192:195], v[26:29]
	v_mfma_f32_16x16x32_bf16 v[18:21], v[140:143], v[214:217], v[18:21]
	v_mfma_f32_16x16x32_bf16 v[10:13], v[148:151], v[214:217], v[10:13]
	v_mfma_f32_16x16x32_bf16 v[54:57], v[152:155], v[172:175], v[54:57]
	v_mfma_f32_16x16x32_bf16 v[46:49], v[160:163], v[172:175], v[46:49]
	v_mfma_f32_16x16x32_bf16 v[38:41], v[152:155], v[180:183], v[38:41]
	v_mfma_f32_16x16x32_bf16 v[30:33], v[160:163], v[180:183], v[30:33]
	v_mfma_f32_16x16x32_bf16 v[22:25], v[152:155], v[188:191], v[22:25]
	v_mfma_f32_16x16x32_bf16 v[14:17], v[160:163], v[188:191], v[14:17]
	v_mfma_f32_16x16x32_bf16 v[6:9], v[152:155], v[202:205], v[6:9]
	v_mfma_f32_16x16x32_bf16 v[2:5], v[160:163], v[202:205], v[2:5]
	v_mfma_f32_16x16x32_bf16 v[54:57], v[156:159], v[176:179], v[54:57]
	v_mfma_f32_16x16x32_bf16 v[46:49], v[168:171], v[176:179], v[46:49]
	v_mfma_f32_16x16x32_bf16 v[38:41], v[156:159], v[184:187], v[38:41]
	v_mfma_f32_16x16x32_bf16 v[30:33], v[168:171], v[184:187], v[30:33]
	v_mfma_f32_16x16x32_bf16 v[22:25], v[156:159], v[192:195], v[22:25]
	v_mfma_f32_16x16x32_bf16 v[14:17], v[168:171], v[192:195], v[14:17]
	v_mfma_f32_16x16x32_bf16 v[6:9], v[156:159], v[214:217], v[6:9]
	v_mfma_f32_16x16x32_bf16 v[2:5], v[168:171], v[214:217], v[2:5]
	s_barrier
	s_add_i32 s48, s48, 2
	s_add_u32 s18, s18, 0x100
	s_addc_u32 s19, s19, 0
	s_add_u32 s46, s46, 0x100
	s_addc_u32 s47, s47, 0
	s_cmp_gt_u32 s48, 13
	s_cbranch_scc0 .LBB0_1008
	s_and_b64 vcc, exec, s[8:9]
	s_cbranch_vccz .LBB0_1011
	s_barrier

.Lp3w_j0:
	s_waitcnt lgkmcnt(0)
	s_barrier
	s_waitcnt lgkmcnt(0)
	v_mfma_f32_16x16x32_bf16 v[126:129], v[144:147], v[176:179], v[126:129]
	v_mfma_f32_16x16x32_bf16 v[118:121], v[152:155], v[176:179], v[118:121]
	v_mfma_f32_16x16x32_bf16 v[110:113], v[144:147], v[184:187], v[110:113]
	v_mfma_f32_16x16x32_bf16 v[102:105], v[152:155], v[184:187], v[102:105]
	v_mfma_f32_16x16x32_bf16 v[94:97], v[144:147], v[192:195], v[94:97]
	v_mfma_f32_16x16x32_bf16 v[86:89], v[152:155], v[192:195], v[86:89]
	v_mfma_f32_16x16x32_bf16 v[78:81], v[144:147], v[214:217], v[78:81]
	v_mfma_f32_16x16x32_bf16 v[70:73], v[152:155], v[214:217], v[70:73]
	v_mfma_f32_16x16x32_bf16 v[126:129], v[148:151], v[180:183], v[126:129]
	v_mfma_f32_16x16x32_bf16 v[118:121], v[156:159], v[180:183], v[118:121]
	v_mfma_f32_16x16x32_bf16 v[110:113], v[148:151], v[188:191], v[110:113]
	v_mfma_f32_16x16x32_bf16 v[102:105], v[156:159], v[188:191], v[102:105]
	v_mfma_f32_16x16x32_bf16 v[94:97], v[148:151], v[202:205], v[94:97]
	v_mfma_f32_16x16x32_bf16 v[86:89], v[156:159], v[202:205], v[86:89]
	v_mfma_f32_16x16x32_bf16 v[78:81], v[148:151], v[224:227], v[78:81]
	v_mfma_f32_16x16x32_bf16 v[70:73], v[156:159], v[224:227], v[70:73]
	v_mfma_f32_16x16x32_bf16 v[122:125], v[160:163], v[176:179], v[122:125]
	v_mfma_f32_16x16x32_bf16 v[114:117], v[168:171], v[176:179], v[114:117]
	v_mfma_f32_16x16x32_bf16 v[106:109], v[160:163], v[184:187], v[106:109]
	v_mfma_f32_16x16x32_bf16 v[98:101], v[168:171], v[184:187], v[98:101]
	v_mfma_f32_16x16x32_bf16 v[90:93], v[160:163], v[192:195], v[90:93]
	v_mfma_f32_16x16x32_bf16 v[82:85], v[168:171], v[192:195], v[82:85]
	v_mfma_f32_16x16x32_bf16 v[74:77], v[160:163], v[214:217], v[74:77]
	v_mfma_f32_16x16x32_bf16 v[66:69], v[168:171], v[214:217], v[66:69]
	v_mfma_f32_16x16x32_bf16 v[122:125], v[164:167], v[180:183], v[122:125]
	v_mfma_f32_16x16x32_bf16 v[114:117], v[172:175], v[180:183], v[114:117]
	v_mfma_f32_16x16x32_bf16 v[106:109], v[164:167], v[188:191], v[106:109]
	v_mfma_f32_16x16x32_bf16 v[98:101], v[172:175], v[188:191], v[98:101]
	v_mfma_f32_16x16x32_bf16 v[90:93], v[164:167], v[202:205], v[90:93]
	v_mfma_f32_16x16x32_bf16 v[82:85], v[172:175], v[202:205], v[82:85]
	v_mfma_f32_16x16x32_bf16 v[74:77], v[164:167], v[224:227], v[74:77]
	v_mfma_f32_16x16x32_bf16 v[66:69], v[172:175], v[224:227], v[66:69]
	s_barrier
	s_add_i32 s54, s54, s37
	v_lshl_add_u64 v[196:197], s[24:25], 0, v[0:1]
	s_mov_b32 m0, s54
	ds_read_b128 v[176:179], v143 offset:16384
	ds_read_b128 v[180:183], v143 offset:17408
	ds_read_b128 v[184:187], v143 offset:18432
	ds_read_b128 v[188:191], v143 offset:19456
	ds_read_b128 v[192:195], v143 offset:20480
	ds_read_b128 v[202:205], v143 offset:21504
	ds_read_b128 v[214:217], v143 offset:22528
	ds_read_b128 v[224:227], v143 offset:23552
	global_load_lds_dwordx4 v[196:197], off
	s_add_i32 m0, s54, 0x2000
	s_add_u32 s54, s24, 0x40000
	v_lshl_add_u64 v[198:199], s[24:25], 0, v[130:131]
	s_addc_u32 s55, s25, 0
	s_add_i32 s56, s56, s37
	global_load_lds_dwordx4 v[198:199], off
	v_lshl_add_u64 v[200:201], s[54:55], 0, v[0:1]
	s_mov_b32 m0, s56
	v_lshl_add_u64 v[206:207], s[26:27], 0, v[132:133]
	global_load_lds_dwordx4 v[200:201], off
	v_lshl_add_u64 v[200:201], s[54:55], 0, v[130:131]
	s_add_i32 m0, s56, 0x2000
	s_nop 0
	global_load_lds_dwordx4 v[200:201], off
	v_lshl_add_u64 v[200:201], s[26:27], 0, v[134:135]
	s_mov_b32 m0, s38
	s_nop 0
	global_load_lds_dwordx4 v[200:201], off
	s_mov_b32 m0, s39
	s_nop 0
	global_load_lds_dwordx4 v[206:207], off
	s_cmp_lg_u32 s53, 12
	s_cbranch_scc1 .Lp3w_nlA
	s_lshl_b32 s56, s47, 8
	s_add_i32 s56, s56, s42
	v_and_b32_e32 v228, 15, v212
	v_lshrrev_b32_e32 v229, 4, v212
	v_or_b32_e32 v228, s56, v228
	v_lshlrev_b32_e32 v228, 6, v228
	v_lshl_add_u32 v230, v229, 4, v228
	v_mov_b32_e32 v231, 0
	v_lshl_add_u64 v[250:251], s[6:7], 0, v[230:231]
	v_mov_b32_e32 v230, 0x2000
	v_lshl_add_u64 v[248:249], v[250:251], 0, v[230:231]
	global_load_dwordx4 v[228:231], v[250:251], off
	global_load_dwordx4 v[232:235], v[250:251], off offset:1024
	global_load_dwordx4 v[236:239], v[250:251], off offset:2048
	global_load_dwordx4 v[240:243], v[250:251], off offset:3072
	global_load_dwordx4 v[244:247], v[248:249], off
	s_nop 0
	global_load_dwordx4 v[248:251], v[248:249], off offset:1024
	s_waitcnt vmcnt(14)
	s_branch .Lp3w_jA

.Lp3w_jA:
	s_waitcnt lgkmcnt(0)
	s_barrier
	s_waitcnt lgkmcnt(0)
	v_mfma_f32_16x16x32_bf16 v[62:65], v[144:147], v[176:179], v[62:65]
	v_mfma_f32_16x16x32_bf16 v[54:57], v[152:155], v[176:179], v[54:57]
	v_mfma_f32_16x16x32_bf16 v[46:49], v[144:147], v[184:187], v[46:49]
	v_mfma_f32_16x16x32_bf16 v[38:41], v[152:155], v[184:187], v[38:41]
	v_mfma_f32_16x16x32_bf16 v[30:33], v[144:147], v[192:195], v[30:33]
	v_mfma_f32_16x16x32_bf16 v[22:25], v[152:155], v[192:195], v[22:25]
	v_mfma_f32_16x16x32_bf16 v[14:17], v[144:147], v[214:217], v[14:17]
	v_mfma_f32_16x16x32_bf16 v[6:9], v[152:155], v[214:217], v[6:9]
	v_mfma_f32_16x16x32_bf16 v[62:65], v[148:151], v[180:183], v[62:65]
	v_mfma_f32_16x16x32_bf16 v[54:57], v[156:159], v[180:183], v[54:57]
	v_mfma_f32_16x16x32_bf16 v[46:49], v[148:151], v[188:191], v[46:49]
	v_mfma_f32_16x16x32_bf16 v[38:41], v[156:159], v[188:191], v[38:41]
	v_mfma_f32_16x16x32_bf16 v[30:33], v[148:151], v[202:205], v[30:33]
	v_mfma_f32_16x16x32_bf16 v[22:25], v[156:159], v[202:205], v[22:25]
	v_mfma_f32_16x16x32_bf16 v[14:17], v[148:151], v[224:227], v[14:17]
	v_mfma_f32_16x16x32_bf16 v[6:9], v[156:159], v[224:227], v[6:9]
	v_mfma_f32_16x16x32_bf16 v[58:61], v[160:163], v[176:179], v[58:61]
	v_mfma_f32_16x16x32_bf16 v[50:53], v[168:171], v[176:179], v[50:53]
	v_mfma_f32_16x16x32_bf16 v[42:45], v[160:163], v[184:187], v[42:45]
	v_mfma_f32_16x16x32_bf16 v[34:37], v[168:171], v[184:187], v[34:37]
	v_mfma_f32_16x16x32_bf16 v[26:29], v[160:163], v[192:195], v[26:29]
	v_mfma_f32_16x16x32_bf16 v[18:21], v[168:171], v[192:195], v[18:21]
	v_mfma_f32_16x16x32_bf16 v[10:13], v[160:163], v[214:217], v[10:13]
	v_mfma_f32_16x16x32_bf16 v[2:5], v[168:171], v[214:217], v[2:5]
	v_mfma_f32_16x16x32_bf16 v[58:61], v[164:167], v[180:183], v[58:61]
	v_mfma_f32_16x16x32_bf16 v[50:53], v[172:175], v[180:183], v[50:53]
	v_mfma_f32_16x16x32_bf16 v[42:45], v[164:167], v[188:191], v[42:45]
	v_mfma_f32_16x16x32_bf16 v[34:37], v[172:175], v[188:191], v[34:37]
	v_mfma_f32_16x16x32_bf16 v[26:29], v[164:167], v[202:205], v[26:29]
	v_mfma_f32_16x16x32_bf16 v[18:21], v[172:175], v[202:205], v[18:21]
	v_mfma_f32_16x16x32_bf16 v[10:13], v[164:167], v[224:227], v[10:13]
	v_mfma_f32_16x16x32_bf16 v[2:5], v[172:175], v[224:227], v[2:5]
	s_barrier
	s_add_i32 s54, 0, 0x18000
	v_add_u32_e32 v140, s54, v141
	s_add_i32 s55, 0, 0x1c000
	ds_read_b128 v[144:147], v140
	ds_read_b128 v[148:151], v140 offset:1024
	ds_read_b128 v[152:155], v140 offset:2048
	ds_read_b128 v[156:159], v140 offset:3072
	v_add_u32_e32 v140, s55, v141
	ds_read_b128 v[160:163], v140
	ds_read_b128 v[164:167], v140 offset:1024
	ds_read_b128 v[168:171], v140 offset:2048
	ds_read_b128 v[172:175], v140 offset:3072
	s_add_u32 s26, s26, 0x40000
	s_addc_u32 s27, s27, 0
	s_mov_b32 m0, s40
	v_lshl_add_u64 v[210:211], s[26:27], 0, v[134:135]
	ds_read_b128 v[176:179], v143 offset:32768
	ds_read_b128 v[180:183], v143 offset:33792
	ds_read_b128 v[184:187], v143 offset:34816
	ds_read_b128 v[188:191], v143 offset:35840
	ds_read_b128 v[192:195], v143 offset:36864
	ds_read_b128 v[202:205], v143 offset:37888
	ds_read_b128 v[214:217], v143 offset:38912
	ds_read_b128 v[224:227], v143 offset:39936
	global_load_lds_dwordx4 v[210:211], off
	v_lshl_add_u64 v[210:211], s[26:27], 0, v[132:133]
	s_mov_b32 m0, s41
	s_nop 0
	global_load_lds_dwordx4 v[210:211], off
	s_cmp_lg_u32 s53, 12
	s_cbranch_scc1 .Lp3w_nlB
	s_waitcnt vmcnt(14)
	s_branch .Lp3w_jB

.Lp3w_jB:
	s_waitcnt lgkmcnt(0)
	s_barrier
	s_waitcnt lgkmcnt(0)
	v_mfma_f32_16x16x32_bf16 v[126:129], v[144:147], v[176:179], v[126:129]
	v_mfma_f32_16x16x32_bf16 v[118:121], v[152:155], v[176:179], v[118:121]
	v_mfma_f32_16x16x32_bf16 v[110:113], v[144:147], v[184:187], v[110:113]
	v_mfma_f32_16x16x32_bf16 v[102:105], v[152:155], v[184:187], v[102:105]
	v_mfma_f32_16x16x32_bf16 v[94:97], v[144:147], v[192:195], v[94:97]
	v_mfma_f32_16x16x32_bf16 v[86:89], v[152:155], v[192:195], v[86:89]
	v_mfma_f32_16x16x32_bf16 v[78:81], v[144:147], v[214:217], v[78:81]
	v_mfma_f32_16x16x32_bf16 v[70:73], v[152:155], v[214:217], v[70:73]
	v_mfma_f32_16x16x32_bf16 v[126:129], v[148:151], v[180:183], v[126:129]
	v_mfma_f32_16x16x32_bf16 v[118:121], v[156:159], v[180:183], v[118:121]
	v_mfma_f32_16x16x32_bf16 v[110:113], v[148:151], v[188:191], v[110:113]
	v_mfma_f32_16x16x32_bf16 v[102:105], v[156:159], v[188:191], v[102:105]
	v_mfma_f32_16x16x32_bf16 v[94:97], v[148:151], v[202:205], v[94:97]
	v_mfma_f32_16x16x32_bf16 v[86:89], v[156:159], v[202:205], v[86:89]
	v_mfma_f32_16x16x32_bf16 v[78:81], v[148:151], v[224:227], v[78:81]
	v_mfma_f32_16x16x32_bf16 v[70:73], v[156:159], v[224:227], v[70:73]
	v_mfma_f32_16x16x32_bf16 v[122:125], v[160:163], v[176:179], v[122:125]
	v_mfma_f32_16x16x32_bf16 v[114:117], v[168:171], v[176:179], v[114:117]
	v_mfma_f32_16x16x32_bf16 v[106:109], v[160:163], v[184:187], v[106:109]
	v_mfma_f32_16x16x32_bf16 v[98:101], v[168:171], v[184:187], v[98:101]
	v_mfma_f32_16x16x32_bf16 v[90:93], v[160:163], v[192:195], v[90:93]
	v_mfma_f32_16x16x32_bf16 v[82:85], v[168:171], v[192:195], v[82:85]
	v_mfma_f32_16x16x32_bf16 v[74:77], v[160:163], v[214:217], v[74:77]
	v_mfma_f32_16x16x32_bf16 v[66:69], v[168:171], v[214:217], v[66:69]
	v_mfma_f32_16x16x32_bf16 v[122:125], v[164:167], v[180:183], v[122:125]
	v_mfma_f32_16x16x32_bf16 v[114:117], v[172:175], v[180:183], v[114:117]
	v_mfma_f32_16x16x32_bf16 v[106:109], v[164:167], v[188:191], v[106:109]
	v_mfma_f32_16x16x32_bf16 v[98:101], v[172:175], v[188:191], v[98:101]
	v_mfma_f32_16x16x32_bf16 v[90:93], v[164:167], v[202:205], v[90:93]
	v_mfma_f32_16x16x32_bf16 v[82:85], v[172:175], v[202:205], v[82:85]
	v_mfma_f32_16x16x32_bf16 v[74:77], v[164:167], v[224:227], v[74:77]
	v_mfma_f32_16x16x32_bf16 v[66:69], v[172:175], v[224:227], v[66:69]
	s_barrier
	s_add_i32 s26, s54, s37
	v_lshl_add_u64 v[196:197], v[196:197], 0, s[94:95]
	s_mov_b32 m0, s26
	ds_read_b128 v[176:179], v143 offset:49152
	ds_read_b128 v[180:183], v143 offset:50176
	ds_read_b128 v[184:187], v143 offset:51200
	ds_read_b128 v[188:191], v143 offset:52224
	ds_read_b128 v[192:195], v143 offset:53248
	ds_read_b128 v[202:205], v143 offset:54272
	ds_read_b128 v[214:217], v143 offset:55296
	ds_read_b128 v[224:227], v143 offset:56320
	global_load_lds_dwordx4 v[196:197], off
	s_add_i32 m0, s26, 0x2000
	s_add_u32 s24, s24, 0x40080
	v_lshl_add_u64 v[196:197], v[198:199], 0, s[94:95]
	s_addc_u32 s25, s25, 0
	s_add_i32 s26, s55, s37
	global_load_lds_dwordx4 v[196:197], off
	v_lshl_add_u64 v[196:197], s[24:25], 0, v[0:1]
	s_mov_b32 m0, s26
	s_nop 0
	global_load_lds_dwordx4 v[196:197], off
	v_lshl_add_u64 v[196:197], s[24:25], 0, v[130:131]
	s_add_i32 m0, s26, 0x2000
	s_nop 0
	global_load_lds_dwordx4 v[196:197], off
	v_lshl_add_u64 v[196:197], v[200:201], 0, s[94:95]
	s_mov_b32 m0, s44
	s_nop 0
	global_load_lds_dwordx4 v[196:197], off
	v_lshl_add_u64 v[196:197], v[206:207], 0, s[94:95]
	s_mov_b32 m0, s45
	s_nop 0
	global_load_lds_dwordx4 v[196:197], off
	s_cmp_lg_u32 s53, 12
	s_cbranch_scc1 .Lp3w_nlC
	s_lshl_b32 s56, s47, 8
	s_add_i32 s56, s56, s42
	v_and_b32_e32 v196, 15, v212
	v_lshrrev_b32_e32 v197, 4, v212
	v_or_b32_e32 v196, s56, v196
	v_lshlrev_b32_e32 v196, 6, v196
	v_lshl_add_u32 v196, v197, 4, v196
	v_add_u32_e32 v196, 0x2800, v196
	v_mov_b32_e32 v197, 0
	v_lshl_add_u64 v[210:211], s[6:7], 0, v[196:197]
	global_load_dwordx4 v[196:199], v[210:211], off
	global_load_dwordx2 v[200:201], v[210:211], off offset:1024
	global_load_dwordx2 v[206:207], v[210:211], off offset:1032
	s_waitcnt vmcnt(17)
	s_branch .Lp3w_jC

.Lp3w_jC:
	s_waitcnt lgkmcnt(0)
	s_barrier
	s_waitcnt lgkmcnt(0)
	v_mfma_f32_16x16x32_bf16 v[62:65], v[144:147], v[176:179], v[62:65]
	v_mfma_f32_16x16x32_bf16 v[54:57], v[152:155], v[176:179], v[54:57]
	v_mfma_f32_16x16x32_bf16 v[46:49], v[144:147], v[184:187], v[46:49]
	v_mfma_f32_16x16x32_bf16 v[38:41], v[152:155], v[184:187], v[38:41]
	v_mfma_f32_16x16x32_bf16 v[30:33], v[144:147], v[192:195], v[30:33]
	v_mfma_f32_16x16x32_bf16 v[22:25], v[152:155], v[192:195], v[22:25]
	v_mfma_f32_16x16x32_bf16 v[14:17], v[144:147], v[214:217], v[14:17]
	v_mfma_f32_16x16x32_bf16 v[6:9], v[152:155], v[214:217], v[6:9]
	v_mfma_f32_16x16x32_bf16 v[62:65], v[148:151], v[180:183], v[62:65]
	v_mfma_f32_16x16x32_bf16 v[54:57], v[156:159], v[180:183], v[54:57]
	v_mfma_f32_16x16x32_bf16 v[46:49], v[148:151], v[188:191], v[46:49]
	v_mfma_f32_16x16x32_bf16 v[38:41], v[156:159], v[188:191], v[38:41]
	v_mfma_f32_16x16x32_bf16 v[30:33], v[148:151], v[202:205], v[30:33]
	v_mfma_f32_16x16x32_bf16 v[22:25], v[156:159], v[202:205], v[22:25]
	v_mfma_f32_16x16x32_bf16 v[14:17], v[148:151], v[224:227], v[14:17]
	v_mfma_f32_16x16x32_bf16 v[6:9], v[156:159], v[224:227], v[6:9]
	v_mfma_f32_16x16x32_bf16 v[58:61], v[160:163], v[176:179], v[58:61]
	v_mfma_f32_16x16x32_bf16 v[50:53], v[168:171], v[176:179], v[50:53]
	v_mfma_f32_16x16x32_bf16 v[42:45], v[160:163], v[184:187], v[42:45]
	v_mfma_f32_16x16x32_bf16 v[34:37], v[168:171], v[184:187], v[34:37]
	v_mfma_f32_16x16x32_bf16 v[26:29], v[160:163], v[192:195], v[26:29]
	v_mfma_f32_16x16x32_bf16 v[18:21], v[168:171], v[192:195], v[18:21]
	v_mfma_f32_16x16x32_bf16 v[10:13], v[160:163], v[214:217], v[10:13]
	v_mfma_f32_16x16x32_bf16 v[2:5], v[168:171], v[214:217], v[2:5]
	v_mfma_f32_16x16x32_bf16 v[58:61], v[164:167], v[180:183], v[58:61]
	v_mfma_f32_16x16x32_bf16 v[50:53], v[172:175], v[180:183], v[50:53]
	v_mfma_f32_16x16x32_bf16 v[42:45], v[164:167], v[188:191], v[42:45]
	v_mfma_f32_16x16x32_bf16 v[34:37], v[172:175], v[188:191], v[34:37]
	v_mfma_f32_16x16x32_bf16 v[26:29], v[164:167], v[202:205], v[26:29]
	v_mfma_f32_16x16x32_bf16 v[18:21], v[172:175], v[202:205], v[18:21]
	v_mfma_f32_16x16x32_bf16 v[10:13], v[164:167], v[224:227], v[10:13]
	v_mfma_f32_16x16x32_bf16 v[2:5], v[172:175], v[224:227], v[2:5]
	s_barrier
	s_add_i32 s53, s53, 2
	s_add_u32 s22, s22, 0x100
	s_addc_u32 s23, s23, 0
	s_add_u32 s51, s51, 0x100
	s_addc_u32 s52, s52, 0
	s_cmp_gt_u32 s53, 13
	s_cbranch_scc0 .LBB0_1083
	v_mov_b32_e32 v140, v212
	s_lshl_b32 s13, s48, 7
	v_and_b32_e32 v153, 15, v140
	v_ashrrev_i32_e32 v140, 4, v140
	s_or_b32 s13, s13, s43
	v_lshl_add_u32 v152, v140, 3, s13
	s_lshl_b32 s13, s47, 8
	s_movk_i32 s15, 0x2000
	v_readlane_b32 s26, v252, 55
	s_and_b64 vcc, exec, s[10:11]
	s_cbranch_vccz .LBB0_1086
	s_barrier

.LBB0_1115:
	s_add_u32 s28, s46, s26
	s_addc_u32 s29, s47, s27
	s_add_u32 s28, s28, 0xc000100
	s_addc_u32 s29, s29, 0
	s_add_u32 s51, s48, s26
	s_addc_u32 s52, s49, s27
	s_add_i32 s53, 0, 0x10000
	s_cmpk_eq_i32 s26, 0x700
	s_cselect_b32 s31, s9, s29
	s_cselect_b32 s30, s8, s28
	s_cselect_b32 s29, s7, s52
	s_cselect_b32 s28, s6, s51
	s_add_i32 s51, 0, 0x14000
	v_add_u32_e32 v154, s53, v116
	v_add_u32_e32 v170, s51, v116
	ds_read_b128 v[118:121], v154
	ds_read_b128 v[146:149], v154 offset:1024
	ds_read_b128 v[150:153], v154 offset:2048
	ds_read_b128 v[154:157], v154 offset:3072
	ds_read_b128 v[158:161], v170
	ds_read_b128 v[162:165], v170 offset:1024
	ds_read_b128 v[166:169], v170 offset:2048
	ds_read_b128 v[170:173], v170 offset:3072
	v_lshl_add_u64 v[182:183], v[112:113], 0, s[26:27]
	s_add_i32 m0, s5, 0xc000
	ds_read_b128 v[174:177], v117
	ds_read_b128 v[178:181], v117 offset:1024
	ds_read_b128 v[186:189], v117 offset:2048
	ds_read_b128 v[190:193], v117 offset:3072
	ds_read_b128 v[194:197], v117 offset:4096
	ds_read_b128 v[198:201], v117 offset:5120
	ds_read_b128 v[202:205], v117 offset:6144
	ds_read_b128 v[214:217], v117 offset:7168
	global_load_lds_dwordx4 v[182:183], off
	v_lshl_add_u64 v[182:183], v[114:115], 0, s[26:27]
	s_add_i32 m0, s5, 0xe000
	s_nop 0
	global_load_lds_dwordx4 v[182:183], off
	s_waitcnt vmcnt(8)
	s_waitcnt lgkmcnt(0)
	s_barrier
	s_waitcnt lgkmcnt(0)
	v_mfma_f32_16x16x32_bf16 v[62:65], v[118:121], v[174:177], v[62:65]
	v_mfma_f32_16x16x32_bf16 v[58:61], v[150:153], v[174:177], v[58:61]
	v_mfma_f32_16x16x32_bf16 v[54:57], v[118:121], v[186:189], v[54:57]
	v_mfma_f32_16x16x32_bf16 v[50:53], v[150:153], v[186:189], v[50:53]
	v_mfma_f32_16x16x32_bf16 v[46:49], v[118:121], v[194:197], v[46:49]
	v_mfma_f32_16x16x32_bf16 v[42:45], v[150:153], v[194:197], v[42:45]
	v_mfma_f32_16x16x32_bf16 v[38:41], v[118:121], v[202:205], v[38:41]
	v_mfma_f32_16x16x32_bf16 v[34:37], v[150:153], v[202:205], v[34:37]
	v_mfma_f32_16x16x32_bf16 v[62:65], v[146:149], v[178:181], v[62:65]
	v_mfma_f32_16x16x32_bf16 v[58:61], v[154:157], v[178:181], v[58:61]
	v_mfma_f32_16x16x32_bf16 v[54:57], v[146:149], v[190:193], v[54:57]
	v_mfma_f32_16x16x32_bf16 v[50:53], v[154:157], v[190:193], v[50:53]
	v_mfma_f32_16x16x32_bf16 v[46:49], v[146:149], v[198:201], v[46:49]
	v_mfma_f32_16x16x32_bf16 v[42:45], v[154:157], v[198:201], v[42:45]
	v_mfma_f32_16x16x32_bf16 v[38:41], v[146:149], v[214:217], v[38:41]
	v_mfma_f32_16x16x32_bf16 v[34:37], v[154:157], v[214:217], v[34:37]
	v_mfma_f32_16x16x32_bf16 v[142:145], v[158:161], v[174:177], v[142:145]
	v_mfma_f32_16x16x32_bf16 v[138:141], v[166:169], v[174:177], v[138:141]
	v_mfma_f32_16x16x32_bf16 v[134:137], v[158:161], v[186:189], v[134:137]
	v_mfma_f32_16x16x32_bf16 v[130:133], v[166:169], v[186:189], v[130:133]
	v_mfma_f32_16x16x32_bf16 v[126:129], v[158:161], v[194:197], v[126:129]
	v_mfma_f32_16x16x32_bf16 v[122:125], v[166:169], v[194:197], v[122:125]
	v_mfma_f32_16x16x32_bf16 v[102:105], v[158:161], v[202:205], v[102:105]
	v_mfma_f32_16x16x32_bf16 v[98:101], v[166:169], v[202:205], v[98:101]
	v_mfma_f32_16x16x32_bf16 v[142:145], v[162:165], v[178:181], v[142:145]
	v_mfma_f32_16x16x32_bf16 v[138:141], v[170:173], v[178:181], v[138:141]
	v_mfma_f32_16x16x32_bf16 v[134:137], v[162:165], v[190:193], v[134:137]
	v_mfma_f32_16x16x32_bf16 v[130:133], v[170:173], v[190:193], v[130:133]
	v_mfma_f32_16x16x32_bf16 v[126:129], v[162:165], v[198:201], v[126:129]
	v_mfma_f32_16x16x32_bf16 v[122:125], v[170:173], v[198:201], v[122:125]
	v_mfma_f32_16x16x32_bf16 v[102:105], v[162:165], v[214:217], v[102:105]
	v_mfma_f32_16x16x32_bf16 v[98:101], v[170:173], v[214:217], v[98:101]
	s_barrier
	s_add_i32 s52, s53, s40
	v_lshl_add_u64 v[182:183], s[28:29], 0, v[0:1]
	s_mov_b32 m0, s52
	ds_read_b128 v[174:177], v117 offset:16384
	ds_read_b128 v[178:181], v117 offset:17408
	ds_read_b128 v[186:189], v117 offset:18432
	ds_read_b128 v[190:193], v117 offset:19456
	ds_read_b128 v[194:197], v117 offset:20480
	ds_read_b128 v[198:201], v117 offset:21504
	ds_read_b128 v[202:205], v117 offset:22528
	ds_read_b128 v[214:217], v117 offset:23552
	global_load_lds_dwordx4 v[182:183], off
	s_add_i32 m0, s52, 0x2000
	s_add_u32 s52, s28, 0x40000
	v_lshl_add_u64 v[206:207], s[28:29], 0, v[110:111]
	s_addc_u32 s53, s29, 0
	s_add_i32 s51, s51, s40
	global_load_lds_dwordx4 v[206:207], off
	v_lshl_add_u64 v[210:211], s[52:53], 0, v[0:1]
	s_mov_b32 m0, s51
	v_lshl_add_u64 v[224:225], s[30:31], 0, v[108:109]
	global_load_lds_dwordx4 v[210:211], off
	v_lshl_add_u64 v[210:211], s[52:53], 0, v[110:111]
	s_add_i32 m0, s51, 0x2000
	s_nop 0
	global_load_lds_dwordx4 v[210:211], off
	v_lshl_add_u64 v[210:211], s[30:31], 0, v[106:107]
	s_mov_b32 m0, s5
	s_nop 0
	global_load_lds_dwordx4 v[210:211], off
	s_mov_b32 m0, s41
	s_nop 0
	global_load_lds_dwordx4 v[224:225], off
	s_waitcnt vmcnt(8)
	s_waitcnt lgkmcnt(0)
	s_barrier
	s_waitcnt lgkmcnt(0)
	v_mfma_f32_16x16x32_bf16 v[30:33], v[118:121], v[174:177], v[30:33]
	v_mfma_f32_16x16x32_bf16 v[26:29], v[150:153], v[174:177], v[26:29]
	v_mfma_f32_16x16x32_bf16 v[22:25], v[118:121], v[186:189], v[22:25]
	v_mfma_f32_16x16x32_bf16 v[18:21], v[150:153], v[186:189], v[18:21]
	v_mfma_f32_16x16x32_bf16 v[14:17], v[118:121], v[194:197], v[14:17]
	v_mfma_f32_16x16x32_bf16 v[10:13], v[150:153], v[194:197], v[10:13]
	v_mfma_f32_16x16x32_bf16 v[6:9], v[118:121], v[202:205], v[6:9]
	v_mfma_f32_16x16x32_bf16 v[2:5], v[150:153], v[202:205], v[2:5]
	v_mfma_f32_16x16x32_bf16 v[30:33], v[146:149], v[178:181], v[30:33]
	v_mfma_f32_16x16x32_bf16 v[26:29], v[154:157], v[178:181], v[26:29]
	v_mfma_f32_16x16x32_bf16 v[22:25], v[146:149], v[190:193], v[22:25]
	v_mfma_f32_16x16x32_bf16 v[18:21], v[154:157], v[190:193], v[18:21]
	v_mfma_f32_16x16x32_bf16 v[14:17], v[146:149], v[198:201], v[14:17]
	v_mfma_f32_16x16x32_bf16 v[10:13], v[154:157], v[198:201], v[10:13]
	v_mfma_f32_16x16x32_bf16 v[6:9], v[146:149], v[214:217], v[6:9]
	v_mfma_f32_16x16x32_bf16 v[2:5], v[154:157], v[214:217], v[2:5]
	v_mfma_f32_16x16x32_bf16 v[94:97], v[158:161], v[174:177], v[94:97]
	v_mfma_f32_16x16x32_bf16 v[90:93], v[166:169], v[174:177], v[90:93]
	v_mfma_f32_16x16x32_bf16 v[86:89], v[158:161], v[186:189], v[86:89]
	v_mfma_f32_16x16x32_bf16 v[82:85], v[166:169], v[186:189], v[82:85]
	v_mfma_f32_16x16x32_bf16 v[78:81], v[158:161], v[194:197], v[78:81]
	v_mfma_f32_16x16x32_bf16 v[74:77], v[166:169], v[194:197], v[74:77]
	v_mfma_f32_16x16x32_bf16 v[70:73], v[158:161], v[202:205], v[70:73]
	v_mfma_f32_16x16x32_bf16 v[66:69], v[166:169], v[202:205], v[66:69]
	v_mfma_f32_16x16x32_bf16 v[94:97], v[162:165], v[178:181], v[94:97]
	v_mfma_f32_16x16x32_bf16 v[90:93], v[170:173], v[178:181], v[90:93]
	v_mfma_f32_16x16x32_bf16 v[86:89], v[162:165], v[190:193], v[86:89]
	v_mfma_f32_16x16x32_bf16 v[82:85], v[170:173], v[190:193], v[82:85]
	v_mfma_f32_16x16x32_bf16 v[78:81], v[162:165], v[198:201], v[78:81]
	v_mfma_f32_16x16x32_bf16 v[74:77], v[170:173], v[198:201], v[74:77]
	v_mfma_f32_16x16x32_bf16 v[70:73], v[162:165], v[214:217], v[70:73]
	v_mfma_f32_16x16x32_bf16 v[66:69], v[170:173], v[214:217], v[66:69]
	s_barrier
	s_add_i32 s51, 0, 0x18000
	s_add_i32 s52, 0, 0x1c000
	v_add_u32_e32 v154, s51, v116
	v_add_u32_e32 v170, s52, v116
	ds_read_b128 v[118:121], v154
	ds_read_b128 v[146:149], v154 offset:1024
	ds_read_b128 v[150:153], v154 offset:2048
	ds_read_b128 v[154:157], v154 offset:3072
	ds_read_b128 v[158:161], v170
	ds_read_b128 v[162:165], v170 offset:1024
	ds_read_b128 v[166:169], v170 offset:2048
	ds_read_b128 v[170:173], v170 offset:3072
	s_add_u32 s30, s30, 0x40000
	s_addc_u32 s31, s31, 0
	s_mov_b32 m0, s42
	v_lshl_add_u64 v[226:227], s[30:31], 0, v[106:107]
	ds_read_b128 v[174:177], v117 offset:32768
	ds_read_b128 v[178:181], v117 offset:33792
	ds_read_b128 v[186:189], v117 offset:34816
	ds_read_b128 v[190:193], v117 offset:35840
	ds_read_b128 v[194:197], v117 offset:36864
	ds_read_b128 v[198:201], v117 offset:37888
	ds_read_b128 v[202:205], v117 offset:38912
	ds_read_b128 v[214:217], v117 offset:39936
	global_load_lds_dwordx4 v[226:227], off
	v_lshl_add_u64 v[226:227], s[30:31], 0, v[108:109]
	s_mov_b32 m0, s43
	s_nop 0
	global_load_lds_dwordx4 v[226:227], off
	s_waitcnt vmcnt(8)
	s_waitcnt lgkmcnt(0)
	s_barrier
	s_waitcnt lgkmcnt(0)
	v_mfma_f32_16x16x32_bf16 v[62:65], v[118:121], v[174:177], v[62:65]
	v_mfma_f32_16x16x32_bf16 v[58:61], v[150:153], v[174:177], v[58:61]
	v_mfma_f32_16x16x32_bf16 v[54:57], v[118:121], v[186:189], v[54:57]
	v_mfma_f32_16x16x32_bf16 v[50:53], v[150:153], v[186:189], v[50:53]
	v_mfma_f32_16x16x32_bf16 v[46:49], v[118:121], v[194:197], v[46:49]
	v_mfma_f32_16x16x32_bf16 v[42:45], v[150:153], v[194:197], v[42:45]
	v_mfma_f32_16x16x32_bf16 v[38:41], v[118:121], v[202:205], v[38:41]
	v_mfma_f32_16x16x32_bf16 v[34:37], v[150:153], v[202:205], v[34:37]
	v_mfma_f32_16x16x32_bf16 v[62:65], v[146:149], v[178:181], v[62:65]
	v_mfma_f32_16x16x32_bf16 v[58:61], v[154:157], v[178:181], v[58:61]
	v_mfma_f32_16x16x32_bf16 v[54:57], v[146:149], v[190:193], v[54:57]
	v_mfma_f32_16x16x32_bf16 v[50:53], v[154:157], v[190:193], v[50:53]
	v_mfma_f32_16x16x32_bf16 v[46:49], v[146:149], v[198:201], v[46:49]
	v_mfma_f32_16x16x32_bf16 v[42:45], v[154:157], v[198:201], v[42:45]
	v_mfma_f32_16x16x32_bf16 v[38:41], v[146:149], v[214:217], v[38:41]
	v_mfma_f32_16x16x32_bf16 v[34:37], v[154:157], v[214:217], v[34:37]
	v_mfma_f32_16x16x32_bf16 v[142:145], v[158:161], v[174:177], v[142:145]
	v_mfma_f32_16x16x32_bf16 v[138:141], v[166:169], v[174:177], v[138:141]
	v_mfma_f32_16x16x32_bf16 v[134:137], v[158:161], v[186:189], v[134:137]
	v_mfma_f32_16x16x32_bf16 v[130:133], v[166:169], v[186:189], v[130:133]
	v_mfma_f32_16x16x32_bf16 v[126:129], v[158:161], v[194:197], v[126:129]
	v_mfma_f32_16x16x32_bf16 v[122:125], v[166:169], v[194:197], v[122:125]
	v_mfma_f32_16x16x32_bf16 v[102:105], v[158:161], v[202:205], v[102:105]
	v_mfma_f32_16x16x32_bf16 v[98:101], v[166:169], v[202:205], v[98:101]
	v_mfma_f32_16x16x32_bf16 v[142:145], v[162:165], v[178:181], v[142:145]
	v_mfma_f32_16x16x32_bf16 v[138:141], v[170:173], v[178:181], v[138:141]
	v_mfma_f32_16x16x32_bf16 v[134:137], v[162:165], v[190:193], v[134:137]
	v_mfma_f32_16x16x32_bf16 v[130:133], v[170:173], v[190:193], v[130:133]
	v_mfma_f32_16x16x32_bf16 v[126:129], v[162:165], v[198:201], v[126:129]
	v_mfma_f32_16x16x32_bf16 v[122:125], v[170:173], v[198:201], v[122:125]
	v_mfma_f32_16x16x32_bf16 v[102:105], v[162:165], v[214:217], v[102:105]
	v_mfma_f32_16x16x32_bf16 v[98:101], v[170:173], v[214:217], v[98:101]
	s_barrier
	s_add_i32 s30, s51, s40
	v_lshl_add_u64 v[182:183], v[182:183], 0, s[94:95]
	s_mov_b32 m0, s30
	ds_read_b128 v[174:177], v117 offset:49152
	ds_read_b128 v[178:181], v117 offset:50176
	ds_read_b128 v[186:189], v117 offset:51200
	ds_read_b128 v[190:193], v117 offset:52224
	ds_read_b128 v[194:197], v117 offset:53248
	ds_read_b128 v[198:201], v117 offset:54272
	ds_read_b128 v[202:205], v117 offset:55296
	ds_read_b128 v[214:217], v117 offset:56320
	global_load_lds_dwordx4 v[182:183], off
	s_add_i32 m0, s30, 0x2000
	s_add_u32 s28, s28, 0x40080
	v_lshl_add_u64 v[182:183], v[206:207], 0, s[94:95]
	s_addc_u32 s29, s29, 0
	s_add_i32 s30, s52, s40
	global_load_lds_dwordx4 v[182:183], off
	v_lshl_add_u64 v[182:183], s[28:29], 0, v[0:1]
	s_mov_b32 m0, s30
	s_nop 0
	global_load_lds_dwordx4 v[182:183], off
	v_lshl_add_u64 v[182:183], s[28:29], 0, v[110:111]
	s_add_i32 m0, s30, 0x2000
	s_nop 0
	global_load_lds_dwordx4 v[182:183], off
	v_lshl_add_u64 v[182:183], v[210:211], 0, s[94:95]
	s_mov_b32 m0, s44
	s_nop 0
	global_load_lds_dwordx4 v[182:183], off
	v_lshl_add_u64 v[182:183], v[224:225], 0, s[94:95]
	s_mov_b32 m0, s45
	s_nop 0
	global_load_lds_dwordx4 v[182:183], off
	s_waitcnt vmcnt(8)
	s_waitcnt lgkmcnt(0)
	s_barrier
	s_waitcnt lgkmcnt(0)
	v_mfma_f32_16x16x32_bf16 v[30:33], v[118:121], v[174:177], v[30:33]
	v_mfma_f32_16x16x32_bf16 v[26:29], v[150:153], v[174:177], v[26:29]
	v_mfma_f32_16x16x32_bf16 v[22:25], v[118:121], v[186:189], v[22:25]
	v_mfma_f32_16x16x32_bf16 v[18:21], v[150:153], v[186:189], v[18:21]
	v_mfma_f32_16x16x32_bf16 v[14:17], v[118:121], v[194:197], v[14:17]
	v_mfma_f32_16x16x32_bf16 v[10:13], v[150:153], v[194:197], v[10:13]
	v_mfma_f32_16x16x32_bf16 v[6:9], v[118:121], v[202:205], v[6:9]
	v_mfma_f32_16x16x32_bf16 v[2:5], v[150:153], v[202:205], v[2:5]
	v_mfma_f32_16x16x32_bf16 v[30:33], v[146:149], v[178:181], v[30:33]
	v_mfma_f32_16x16x32_bf16 v[26:29], v[154:157], v[178:181], v[26:29]
	v_mfma_f32_16x16x32_bf16 v[22:25], v[146:149], v[190:193], v[22:25]
	v_mfma_f32_16x16x32_bf16 v[18:21], v[154:157], v[190:193], v[18:21]
	v_mfma_f32_16x16x32_bf16 v[14:17], v[146:149], v[198:201], v[14:17]
	v_mfma_f32_16x16x32_bf16 v[10:13], v[154:157], v[198:201], v[10:13]
	v_mfma_f32_16x16x32_bf16 v[6:9], v[146:149], v[214:217], v[6:9]
	v_mfma_f32_16x16x32_bf16 v[2:5], v[154:157], v[214:217], v[2:5]
	v_mfma_f32_16x16x32_bf16 v[94:97], v[158:161], v[174:177], v[94:97]
	v_mfma_f32_16x16x32_bf16 v[90:93], v[166:169], v[174:177], v[90:93]
	v_mfma_f32_16x16x32_bf16 v[86:89], v[158:161], v[186:189], v[86:89]
	v_mfma_f32_16x16x32_bf16 v[82:85], v[166:169], v[186:189], v[82:85]
	v_mfma_f32_16x16x32_bf16 v[78:81], v[158:161], v[194:197], v[78:81]
	v_mfma_f32_16x16x32_bf16 v[74:77], v[166:169], v[194:197], v[74:77]
	v_mfma_f32_16x16x32_bf16 v[70:73], v[158:161], v[202:205], v[70:73]
	v_mfma_f32_16x16x32_bf16 v[66:69], v[166:169], v[202:205], v[66:69]
	v_mfma_f32_16x16x32_bf16 v[94:97], v[162:165], v[178:181], v[94:97]
	v_mfma_f32_16x16x32_bf16 v[90:93], v[170:173], v[178:181], v[90:93]
	v_mfma_f32_16x16x32_bf16 v[86:89], v[162:165], v[190:193], v[86:89]
	v_mfma_f32_16x16x32_bf16 v[82:85], v[170:173], v[190:193], v[82:85]
	v_mfma_f32_16x16x32_bf16 v[78:81], v[162:165], v[198:201], v[78:81]
	v_mfma_f32_16x16x32_bf16 v[74:77], v[170:173], v[198:201], v[74:77]
	v_mfma_f32_16x16x32_bf16 v[70:73], v[162:165], v[214:217], v[70:73]
	v_mfma_f32_16x16x32_bf16 v[66:69], v[170:173], v[214:217], v[66:69]
	s_barrier
	s_add_i32 s50, s50, 2
	s_add_u32 s26, s26, 0x100
	s_addc_u32 s27, s27, 0
	s_cmp_gt_u32 s50, 13
	s_cbranch_scc0 .LBB0_1115
	s_cmpk_lt_u32 s39, 0x100
	s_cbranch_scc0 .LBB0_1118
	s_barrier

.LBB0_1180:
	s_add_u32 s8, s46, s6
	s_addc_u32 s9, s47, s7
	s_add_u32 s8, s8, 0x2a400100
	s_addc_u32 s9, s9, 0
	s_add_u32 s51, s48, s6
	s_addc_u32 s52, s49, s7
	s_add_i32 s53, 0, 0x10000
	s_cmpk_eq_i32 s6, 0x1500
	s_cselect_b32 s27, s5, s9
	s_cselect_b32 s26, s4, s8
	s_cselect_b32 s9, s3, s52
	s_cselect_b32 s8, s2, s51
	s_add_i32 s51, 0, 0x14000
	v_add_u32_e32 v150, s53, v136
	v_add_u32_e32 v166, s51, v136
	ds_read_b128 v[138:141], v150
	ds_read_b128 v[142:145], v150 offset:1024
	ds_read_b128 v[146:149], v150 offset:2048
	ds_read_b128 v[150:153], v150 offset:3072
	ds_read_b128 v[154:157], v166
	ds_read_b128 v[158:161], v166 offset:1024
	ds_read_b128 v[162:165], v166 offset:2048
	ds_read_b128 v[166:169], v166 offset:3072
	v_lshl_add_u64 v[182:183], v[132:133], 0, s[6:7]
	s_add_i32 m0, s39, 0xc000
	ds_read_b128 v[170:173], v137
	ds_read_b128 v[174:177], v137 offset:1024
	ds_read_b128 v[178:181], v137 offset:2048
	ds_read_b128 v[186:189], v137 offset:3072
	ds_read_b128 v[190:193], v137 offset:4096
	ds_read_b128 v[194:197], v137 offset:5120
	ds_read_b128 v[198:201], v137 offset:6144
	ds_read_b128 v[202:205], v137 offset:7168
	global_load_lds_dwordx4 v[182:183], off
	v_lshl_add_u64 v[182:183], v[134:135], 0, s[6:7]
	s_add_i32 m0, s39, 0xe000
	s_nop 0
	global_load_lds_dwordx4 v[182:183], off
	s_waitcnt vmcnt(8)
	s_waitcnt lgkmcnt(0)
	s_barrier
	s_waitcnt lgkmcnt(0)
	v_mfma_f32_16x16x32_bf16 v[126:129], v[138:141], v[170:173], v[126:129]
	v_mfma_f32_16x16x32_bf16 v[122:125], v[146:149], v[170:173], v[122:125]
	v_mfma_f32_16x16x32_bf16 v[110:113], v[138:141], v[178:181], v[110:113]
	v_mfma_f32_16x16x32_bf16 v[106:109], v[146:149], v[178:181], v[106:109]
	v_mfma_f32_16x16x32_bf16 v[94:97], v[138:141], v[190:193], v[94:97]
	v_mfma_f32_16x16x32_bf16 v[90:93], v[146:149], v[190:193], v[90:93]
	v_mfma_f32_16x16x32_bf16 v[78:81], v[138:141], v[198:201], v[78:81]
	v_mfma_f32_16x16x32_bf16 v[74:77], v[146:149], v[198:201], v[74:77]
	v_mfma_f32_16x16x32_bf16 v[126:129], v[142:145], v[174:177], v[126:129]
	v_mfma_f32_16x16x32_bf16 v[122:125], v[150:153], v[174:177], v[122:125]
	v_mfma_f32_16x16x32_bf16 v[110:113], v[142:145], v[186:189], v[110:113]
	v_mfma_f32_16x16x32_bf16 v[106:109], v[150:153], v[186:189], v[106:109]
	v_mfma_f32_16x16x32_bf16 v[94:97], v[142:145], v[194:197], v[94:97]
	v_mfma_f32_16x16x32_bf16 v[90:93], v[150:153], v[194:197], v[90:93]
	v_mfma_f32_16x16x32_bf16 v[78:81], v[142:145], v[202:205], v[78:81]
	v_mfma_f32_16x16x32_bf16 v[74:77], v[150:153], v[202:205], v[74:77]
	v_mfma_f32_16x16x32_bf16 v[118:121], v[154:157], v[170:173], v[118:121]
	v_mfma_f32_16x16x32_bf16 v[114:117], v[162:165], v[170:173], v[114:117]
	v_mfma_f32_16x16x32_bf16 v[102:105], v[154:157], v[178:181], v[102:105]
	v_mfma_f32_16x16x32_bf16 v[98:101], v[162:165], v[178:181], v[98:101]
	v_mfma_f32_16x16x32_bf16 v[86:89], v[154:157], v[190:193], v[86:89]
	v_mfma_f32_16x16x32_bf16 v[82:85], v[162:165], v[190:193], v[82:85]
	v_mfma_f32_16x16x32_bf16 v[70:73], v[154:157], v[198:201], v[70:73]
	v_mfma_f32_16x16x32_bf16 v[66:69], v[162:165], v[198:201], v[66:69]
	v_mfma_f32_16x16x32_bf16 v[118:121], v[158:161], v[174:177], v[118:121]
	v_mfma_f32_16x16x32_bf16 v[114:117], v[166:169], v[174:177], v[114:117]
	v_mfma_f32_16x16x32_bf16 v[102:105], v[158:161], v[186:189], v[102:105]
	v_mfma_f32_16x16x32_bf16 v[98:101], v[166:169], v[186:189], v[98:101]
	v_mfma_f32_16x16x32_bf16 v[86:89], v[158:161], v[194:197], v[86:89]
	v_mfma_f32_16x16x32_bf16 v[82:85], v[166:169], v[194:197], v[82:85]
	v_mfma_f32_16x16x32_bf16 v[70:73], v[158:161], v[202:205], v[70:73]
	v_mfma_f32_16x16x32_bf16 v[66:69], v[166:169], v[202:205], v[66:69]
	s_barrier
	s_add_i32 s52, s53, s38
	v_lshl_add_u64 v[182:183], s[8:9], 0, v[0:1]
	s_mov_b32 m0, s52
	ds_read_b128 v[170:173], v137 offset:16384
	ds_read_b128 v[174:177], v137 offset:17408
	ds_read_b128 v[178:181], v137 offset:18432
	ds_read_b128 v[186:189], v137 offset:19456
	ds_read_b128 v[190:193], v137 offset:20480
	ds_read_b128 v[194:197], v137 offset:21504
	ds_read_b128 v[198:201], v137 offset:22528
	ds_read_b128 v[202:205], v137 offset:23552
	global_load_lds_dwordx4 v[182:183], off
	s_add_i32 m0, s52, 0x2000
	s_add_u32 s52, s8, 0xb0000
	v_lshl_add_u64 v[206:207], s[8:9], 0, v[130:131]
	s_addc_u32 s53, s9, 0
	s_add_i32 s51, s51, s38
	global_load_lds_dwordx4 v[206:207], off
	v_lshl_add_u64 v[210:211], s[52:53], 0, v[0:1]
	s_mov_b32 m0, s51
	v_lshl_add_u64 v[214:215], s[26:27], 0, v[130:131]
	global_load_lds_dwordx4 v[210:211], off
	v_lshl_add_u64 v[210:211], s[52:53], 0, v[130:131]
	s_add_i32 m0, s51, 0x2000
	s_nop 0
	global_load_lds_dwordx4 v[210:211], off
	v_lshl_add_u64 v[210:211], s[26:27], 0, v[0:1]
	s_mov_b32 m0, s39
	s_nop 0
	global_load_lds_dwordx4 v[210:211], off
	s_mov_b32 m0, s40
	s_nop 0
	global_load_lds_dwordx4 v[214:215], off
	s_waitcnt vmcnt(8)
	s_waitcnt lgkmcnt(0)
	s_barrier
	s_waitcnt lgkmcnt(0)
	v_mfma_f32_16x16x32_bf16 v[62:65], v[138:141], v[170:173], v[62:65]
	v_mfma_f32_16x16x32_bf16 v[58:61], v[146:149], v[170:173], v[58:61]
	v_mfma_f32_16x16x32_bf16 v[46:49], v[138:141], v[178:181], v[46:49]
	v_mfma_f32_16x16x32_bf16 v[42:45], v[146:149], v[178:181], v[42:45]
	v_mfma_f32_16x16x32_bf16 v[30:33], v[138:141], v[190:193], v[30:33]
	v_mfma_f32_16x16x32_bf16 v[26:29], v[146:149], v[190:193], v[26:29]
	v_mfma_f32_16x16x32_bf16 v[14:17], v[138:141], v[198:201], v[14:17]
	v_mfma_f32_16x16x32_bf16 v[10:13], v[146:149], v[198:201], v[10:13]
	v_mfma_f32_16x16x32_bf16 v[62:65], v[142:145], v[174:177], v[62:65]
	v_mfma_f32_16x16x32_bf16 v[58:61], v[150:153], v[174:177], v[58:61]
	v_mfma_f32_16x16x32_bf16 v[46:49], v[142:145], v[186:189], v[46:49]
	v_mfma_f32_16x16x32_bf16 v[42:45], v[150:153], v[186:189], v[42:45]
	v_mfma_f32_16x16x32_bf16 v[30:33], v[142:145], v[194:197], v[30:33]
	v_mfma_f32_16x16x32_bf16 v[26:29], v[150:153], v[194:197], v[26:29]
	v_mfma_f32_16x16x32_bf16 v[14:17], v[142:145], v[202:205], v[14:17]
	v_mfma_f32_16x16x32_bf16 v[10:13], v[150:153], v[202:205], v[10:13]
	v_mfma_f32_16x16x32_bf16 v[54:57], v[154:157], v[170:173], v[54:57]
	v_mfma_f32_16x16x32_bf16 v[50:53], v[162:165], v[170:173], v[50:53]
	v_mfma_f32_16x16x32_bf16 v[38:41], v[154:157], v[178:181], v[38:41]
	v_mfma_f32_16x16x32_bf16 v[34:37], v[162:165], v[178:181], v[34:37]
	v_mfma_f32_16x16x32_bf16 v[22:25], v[154:157], v[190:193], v[22:25]
	v_mfma_f32_16x16x32_bf16 v[18:21], v[162:165], v[190:193], v[18:21]
	v_mfma_f32_16x16x32_bf16 v[6:9], v[154:157], v[198:201], v[6:9]
	v_mfma_f32_16x16x32_bf16 v[2:5], v[162:165], v[198:201], v[2:5]
	v_mfma_f32_16x16x32_bf16 v[54:57], v[158:161], v[174:177], v[54:57]
	v_mfma_f32_16x16x32_bf16 v[50:53], v[166:169], v[174:177], v[50:53]
	v_mfma_f32_16x16x32_bf16 v[38:41], v[158:161], v[186:189], v[38:41]
	v_mfma_f32_16x16x32_bf16 v[34:37], v[166:169], v[186:189], v[34:37]
	v_mfma_f32_16x16x32_bf16 v[22:25], v[158:161], v[194:197], v[22:25]
	v_mfma_f32_16x16x32_bf16 v[18:21], v[166:169], v[194:197], v[18:21]
	v_mfma_f32_16x16x32_bf16 v[6:9], v[158:161], v[202:205], v[6:9]
	v_mfma_f32_16x16x32_bf16 v[2:5], v[166:169], v[202:205], v[2:5]
	s_barrier
	s_add_i32 s51, 0, 0x18000
	s_add_i32 s52, 0, 0x1c000
	v_add_u32_e32 v150, s51, v136
	v_add_u32_e32 v166, s52, v136
	ds_read_b128 v[138:141], v150
	ds_read_b128 v[142:145], v150 offset:1024
	ds_read_b128 v[146:149], v150 offset:2048
	ds_read_b128 v[150:153], v150 offset:3072
	ds_read_b128 v[154:157], v166
	ds_read_b128 v[158:161], v166 offset:1024
	ds_read_b128 v[162:165], v166 offset:2048
	ds_read_b128 v[166:169], v166 offset:3072
	s_add_u32 s26, s26, 0xb0000
	s_addc_u32 s27, s27, 0
	s_mov_b32 m0, s41
	v_lshl_add_u64 v[216:217], s[26:27], 0, v[0:1]
	ds_read_b128 v[170:173], v137 offset:32768
	ds_read_b128 v[174:177], v137 offset:33792
	ds_read_b128 v[178:181], v137 offset:34816
	ds_read_b128 v[186:189], v137 offset:35840
	ds_read_b128 v[190:193], v137 offset:36864
	ds_read_b128 v[194:197], v137 offset:37888
	ds_read_b128 v[198:201], v137 offset:38912
	ds_read_b128 v[202:205], v137 offset:39936
	global_load_lds_dwordx4 v[216:217], off
	v_lshl_add_u64 v[216:217], s[26:27], 0, v[130:131]
	s_mov_b32 m0, s43
	s_nop 0
	global_load_lds_dwordx4 v[216:217], off
	s_waitcnt vmcnt(8)
	s_waitcnt lgkmcnt(0)
	s_barrier
	s_waitcnt lgkmcnt(0)
	v_mfma_f32_16x16x32_bf16 v[126:129], v[138:141], v[170:173], v[126:129]
	v_mfma_f32_16x16x32_bf16 v[122:125], v[146:149], v[170:173], v[122:125]
	v_mfma_f32_16x16x32_bf16 v[110:113], v[138:141], v[178:181], v[110:113]
	v_mfma_f32_16x16x32_bf16 v[106:109], v[146:149], v[178:181], v[106:109]
	v_mfma_f32_16x16x32_bf16 v[94:97], v[138:141], v[190:193], v[94:97]
	v_mfma_f32_16x16x32_bf16 v[90:93], v[146:149], v[190:193], v[90:93]
	v_mfma_f32_16x16x32_bf16 v[78:81], v[138:141], v[198:201], v[78:81]
	v_mfma_f32_16x16x32_bf16 v[74:77], v[146:149], v[198:201], v[74:77]
	v_mfma_f32_16x16x32_bf16 v[126:129], v[142:145], v[174:177], v[126:129]
	v_mfma_f32_16x16x32_bf16 v[122:125], v[150:153], v[174:177], v[122:125]
	v_mfma_f32_16x16x32_bf16 v[110:113], v[142:145], v[186:189], v[110:113]
	v_mfma_f32_16x16x32_bf16 v[106:109], v[150:153], v[186:189], v[106:109]
	v_mfma_f32_16x16x32_bf16 v[94:97], v[142:145], v[194:197], v[94:97]
	v_mfma_f32_16x16x32_bf16 v[90:93], v[150:153], v[194:197], v[90:93]
	v_mfma_f32_16x16x32_bf16 v[78:81], v[142:145], v[202:205], v[78:81]
	v_mfma_f32_16x16x32_bf16 v[74:77], v[150:153], v[202:205], v[74:77]
	v_mfma_f32_16x16x32_bf16 v[118:121], v[154:157], v[170:173], v[118:121]
	v_mfma_f32_16x16x32_bf16 v[114:117], v[162:165], v[170:173], v[114:117]
	v_mfma_f32_16x16x32_bf16 v[102:105], v[154:157], v[178:181], v[102:105]
	v_mfma_f32_16x16x32_bf16 v[98:101], v[162:165], v[178:181], v[98:101]
	v_mfma_f32_16x16x32_bf16 v[86:89], v[154:157], v[190:193], v[86:89]
	v_mfma_f32_16x16x32_bf16 v[82:85], v[162:165], v[190:193], v[82:85]
	v_mfma_f32_16x16x32_bf16 v[70:73], v[154:157], v[198:201], v[70:73]
	v_mfma_f32_16x16x32_bf16 v[66:69], v[162:165], v[198:201], v[66:69]
	v_mfma_f32_16x16x32_bf16 v[118:121], v[158:161], v[174:177], v[118:121]
	v_mfma_f32_16x16x32_bf16 v[114:117], v[166:169], v[174:177], v[114:117]
	v_mfma_f32_16x16x32_bf16 v[102:105], v[158:161], v[186:189], v[102:105]
	v_mfma_f32_16x16x32_bf16 v[98:101], v[166:169], v[186:189], v[98:101]
	v_mfma_f32_16x16x32_bf16 v[86:89], v[158:161], v[194:197], v[86:89]
	v_mfma_f32_16x16x32_bf16 v[82:85], v[166:169], v[194:197], v[82:85]
	v_mfma_f32_16x16x32_bf16 v[70:73], v[158:161], v[202:205], v[70:73]
	v_mfma_f32_16x16x32_bf16 v[66:69], v[166:169], v[202:205], v[66:69]
	s_barrier
	s_add_i32 s26, s51, s38
	v_lshl_add_u64 v[182:183], v[182:183], 0, s[94:95]
	s_mov_b32 m0, s26
	ds_read_b128 v[170:173], v137 offset:49152
	ds_read_b128 v[174:177], v137 offset:50176
	ds_read_b128 v[178:181], v137 offset:51200
	ds_read_b128 v[186:189], v137 offset:52224
	ds_read_b128 v[190:193], v137 offset:53248
	ds_read_b128 v[194:197], v137 offset:54272
	ds_read_b128 v[198:201], v137 offset:55296
	ds_read_b128 v[202:205], v137 offset:56320
	global_load_lds_dwordx4 v[182:183], off
	s_add_i32 m0, s26, 0x2000
	s_add_u32 s8, s8, 0xb0080
	v_lshl_add_u64 v[182:183], v[206:207], 0, s[94:95]
	s_addc_u32 s9, s9, 0
	s_add_i32 s26, s52, s38
	global_load_lds_dwordx4 v[182:183], off
	v_lshl_add_u64 v[182:183], s[8:9], 0, v[0:1]
	s_mov_b32 m0, s26
	s_nop 0
	global_load_lds_dwordx4 v[182:183], off
	v_lshl_add_u64 v[182:183], s[8:9], 0, v[130:131]
	s_add_i32 m0, s26, 0x2000
	s_nop 0
	global_load_lds_dwordx4 v[182:183], off
	v_lshl_add_u64 v[182:183], v[210:211], 0, s[94:95]
	s_mov_b32 m0, s44
	s_nop 0
	global_load_lds_dwordx4 v[182:183], off
	v_lshl_add_u64 v[182:183], v[214:215], 0, s[94:95]
	s_mov_b32 m0, s45
	s_nop 0
	global_load_lds_dwordx4 v[182:183], off
	s_waitcnt vmcnt(8)
	s_waitcnt lgkmcnt(0)
	s_barrier
	s_waitcnt lgkmcnt(0)
	v_mfma_f32_16x16x32_bf16 v[62:65], v[138:141], v[170:173], v[62:65]
	v_mfma_f32_16x16x32_bf16 v[58:61], v[146:149], v[170:173], v[58:61]
	v_mfma_f32_16x16x32_bf16 v[46:49], v[138:141], v[178:181], v[46:49]
	v_mfma_f32_16x16x32_bf16 v[42:45], v[146:149], v[178:181], v[42:45]
	v_mfma_f32_16x16x32_bf16 v[30:33], v[138:141], v[190:193], v[30:33]
	v_mfma_f32_16x16x32_bf16 v[26:29], v[146:149], v[190:193], v[26:29]
	v_mfma_f32_16x16x32_bf16 v[14:17], v[138:141], v[198:201], v[14:17]
	v_mfma_f32_16x16x32_bf16 v[10:13], v[146:149], v[198:201], v[10:13]
	v_mfma_f32_16x16x32_bf16 v[62:65], v[142:145], v[174:177], v[62:65]
	v_mfma_f32_16x16x32_bf16 v[58:61], v[150:153], v[174:177], v[58:61]
	v_mfma_f32_16x16x32_bf16 v[46:49], v[142:145], v[186:189], v[46:49]
	v_mfma_f32_16x16x32_bf16 v[42:45], v[150:153], v[186:189], v[42:45]
	v_mfma_f32_16x16x32_bf16 v[30:33], v[142:145], v[194:197], v[30:33]
	v_mfma_f32_16x16x32_bf16 v[26:29], v[150:153], v[194:197], v[26:29]
	v_mfma_f32_16x16x32_bf16 v[14:17], v[142:145], v[202:205], v[14:17]
	v_mfma_f32_16x16x32_bf16 v[10:13], v[150:153], v[202:205], v[10:13]
	v_mfma_f32_16x16x32_bf16 v[54:57], v[154:157], v[170:173], v[54:57]
	v_mfma_f32_16x16x32_bf16 v[50:53], v[162:165], v[170:173], v[50:53]
	v_mfma_f32_16x16x32_bf16 v[38:41], v[154:157], v[178:181], v[38:41]
	v_mfma_f32_16x16x32_bf16 v[34:37], v[162:165], v[178:181], v[34:37]
	v_mfma_f32_16x16x32_bf16 v[22:25], v[154:157], v[190:193], v[22:25]
	v_mfma_f32_16x16x32_bf16 v[18:21], v[162:165], v[190:193], v[18:21]
	v_mfma_f32_16x16x32_bf16 v[6:9], v[154:157], v[198:201], v[6:9]
	v_mfma_f32_16x16x32_bf16 v[2:5], v[162:165], v[198:201], v[2:5]
	v_mfma_f32_16x16x32_bf16 v[54:57], v[158:161], v[174:177], v[54:57]
	v_mfma_f32_16x16x32_bf16 v[50:53], v[166:169], v[174:177], v[50:53]
	v_mfma_f32_16x16x32_bf16 v[38:41], v[158:161], v[186:189], v[38:41]
	v_mfma_f32_16x16x32_bf16 v[34:37], v[166:169], v[186:189], v[34:37]
	v_mfma_f32_16x16x32_bf16 v[22:25], v[158:161], v[194:197], v[22:25]
	v_mfma_f32_16x16x32_bf16 v[18:21], v[166:169], v[194:197], v[18:21]
	v_mfma_f32_16x16x32_bf16 v[6:9], v[158:161], v[202:205], v[6:9]
	v_mfma_f32_16x16x32_bf16 v[2:5], v[166:169], v[202:205], v[2:5]
	s_barrier
	s_add_i32 s50, s50, 2
	s_add_u32 s6, s6, 0x100
	s_addc_u32 s7, s7, 0
	s_cmp_gt_u32 s50, 41
	s_cbranch_scc0 .LBB0_1180
	s_cmpk_lt_u32 s31, 0x100
	s_cbranch_scc0 .LBB0_1183
	s_barrier

.LBB0_1192:
	s_add_u32 s26, s44, s24
	s_addc_u32 s27, s45, s25
	s_add_u32 s26, s26, 0xc000100
	s_addc_u32 s27, s27, 0
	s_add_u32 s49, s46, s24
	s_addc_u32 s50, s47, s25
	s_add_i32 s51, 0, 0x10000
	s_cmpk_eq_i32 s24, 0x700
	s_cselect_b32 s29, s9, s27
	s_cselect_b32 s28, s8, s26
	s_cselect_b32 s27, s7, s50
	s_cselect_b32 s26, s6, s49
	s_add_i32 s49, 0, 0x14000
	v_add_u32_e32 v154, s51, v140
	v_add_u32_e32 v170, s49, v140
	ds_read_b128 v[142:145], v154
	ds_read_b128 v[146:149], v154 offset:1024
	ds_read_b128 v[150:153], v154 offset:2048
	ds_read_b128 v[154:157], v154 offset:3072
	ds_read_b128 v[158:161], v170
	ds_read_b128 v[162:165], v170 offset:1024
	ds_read_b128 v[166:169], v170 offset:2048
	ds_read_b128 v[170:173], v170 offset:3072
	v_lshl_add_u64 v[182:183], v[136:137], 0, s[24:25]
	s_add_i32 m0, s5, 0xc000
	ds_read_b128 v[174:177], v141
	ds_read_b128 v[178:181], v141 offset:1024
	ds_read_b128 v[186:189], v141 offset:2048
	ds_read_b128 v[190:193], v141 offset:3072
	ds_read_b128 v[194:197], v141 offset:4096
	ds_read_b128 v[198:201], v141 offset:5120
	ds_read_b128 v[202:205], v141 offset:6144
	ds_read_b128 v[214:217], v141 offset:7168
	global_load_lds_dwordx4 v[182:183], off
	v_lshl_add_u64 v[182:183], v[138:139], 0, s[24:25]
	s_add_i32 m0, s5, 0xe000
	s_nop 0
	global_load_lds_dwordx4 v[182:183], off
	s_waitcnt vmcnt(8)
	s_waitcnt lgkmcnt(0)
	s_barrier
	s_waitcnt lgkmcnt(0)
	v_mfma_f32_16x16x32_bf16 v[126:129], v[142:145], v[174:177], v[126:129]
	v_mfma_f32_16x16x32_bf16 v[118:121], v[150:153], v[174:177], v[118:121]
	v_mfma_f32_16x16x32_bf16 v[110:113], v[142:145], v[186:189], v[110:113]
	v_mfma_f32_16x16x32_bf16 v[102:105], v[150:153], v[186:189], v[102:105]
	v_mfma_f32_16x16x32_bf16 v[94:97], v[142:145], v[194:197], v[94:97]
	v_mfma_f32_16x16x32_bf16 v[86:89], v[150:153], v[194:197], v[86:89]
	v_mfma_f32_16x16x32_bf16 v[78:81], v[142:145], v[202:205], v[78:81]
	v_mfma_f32_16x16x32_bf16 v[70:73], v[150:153], v[202:205], v[70:73]
	v_mfma_f32_16x16x32_bf16 v[126:129], v[146:149], v[178:181], v[126:129]
	v_mfma_f32_16x16x32_bf16 v[118:121], v[154:157], v[178:181], v[118:121]
	v_mfma_f32_16x16x32_bf16 v[110:113], v[146:149], v[190:193], v[110:113]
	v_mfma_f32_16x16x32_bf16 v[102:105], v[154:157], v[190:193], v[102:105]
	v_mfma_f32_16x16x32_bf16 v[94:97], v[146:149], v[198:201], v[94:97]
	v_mfma_f32_16x16x32_bf16 v[86:89], v[154:157], v[198:201], v[86:89]
	v_mfma_f32_16x16x32_bf16 v[78:81], v[146:149], v[214:217], v[78:81]
	v_mfma_f32_16x16x32_bf16 v[70:73], v[154:157], v[214:217], v[70:73]
	v_mfma_f32_16x16x32_bf16 v[122:125], v[158:161], v[174:177], v[122:125]
	v_mfma_f32_16x16x32_bf16 v[114:117], v[166:169], v[174:177], v[114:117]
	v_mfma_f32_16x16x32_bf16 v[106:109], v[158:161], v[186:189], v[106:109]
	v_mfma_f32_16x16x32_bf16 v[98:101], v[166:169], v[186:189], v[98:101]
	v_mfma_f32_16x16x32_bf16 v[90:93], v[158:161], v[194:197], v[90:93]
	v_mfma_f32_16x16x32_bf16 v[82:85], v[166:169], v[194:197], v[82:85]
	v_mfma_f32_16x16x32_bf16 v[74:77], v[158:161], v[202:205], v[74:77]
	v_mfma_f32_16x16x32_bf16 v[66:69], v[166:169], v[202:205], v[66:69]
	v_mfma_f32_16x16x32_bf16 v[122:125], v[162:165], v[178:181], v[122:125]
	v_mfma_f32_16x16x32_bf16 v[114:117], v[170:173], v[178:181], v[114:117]
	v_mfma_f32_16x16x32_bf16 v[106:109], v[162:165], v[190:193], v[106:109]
	v_mfma_f32_16x16x32_bf16 v[98:101], v[170:173], v[190:193], v[98:101]
	v_mfma_f32_16x16x32_bf16 v[90:93], v[162:165], v[198:201], v[90:93]
	v_mfma_f32_16x16x32_bf16 v[82:85], v[170:173], v[198:201], v[82:85]
	v_mfma_f32_16x16x32_bf16 v[74:77], v[162:165], v[214:217], v[74:77]
	v_mfma_f32_16x16x32_bf16 v[66:69], v[170:173], v[214:217], v[66:69]
	s_barrier
	s_add_i32 s50, s51, s31
	v_lshl_add_u64 v[182:183], s[26:27], 0, v[0:1]
	s_mov_b32 m0, s50
	ds_read_b128 v[174:177], v141 offset:16384
	ds_read_b128 v[178:181], v141 offset:17408
	ds_read_b128 v[186:189], v141 offset:18432
	ds_read_b128 v[190:193], v141 offset:19456
	ds_read_b128 v[194:197], v141 offset:20480
	ds_read_b128 v[198:201], v141 offset:21504
	ds_read_b128 v[202:205], v141 offset:22528
	ds_read_b128 v[214:217], v141 offset:23552
	global_load_lds_dwordx4 v[182:183], off
	s_add_i32 m0, s50, 0x2000
	s_add_u32 s50, s26, 0x40000
	v_lshl_add_u64 v[206:207], s[26:27], 0, v[134:135]
	s_addc_u32 s51, s27, 0
	s_add_i32 s49, s49, s31
	global_load_lds_dwordx4 v[206:207], off
	v_lshl_add_u64 v[210:211], s[50:51], 0, v[0:1]
	s_mov_b32 m0, s49
	v_lshl_add_u64 v[224:225], s[28:29], 0, v[132:133]
	global_load_lds_dwordx4 v[210:211], off
	v_lshl_add_u64 v[210:211], s[50:51], 0, v[134:135]
	s_add_i32 m0, s49, 0x2000
	s_nop 0
	global_load_lds_dwordx4 v[210:211], off
	v_lshl_add_u64 v[210:211], s[28:29], 0, v[130:131]
	s_mov_b32 m0, s5
	s_nop 0
	global_load_lds_dwordx4 v[210:211], off
	s_mov_b32 m0, s38
	s_nop 0
	global_load_lds_dwordx4 v[224:225], off
	s_waitcnt vmcnt(8)
	s_waitcnt lgkmcnt(0)
	s_barrier
	s_waitcnt lgkmcnt(0)
	v_mfma_f32_16x16x32_bf16 v[62:65], v[142:145], v[174:177], v[62:65]
	v_mfma_f32_16x16x32_bf16 v[54:57], v[150:153], v[174:177], v[54:57]
	v_mfma_f32_16x16x32_bf16 v[46:49], v[142:145], v[186:189], v[46:49]
	v_mfma_f32_16x16x32_bf16 v[38:41], v[150:153], v[186:189], v[38:41]
	v_mfma_f32_16x16x32_bf16 v[30:33], v[142:145], v[194:197], v[30:33]
	v_mfma_f32_16x16x32_bf16 v[22:25], v[150:153], v[194:197], v[22:25]
	v_mfma_f32_16x16x32_bf16 v[14:17], v[142:145], v[202:205], v[14:17]
	v_mfma_f32_16x16x32_bf16 v[6:9], v[150:153], v[202:205], v[6:9]
	v_mfma_f32_16x16x32_bf16 v[62:65], v[146:149], v[178:181], v[62:65]
	v_mfma_f32_16x16x32_bf16 v[54:57], v[154:157], v[178:181], v[54:57]
	v_mfma_f32_16x16x32_bf16 v[46:49], v[146:149], v[190:193], v[46:49]
	v_mfma_f32_16x16x32_bf16 v[38:41], v[154:157], v[190:193], v[38:41]
	v_mfma_f32_16x16x32_bf16 v[30:33], v[146:149], v[198:201], v[30:33]
	v_mfma_f32_16x16x32_bf16 v[22:25], v[154:157], v[198:201], v[22:25]
	v_mfma_f32_16x16x32_bf16 v[14:17], v[146:149], v[214:217], v[14:17]
	v_mfma_f32_16x16x32_bf16 v[6:9], v[154:157], v[214:217], v[6:9]
	v_mfma_f32_16x16x32_bf16 v[58:61], v[158:161], v[174:177], v[58:61]
	v_mfma_f32_16x16x32_bf16 v[50:53], v[166:169], v[174:177], v[50:53]
	v_mfma_f32_16x16x32_bf16 v[42:45], v[158:161], v[186:189], v[42:45]
	v_mfma_f32_16x16x32_bf16 v[34:37], v[166:169], v[186:189], v[34:37]
	v_mfma_f32_16x16x32_bf16 v[26:29], v[158:161], v[194:197], v[26:29]
	v_mfma_f32_16x16x32_bf16 v[18:21], v[166:169], v[194:197], v[18:21]
	v_mfma_f32_16x16x32_bf16 v[10:13], v[158:161], v[202:205], v[10:13]
	v_mfma_f32_16x16x32_bf16 v[2:5], v[166:169], v[202:205], v[2:5]
	v_mfma_f32_16x16x32_bf16 v[58:61], v[162:165], v[178:181], v[58:61]
	v_mfma_f32_16x16x32_bf16 v[50:53], v[170:173], v[178:181], v[50:53]
	v_mfma_f32_16x16x32_bf16 v[42:45], v[162:165], v[190:193], v[42:45]
	v_mfma_f32_16x16x32_bf16 v[34:37], v[170:173], v[190:193], v[34:37]
	v_mfma_f32_16x16x32_bf16 v[26:29], v[162:165], v[198:201], v[26:29]
	v_mfma_f32_16x16x32_bf16 v[18:21], v[170:173], v[198:201], v[18:21]
	v_mfma_f32_16x16x32_bf16 v[10:13], v[162:165], v[214:217], v[10:13]
	v_mfma_f32_16x16x32_bf16 v[2:5], v[170:173], v[214:217], v[2:5]
	s_barrier
	s_add_i32 s49, 0, 0x18000
	s_add_i32 s50, 0, 0x1c000
	v_add_u32_e32 v154, s49, v140
	v_add_u32_e32 v170, s50, v140
	ds_read_b128 v[142:145], v154
	ds_read_b128 v[146:149], v154 offset:1024
	ds_read_b128 v[150:153], v154 offset:2048
	ds_read_b128 v[154:157], v154 offset:3072
	ds_read_b128 v[158:161], v170
	ds_read_b128 v[162:165], v170 offset:1024
	ds_read_b128 v[166:169], v170 offset:2048
	ds_read_b128 v[170:173], v170 offset:3072
	s_add_u32 s28, s28, 0x40000
	s_addc_u32 s29, s29, 0
	s_mov_b32 m0, s39
	v_lshl_add_u64 v[226:227], s[28:29], 0, v[130:131]
	ds_read_b128 v[174:177], v141 offset:32768
	ds_read_b128 v[178:181], v141 offset:33792
	ds_read_b128 v[186:189], v141 offset:34816
	ds_read_b128 v[190:193], v141 offset:35840
	ds_read_b128 v[194:197], v141 offset:36864
	ds_read_b128 v[198:201], v141 offset:37888
	ds_read_b128 v[202:205], v141 offset:38912
	ds_read_b128 v[214:217], v141 offset:39936
	global_load_lds_dwordx4 v[226:227], off
	v_lshl_add_u64 v[226:227], s[28:29], 0, v[132:133]
	s_mov_b32 m0, s40
	s_nop 0
	global_load_lds_dwordx4 v[226:227], off
	s_waitcnt vmcnt(8)
	s_waitcnt lgkmcnt(0)
	s_barrier
	s_waitcnt lgkmcnt(0)
	v_mfma_f32_16x16x32_bf16 v[126:129], v[142:145], v[174:177], v[126:129]
	v_mfma_f32_16x16x32_bf16 v[118:121], v[150:153], v[174:177], v[118:121]
	v_mfma_f32_16x16x32_bf16 v[110:113], v[142:145], v[186:189], v[110:113]
	v_mfma_f32_16x16x32_bf16 v[102:105], v[150:153], v[186:189], v[102:105]
	v_mfma_f32_16x16x32_bf16 v[94:97], v[142:145], v[194:197], v[94:97]
	v_mfma_f32_16x16x32_bf16 v[86:89], v[150:153], v[194:197], v[86:89]
	v_mfma_f32_16x16x32_bf16 v[78:81], v[142:145], v[202:205], v[78:81]
	v_mfma_f32_16x16x32_bf16 v[70:73], v[150:153], v[202:205], v[70:73]
	v_mfma_f32_16x16x32_bf16 v[126:129], v[146:149], v[178:181], v[126:129]
	v_mfma_f32_16x16x32_bf16 v[118:121], v[154:157], v[178:181], v[118:121]
	v_mfma_f32_16x16x32_bf16 v[110:113], v[146:149], v[190:193], v[110:113]
	v_mfma_f32_16x16x32_bf16 v[102:105], v[154:157], v[190:193], v[102:105]
	v_mfma_f32_16x16x32_bf16 v[94:97], v[146:149], v[198:201], v[94:97]
	v_mfma_f32_16x16x32_bf16 v[86:89], v[154:157], v[198:201], v[86:89]
	v_mfma_f32_16x16x32_bf16 v[78:81], v[146:149], v[214:217], v[78:81]
	v_mfma_f32_16x16x32_bf16 v[70:73], v[154:157], v[214:217], v[70:73]
	v_mfma_f32_16x16x32_bf16 v[122:125], v[158:161], v[174:177], v[122:125]
	v_mfma_f32_16x16x32_bf16 v[114:117], v[166:169], v[174:177], v[114:117]
	v_mfma_f32_16x16x32_bf16 v[106:109], v[158:161], v[186:189], v[106:109]
	v_mfma_f32_16x16x32_bf16 v[98:101], v[166:169], v[186:189], v[98:101]
	v_mfma_f32_16x16x32_bf16 v[90:93], v[158:161], v[194:197], v[90:93]
	v_mfma_f32_16x16x32_bf16 v[82:85], v[166:169], v[194:197], v[82:85]
	v_mfma_f32_16x16x32_bf16 v[74:77], v[158:161], v[202:205], v[74:77]
	v_mfma_f32_16x16x32_bf16 v[66:69], v[166:169], v[202:205], v[66:69]
	v_mfma_f32_16x16x32_bf16 v[122:125], v[162:165], v[178:181], v[122:125]
	v_mfma_f32_16x16x32_bf16 v[114:117], v[170:173], v[178:181], v[114:117]
	v_mfma_f32_16x16x32_bf16 v[106:109], v[162:165], v[190:193], v[106:109]
	v_mfma_f32_16x16x32_bf16 v[98:101], v[170:173], v[190:193], v[98:101]
	v_mfma_f32_16x16x32_bf16 v[90:93], v[162:165], v[198:201], v[90:93]
	v_mfma_f32_16x16x32_bf16 v[82:85], v[170:173], v[198:201], v[82:85]
	v_mfma_f32_16x16x32_bf16 v[74:77], v[162:165], v[214:217], v[74:77]
	v_mfma_f32_16x16x32_bf16 v[66:69], v[170:173], v[214:217], v[66:69]
	s_barrier
	s_add_i32 s28, s49, s31
	v_lshl_add_u64 v[182:183], v[182:183], 0, s[94:95]
	s_mov_b32 m0, s28
	ds_read_b128 v[174:177], v141 offset:49152
	ds_read_b128 v[178:181], v141 offset:50176
	ds_read_b128 v[186:189], v141 offset:51200
	ds_read_b128 v[190:193], v141 offset:52224
	ds_read_b128 v[194:197], v141 offset:53248
	ds_read_b128 v[198:201], v141 offset:54272
	ds_read_b128 v[202:205], v141 offset:55296
	ds_read_b128 v[214:217], v141 offset:56320
	global_load_lds_dwordx4 v[182:183], off
	s_add_i32 m0, s28, 0x2000
	s_add_u32 s26, s26, 0x40080
	v_lshl_add_u64 v[182:183], v[206:207], 0, s[94:95]
	s_addc_u32 s27, s27, 0
	s_add_i32 s28, s50, s31
	global_load_lds_dwordx4 v[182:183], off
	v_lshl_add_u64 v[182:183], s[26:27], 0, v[0:1]
	s_mov_b32 m0, s28
	s_nop 0
	global_load_lds_dwordx4 v[182:183], off
	v_lshl_add_u64 v[182:183], s[26:27], 0, v[134:135]
	s_add_i32 m0, s28, 0x2000
	s_nop 0
	global_load_lds_dwordx4 v[182:183], off
	v_lshl_add_u64 v[182:183], v[210:211], 0, s[94:95]
	s_mov_b32 m0, s42
	s_nop 0
	global_load_lds_dwordx4 v[182:183], off
	v_lshl_add_u64 v[182:183], v[224:225], 0, s[94:95]
	s_mov_b32 m0, s43
	s_nop 0
	global_load_lds_dwordx4 v[182:183], off
	s_waitcnt vmcnt(8)
	s_waitcnt lgkmcnt(0)
	s_barrier
	s_waitcnt lgkmcnt(0)
	v_mfma_f32_16x16x32_bf16 v[62:65], v[142:145], v[174:177], v[62:65]
	v_mfma_f32_16x16x32_bf16 v[54:57], v[150:153], v[174:177], v[54:57]
	v_mfma_f32_16x16x32_bf16 v[46:49], v[142:145], v[186:189], v[46:49]
	v_mfma_f32_16x16x32_bf16 v[38:41], v[150:153], v[186:189], v[38:41]
	v_mfma_f32_16x16x32_bf16 v[30:33], v[142:145], v[194:197], v[30:33]
	v_mfma_f32_16x16x32_bf16 v[22:25], v[150:153], v[194:197], v[22:25]
	v_mfma_f32_16x16x32_bf16 v[14:17], v[142:145], v[202:205], v[14:17]
	v_mfma_f32_16x16x32_bf16 v[6:9], v[150:153], v[202:205], v[6:9]
	v_mfma_f32_16x16x32_bf16 v[62:65], v[146:149], v[178:181], v[62:65]
	v_mfma_f32_16x16x32_bf16 v[54:57], v[154:157], v[178:181], v[54:57]
	v_mfma_f32_16x16x32_bf16 v[46:49], v[146:149], v[190:193], v[46:49]
	v_mfma_f32_16x16x32_bf16 v[38:41], v[154:157], v[190:193], v[38:41]
	v_mfma_f32_16x16x32_bf16 v[30:33], v[146:149], v[198:201], v[30:33]
	v_mfma_f32_16x16x32_bf16 v[22:25], v[154:157], v[198:201], v[22:25]
	v_mfma_f32_16x16x32_bf16 v[14:17], v[146:149], v[214:217], v[14:17]
	v_mfma_f32_16x16x32_bf16 v[6:9], v[154:157], v[214:217], v[6:9]
	v_mfma_f32_16x16x32_bf16 v[58:61], v[158:161], v[174:177], v[58:61]
	v_mfma_f32_16x16x32_bf16 v[50:53], v[166:169], v[174:177], v[50:53]
	v_mfma_f32_16x16x32_bf16 v[42:45], v[158:161], v[186:189], v[42:45]
	v_mfma_f32_16x16x32_bf16 v[34:37], v[166:169], v[186:189], v[34:37]
	v_mfma_f32_16x16x32_bf16 v[26:29], v[158:161], v[194:197], v[26:29]
	v_mfma_f32_16x16x32_bf16 v[18:21], v[166:169], v[194:197], v[18:21]
	v_mfma_f32_16x16x32_bf16 v[10:13], v[158:161], v[202:205], v[10:13]
	v_mfma_f32_16x16x32_bf16 v[2:5], v[166:169], v[202:205], v[2:5]
	v_mfma_f32_16x16x32_bf16 v[58:61], v[162:165], v[178:181], v[58:61]
	v_mfma_f32_16x16x32_bf16 v[50:53], v[170:173], v[178:181], v[50:53]
	v_mfma_f32_16x16x32_bf16 v[42:45], v[162:165], v[190:193], v[42:45]
	v_mfma_f32_16x16x32_bf16 v[34:37], v[170:173], v[190:193], v[34:37]
	v_mfma_f32_16x16x32_bf16 v[26:29], v[162:165], v[198:201], v[26:29]
	v_mfma_f32_16x16x32_bf16 v[18:21], v[170:173], v[198:201], v[18:21]
	v_mfma_f32_16x16x32_bf16 v[10:13], v[162:165], v[214:217], v[10:13]
	v_mfma_f32_16x16x32_bf16 v[2:5], v[170:173], v[214:217], v[2:5]
	s_barrier
	s_add_i32 s48, s48, 2
	s_add_u32 s24, s24, 0x100
	s_addc_u32 s25, s25, 0
	s_cmp_gt_u32 s48, 13
	s_cbranch_scc0 .LBB0_1192
	s_cmpk_lt_u32 s30, 0x100
	s_cbranch_scc0 .LBB0_1195
	s_barrier

.LBB0_1202:
	s_add_u32 s20, s41, s8
	s_addc_u32 s21, s42, s9
	s_add_u32 s20, s20, 0x14200100
	s_addc_u32 s21, s21, 0
	s_add_u32 s46, s43, s8
	s_addc_u32 s47, s44, s9
	s_add_i32 s48, 0, 0x10000
	s_cmpk_eq_i32 s8, 0x700
	s_cselect_b32 s23, s7, s21
	s_cselect_b32 s22, s6, s20
	s_cselect_b32 s21, s5, s47
	s_cselect_b32 s20, s4, s46
	s_add_i32 s49, 0, 0x14000
	v_add_u32_e32 v150, s48, v136
	v_add_u32_e32 v166, s49, v136
	ds_read_b128 v[138:141], v150
	ds_read_b128 v[142:145], v150 offset:1024
	ds_read_b128 v[146:149], v150 offset:2048
	ds_read_b128 v[150:153], v150 offset:3072
	ds_read_b128 v[154:157], v166
	ds_read_b128 v[158:161], v166 offset:1024
	ds_read_b128 v[162:165], v166 offset:2048
	ds_read_b128 v[166:169], v166 offset:3072
	v_lshl_add_u64 v[182:183], v[132:133], 0, s[8:9]
	s_add_i32 m0, s29, 0xc000
	ds_read_b128 v[170:173], v137
	ds_read_b128 v[174:177], v137 offset:1024
	ds_read_b128 v[178:181], v137 offset:2048
	ds_read_b128 v[186:189], v137 offset:3072
	ds_read_b128 v[190:193], v137 offset:4096
	ds_read_b128 v[202:205], v137 offset:5120
	ds_read_b128 v[214:217], v137 offset:6144
	ds_read_b128 v[224:227], v137 offset:7168
	global_load_lds_dwordx4 v[182:183], off
	v_lshl_add_u64 v[182:183], v[134:135], 0, s[8:9]
	s_add_i32 m0, s29, 0xe000
	s_nop 0
	global_load_lds_dwordx4 v[182:183], off
	s_waitcnt vmcnt(8)
	s_waitcnt lgkmcnt(0)
	s_barrier
	s_waitcnt lgkmcnt(0)
	v_mfma_f32_16x16x32_bf16 v[126:129], v[138:141], v[170:173], v[126:129]
	v_mfma_f32_16x16x32_bf16 v[122:125], v[146:149], v[170:173], v[122:125]
	v_mfma_f32_16x16x32_bf16 v[114:117], v[138:141], v[178:181], v[114:117]
	v_mfma_f32_16x16x32_bf16 v[106:109], v[146:149], v[178:181], v[106:109]
	v_mfma_f32_16x16x32_bf16 v[98:101], v[138:141], v[190:193], v[98:101]
	v_mfma_f32_16x16x32_bf16 v[90:93], v[146:149], v[190:193], v[90:93]
	v_mfma_f32_16x16x32_bf16 v[82:85], v[138:141], v[214:217], v[82:85]
	v_mfma_f32_16x16x32_bf16 v[74:77], v[146:149], v[214:217], v[74:77]
	v_mfma_f32_16x16x32_bf16 v[126:129], v[142:145], v[174:177], v[126:129]
	v_mfma_f32_16x16x32_bf16 v[122:125], v[150:153], v[174:177], v[122:125]
	v_mfma_f32_16x16x32_bf16 v[114:117], v[142:145], v[186:189], v[114:117]
	v_mfma_f32_16x16x32_bf16 v[106:109], v[150:153], v[186:189], v[106:109]
	v_mfma_f32_16x16x32_bf16 v[98:101], v[142:145], v[202:205], v[98:101]
	v_mfma_f32_16x16x32_bf16 v[90:93], v[150:153], v[202:205], v[90:93]
	v_mfma_f32_16x16x32_bf16 v[82:85], v[142:145], v[224:227], v[82:85]
	v_mfma_f32_16x16x32_bf16 v[74:77], v[150:153], v[224:227], v[74:77]
	v_mfma_f32_16x16x32_bf16 v[118:121], v[154:157], v[170:173], v[118:121]
	v_mfma_f32_16x16x32_bf16 v[110:113], v[162:165], v[170:173], v[110:113]
	v_mfma_f32_16x16x32_bf16 v[102:105], v[154:157], v[178:181], v[102:105]
	v_mfma_f32_16x16x32_bf16 v[94:97], v[162:165], v[178:181], v[94:97]
	v_mfma_f32_16x16x32_bf16 v[86:89], v[154:157], v[190:193], v[86:89]
	v_mfma_f32_16x16x32_bf16 v[78:81], v[162:165], v[190:193], v[78:81]
	v_mfma_f32_16x16x32_bf16 v[70:73], v[154:157], v[214:217], v[70:73]
	v_mfma_f32_16x16x32_bf16 v[66:69], v[162:165], v[214:217], v[66:69]
	v_mfma_f32_16x16x32_bf16 v[118:121], v[158:161], v[174:177], v[118:121]
	v_mfma_f32_16x16x32_bf16 v[110:113], v[166:169], v[174:177], v[110:113]
	v_mfma_f32_16x16x32_bf16 v[102:105], v[158:161], v[186:189], v[102:105]
	v_mfma_f32_16x16x32_bf16 v[94:97], v[166:169], v[186:189], v[94:97]
	v_mfma_f32_16x16x32_bf16 v[86:89], v[158:161], v[202:205], v[86:89]
	v_mfma_f32_16x16x32_bf16 v[78:81], v[166:169], v[202:205], v[78:81]
	v_mfma_f32_16x16x32_bf16 v[70:73], v[158:161], v[224:227], v[70:73]
	v_mfma_f32_16x16x32_bf16 v[66:69], v[166:169], v[224:227], v[66:69]
	s_barrier
	s_add_i32 s46, s48, s28
	v_lshl_add_u64 v[182:183], s[20:21], 0, v[0:1]
	s_mov_b32 m0, s46
	ds_read_b128 v[170:173], v137 offset:16384
	ds_read_b128 v[174:177], v137 offset:17408
	ds_read_b128 v[178:181], v137 offset:18432
	ds_read_b128 v[186:189], v137 offset:19456
	ds_read_b128 v[190:193], v137 offset:20480
	ds_read_b128 v[202:205], v137 offset:21504
	ds_read_b128 v[214:217], v137 offset:22528
	ds_read_b128 v[224:227], v137 offset:23552
	global_load_lds_dwordx4 v[182:183], off
	s_add_i32 m0, s46, 0x2000
	s_add_u32 s46, s20, 0x40000
	v_lshl_add_u64 v[194:195], s[20:21], 0, v[130:131]
	s_addc_u32 s47, s21, 0
	s_add_i32 s48, s49, s28
	global_load_lds_dwordx4 v[194:195], off
	v_lshl_add_u64 v[196:197], s[46:47], 0, v[0:1]
	s_mov_b32 m0, s48
	v_lshl_add_u64 v[198:199], s[22:23], 0, v[130:131]
	global_load_lds_dwordx4 v[196:197], off
	v_lshl_add_u64 v[196:197], s[46:47], 0, v[130:131]
	s_add_i32 m0, s48, 0x2000
	s_nop 0
	global_load_lds_dwordx4 v[196:197], off
	v_lshl_add_u64 v[196:197], s[22:23], 0, v[0:1]
	s_mov_b32 m0, s29
	s_nop 0
	global_load_lds_dwordx4 v[196:197], off
	s_mov_b32 m0, s30
	s_nop 0
	global_load_lds_dwordx4 v[198:199], off
	s_waitcnt vmcnt(8)
	s_waitcnt lgkmcnt(0)
	s_barrier
	s_waitcnt lgkmcnt(0)
	v_mfma_f32_16x16x32_bf16 v[62:65], v[138:141], v[170:173], v[62:65]
	v_mfma_f32_16x16x32_bf16 v[58:61], v[146:149], v[170:173], v[58:61]
	v_mfma_f32_16x16x32_bf16 v[50:53], v[138:141], v[178:181], v[50:53]
	v_mfma_f32_16x16x32_bf16 v[42:45], v[146:149], v[178:181], v[42:45]
	v_mfma_f32_16x16x32_bf16 v[34:37], v[138:141], v[190:193], v[34:37]
	v_mfma_f32_16x16x32_bf16 v[26:29], v[146:149], v[190:193], v[26:29]
	v_mfma_f32_16x16x32_bf16 v[18:21], v[138:141], v[214:217], v[18:21]
	v_mfma_f32_16x16x32_bf16 v[10:13], v[146:149], v[214:217], v[10:13]
	v_mfma_f32_16x16x32_bf16 v[62:65], v[142:145], v[174:177], v[62:65]
	v_mfma_f32_16x16x32_bf16 v[58:61], v[150:153], v[174:177], v[58:61]
	v_mfma_f32_16x16x32_bf16 v[50:53], v[142:145], v[186:189], v[50:53]
	v_mfma_f32_16x16x32_bf16 v[42:45], v[150:153], v[186:189], v[42:45]
	v_mfma_f32_16x16x32_bf16 v[34:37], v[142:145], v[202:205], v[34:37]
	v_mfma_f32_16x16x32_bf16 v[26:29], v[150:153], v[202:205], v[26:29]
	v_mfma_f32_16x16x32_bf16 v[18:21], v[142:145], v[224:227], v[18:21]
	v_mfma_f32_16x16x32_bf16 v[10:13], v[150:153], v[224:227], v[10:13]
	v_mfma_f32_16x16x32_bf16 v[54:57], v[154:157], v[170:173], v[54:57]
	v_mfma_f32_16x16x32_bf16 v[46:49], v[162:165], v[170:173], v[46:49]
	v_mfma_f32_16x16x32_bf16 v[38:41], v[154:157], v[178:181], v[38:41]
	v_mfma_f32_16x16x32_bf16 v[30:33], v[162:165], v[178:181], v[30:33]
	v_mfma_f32_16x16x32_bf16 v[22:25], v[154:157], v[190:193], v[22:25]
	v_mfma_f32_16x16x32_bf16 v[14:17], v[162:165], v[190:193], v[14:17]
	v_mfma_f32_16x16x32_bf16 v[6:9], v[154:157], v[214:217], v[6:9]
	v_mfma_f32_16x16x32_bf16 v[2:5], v[162:165], v[214:217], v[2:5]
	v_mfma_f32_16x16x32_bf16 v[54:57], v[158:161], v[174:177], v[54:57]
	v_mfma_f32_16x16x32_bf16 v[46:49], v[166:169], v[174:177], v[46:49]
	v_mfma_f32_16x16x32_bf16 v[38:41], v[158:161], v[186:189], v[38:41]
	v_mfma_f32_16x16x32_bf16 v[30:33], v[166:169], v[186:189], v[30:33]
	v_mfma_f32_16x16x32_bf16 v[22:25], v[158:161], v[202:205], v[22:25]
	v_mfma_f32_16x16x32_bf16 v[14:17], v[166:169], v[202:205], v[14:17]
	v_mfma_f32_16x16x32_bf16 v[6:9], v[158:161], v[224:227], v[6:9]
	v_mfma_f32_16x16x32_bf16 v[2:5], v[166:169], v[224:227], v[2:5]
	s_barrier
	s_add_i32 s46, 0, 0x18000
	s_add_i32 s47, 0, 0x1c000
	v_add_u32_e32 v150, s46, v136
	v_add_u32_e32 v166, s47, v136
	ds_read_b128 v[138:141], v150
	ds_read_b128 v[142:145], v150 offset:1024
	ds_read_b128 v[146:149], v150 offset:2048
	ds_read_b128 v[150:153], v150 offset:3072
	ds_read_b128 v[154:157], v166
	ds_read_b128 v[158:161], v166 offset:1024
	ds_read_b128 v[162:165], v166 offset:2048
	ds_read_b128 v[166:169], v166 offset:3072
	s_add_u32 s22, s22, 0x40000
	s_addc_u32 s23, s23, 0
	s_mov_b32 m0, s31
	v_lshl_add_u64 v[200:201], s[22:23], 0, v[0:1]
	ds_read_b128 v[170:173], v137 offset:32768
	ds_read_b128 v[174:177], v137 offset:33792
	ds_read_b128 v[178:181], v137 offset:34816
	ds_read_b128 v[186:189], v137 offset:35840
	ds_read_b128 v[190:193], v137 offset:36864
	ds_read_b128 v[202:205], v137 offset:37888
	ds_read_b128 v[214:217], v137 offset:38912
	ds_read_b128 v[224:227], v137 offset:39936
	global_load_lds_dwordx4 v[200:201], off
	v_lshl_add_u64 v[200:201], s[22:23], 0, v[130:131]
	s_mov_b32 m0, s37
	s_nop 0
	global_load_lds_dwordx4 v[200:201], off
	s_waitcnt vmcnt(8)
	s_waitcnt lgkmcnt(0)
	s_barrier
	s_waitcnt lgkmcnt(0)
	v_mfma_f32_16x16x32_bf16 v[126:129], v[138:141], v[170:173], v[126:129]
	v_mfma_f32_16x16x32_bf16 v[122:125], v[146:149], v[170:173], v[122:125]
	v_mfma_f32_16x16x32_bf16 v[114:117], v[138:141], v[178:181], v[114:117]
	v_mfma_f32_16x16x32_bf16 v[106:109], v[146:149], v[178:181], v[106:109]
	v_mfma_f32_16x16x32_bf16 v[98:101], v[138:141], v[190:193], v[98:101]
	v_mfma_f32_16x16x32_bf16 v[90:93], v[146:149], v[190:193], v[90:93]
	v_mfma_f32_16x16x32_bf16 v[82:85], v[138:141], v[214:217], v[82:85]
	v_mfma_f32_16x16x32_bf16 v[74:77], v[146:149], v[214:217], v[74:77]
	v_mfma_f32_16x16x32_bf16 v[126:129], v[142:145], v[174:177], v[126:129]
	v_mfma_f32_16x16x32_bf16 v[122:125], v[150:153], v[174:177], v[122:125]
	v_mfma_f32_16x16x32_bf16 v[114:117], v[142:145], v[186:189], v[114:117]
	v_mfma_f32_16x16x32_bf16 v[106:109], v[150:153], v[186:189], v[106:109]
	v_mfma_f32_16x16x32_bf16 v[98:101], v[142:145], v[202:205], v[98:101]
	v_mfma_f32_16x16x32_bf16 v[90:93], v[150:153], v[202:205], v[90:93]
	v_mfma_f32_16x16x32_bf16 v[82:85], v[142:145], v[224:227], v[82:85]
	v_mfma_f32_16x16x32_bf16 v[74:77], v[150:153], v[224:227], v[74:77]
	v_mfma_f32_16x16x32_bf16 v[118:121], v[154:157], v[170:173], v[118:121]
	v_mfma_f32_16x16x32_bf16 v[110:113], v[162:165], v[170:173], v[110:113]
	v_mfma_f32_16x16x32_bf16 v[102:105], v[154:157], v[178:181], v[102:105]
	v_mfma_f32_16x16x32_bf16 v[94:97], v[162:165], v[178:181], v[94:97]
	v_mfma_f32_16x16x32_bf16 v[86:89], v[154:157], v[190:193], v[86:89]
	v_mfma_f32_16x16x32_bf16 v[78:81], v[162:165], v[190:193], v[78:81]
	v_mfma_f32_16x16x32_bf16 v[70:73], v[154:157], v[214:217], v[70:73]
	v_mfma_f32_16x16x32_bf16 v[66:69], v[162:165], v[214:217], v[66:69]
	v_mfma_f32_16x16x32_bf16 v[118:121], v[158:161], v[174:177], v[118:121]
	v_mfma_f32_16x16x32_bf16 v[110:113], v[166:169], v[174:177], v[110:113]
	v_mfma_f32_16x16x32_bf16 v[102:105], v[158:161], v[186:189], v[102:105]
	v_mfma_f32_16x16x32_bf16 v[94:97], v[166:169], v[186:189], v[94:97]
	v_mfma_f32_16x16x32_bf16 v[86:89], v[158:161], v[202:205], v[86:89]
	v_mfma_f32_16x16x32_bf16 v[78:81], v[166:169], v[202:205], v[78:81]
	v_mfma_f32_16x16x32_bf16 v[70:73], v[158:161], v[224:227], v[70:73]
	v_mfma_f32_16x16x32_bf16 v[66:69], v[166:169], v[224:227], v[66:69]
	s_barrier
	s_add_i32 s22, s46, s28
	v_lshl_add_u64 v[182:183], v[182:183], 0, s[94:95]
	s_mov_b32 m0, s22
	ds_read_b128 v[170:173], v137 offset:49152
	ds_read_b128 v[174:177], v137 offset:50176
	ds_read_b128 v[178:181], v137 offset:51200
	ds_read_b128 v[186:189], v137 offset:52224
	ds_read_b128 v[190:193], v137 offset:53248
	ds_read_b128 v[202:205], v137 offset:54272
	ds_read_b128 v[214:217], v137 offset:55296
	ds_read_b128 v[224:227], v137 offset:56320
	global_load_lds_dwordx4 v[182:183], off
	s_add_i32 m0, s22, 0x2000
	s_add_u32 s20, s20, 0x40080
	v_lshl_add_u64 v[182:183], v[194:195], 0, s[94:95]
	s_addc_u32 s21, s21, 0
	s_add_i32 s22, s47, s28
	global_load_lds_dwordx4 v[182:183], off
	v_lshl_add_u64 v[182:183], s[20:21], 0, v[0:1]
	s_mov_b32 m0, s22
	s_nop 0
	global_load_lds_dwordx4 v[182:183], off
	v_lshl_add_u64 v[182:183], s[20:21], 0, v[130:131]
	s_add_i32 m0, s22, 0x2000
	s_nop 0
	global_load_lds_dwordx4 v[182:183], off
	v_lshl_add_u64 v[182:183], v[196:197], 0, s[94:95]
	s_mov_b32 m0, s39
	s_nop 0
	global_load_lds_dwordx4 v[182:183], off
	v_lshl_add_u64 v[182:183], v[198:199], 0, s[94:95]
	s_mov_b32 m0, s40
	s_nop 0
	global_load_lds_dwordx4 v[182:183], off
	s_waitcnt vmcnt(8)
	s_waitcnt lgkmcnt(0)
	s_barrier
	s_waitcnt lgkmcnt(0)
	v_mfma_f32_16x16x32_bf16 v[62:65], v[138:141], v[170:173], v[62:65]
	v_mfma_f32_16x16x32_bf16 v[58:61], v[146:149], v[170:173], v[58:61]
	v_mfma_f32_16x16x32_bf16 v[50:53], v[138:141], v[178:181], v[50:53]
	v_mfma_f32_16x16x32_bf16 v[42:45], v[146:149], v[178:181], v[42:45]
	v_mfma_f32_16x16x32_bf16 v[34:37], v[138:141], v[190:193], v[34:37]
	v_mfma_f32_16x16x32_bf16 v[26:29], v[146:149], v[190:193], v[26:29]
	v_mfma_f32_16x16x32_bf16 v[18:21], v[138:141], v[214:217], v[18:21]
	v_mfma_f32_16x16x32_bf16 v[10:13], v[146:149], v[214:217], v[10:13]
	v_mfma_f32_16x16x32_bf16 v[62:65], v[142:145], v[174:177], v[62:65]
	v_mfma_f32_16x16x32_bf16 v[58:61], v[150:153], v[174:177], v[58:61]
	v_mfma_f32_16x16x32_bf16 v[50:53], v[142:145], v[186:189], v[50:53]
	v_mfma_f32_16x16x32_bf16 v[42:45], v[150:153], v[186:189], v[42:45]
	v_mfma_f32_16x16x32_bf16 v[34:37], v[142:145], v[202:205], v[34:37]
	v_mfma_f32_16x16x32_bf16 v[26:29], v[150:153], v[202:205], v[26:29]
	v_mfma_f32_16x16x32_bf16 v[18:21], v[142:145], v[224:227], v[18:21]
	v_mfma_f32_16x16x32_bf16 v[10:13], v[150:153], v[224:227], v[10:13]
	v_mfma_f32_16x16x32_bf16 v[54:57], v[154:157], v[170:173], v[54:57]
	v_mfma_f32_16x16x32_bf16 v[46:49], v[162:165], v[170:173], v[46:49]
	v_mfma_f32_16x16x32_bf16 v[38:41], v[154:157], v[178:181], v[38:41]
	v_mfma_f32_16x16x32_bf16 v[30:33], v[162:165], v[178:181], v[30:33]
	v_mfma_f32_16x16x32_bf16 v[22:25], v[154:157], v[190:193], v[22:25]
	v_mfma_f32_16x16x32_bf16 v[14:17], v[162:165], v[190:193], v[14:17]
	v_mfma_f32_16x16x32_bf16 v[6:9], v[154:157], v[214:217], v[6:9]
	v_mfma_f32_16x16x32_bf16 v[2:5], v[162:165], v[214:217], v[2:5]
	v_mfma_f32_16x16x32_bf16 v[54:57], v[158:161], v[174:177], v[54:57]
	v_mfma_f32_16x16x32_bf16 v[46:49], v[166:169], v[174:177], v[46:49]
	v_mfma_f32_16x16x32_bf16 v[38:41], v[158:161], v[186:189], v[38:41]
	v_mfma_f32_16x16x32_bf16 v[30:33], v[166:169], v[186:189], v[30:33]
	v_mfma_f32_16x16x32_bf16 v[22:25], v[158:161], v[202:205], v[22:25]
	v_mfma_f32_16x16x32_bf16 v[14:17], v[166:169], v[202:205], v[14:17]
	v_mfma_f32_16x16x32_bf16 v[6:9], v[158:161], v[224:227], v[6:9]
	v_mfma_f32_16x16x32_bf16 v[2:5], v[166:169], v[224:227], v[2:5]
	s_barrier
	s_add_i32 s45, s45, 2
	s_add_u32 s8, s8, 0x100
	s_addc_u32 s9, s9, 0
	s_cmp_gt_u32 s45, 13
	s_cbranch_scc0 .LBB0_1202
	s_cmpk_lt_u32 s27, 0x100
	s_cbranch_scc0 .LBB0_1205
	s_barrier

.LBB0_1213:
	s_add_i32 s23, 0, 0x18000
	s_and_b32 s13, s7, 3
	s_add_i32 s28, s23, s6
	s_lshl_b32 s7, s27, 13
	s_lshl_b32 s22, s13, 12
	v_lshl_add_u64 v[22:23], v[2:3], 0, s[94:95]
	s_mov_b32 m0, s28
	s_add_i32 s30, s28, 0x2000
	s_add_i32 s29, s3, 0x8000
	s_add_i32 s31, s3, 0xa000
	s_waitcnt vmcnt(2)
	s_barrier
	global_load_lds_dwordx4 v[22:23], off
	v_lshl_add_u64 v[24:25], v[6:7], 0, s[94:95]
	s_mov_b32 m0, s30
	s_add_u32 s20, s4, 0x10080
	global_load_lds_dwordx4 v[24:25], off
	v_lshl_add_u64 v[20:21], v[18:19], 0, s[94:95]
	s_mov_b32 m0, s29
	s_addc_u32 s21, s5, 0
	s_add_i32 s39, 0, 0x1c000
	global_load_lds_dwordx4 v[20:21], off
	v_lshl_add_u64 v[26:27], v[28:29], 0, s[94:95]
	s_mov_b32 m0, s31
	s_add_i32 s36, s39, s6
	global_load_lds_dwordx4 v[26:27], off
	v_lshl_add_u64 v[30:31], s[20:21], 0, v[0:1]
	s_mov_b32 m0, s36
	s_add_i32 s37, s36, 0x2000
	global_load_lds_dwordx4 v[30:31], off
	v_lshl_add_u64 v[32:33], s[20:21], 0, v[34:35]
	s_mov_b32 m0, s37
	v_and_b32_e32 v8, 48, v36
	global_load_lds_dwordx4 v[32:33], off
	v_lshlrev_b32_e32 v9, 6, v36
	s_movk_i32 s20, 0x3c0
	v_and_or_b32 v8, v9, s20, v8
	v_lshlrev_b32_e32 v9, 2, v36
	v_and_b32_e32 v9, 32, v9
	v_bitop3_b32 v10, v8, s7, v9 bitop3:0xde
	v_bitop3_b32 v8, v8, s22, v9 bitop3:0xde
	s_add_i32 s40, 0, 0x10000
	s_add_i32 s42, 0, 0x14000
	v_add_u32_e32 v11, s40, v8
	s_add_u32 s46, s8, 0x40080
	s_waitcnt vmcnt(6)
	s_barrier
	v_add_u32_e32 v184, s42, v8
	s_addc_u32 s47, s9, 0
	s_add_i32 s40, s40, s6
	ds_read_b128 v[36:39], v11
	ds_read_b128 v[40:43], v11 offset:1024
	ds_read_b128 v[44:47], v11 offset:2048
	ds_read_b128 v[48:51], v11 offset:3072
	ds_read_b128 v[52:55], v184
	ds_read_b128 v[56:59], v184 offset:1024
	ds_read_b128 v[60:63], v184 offset:2048
	ds_read_b128 v[64:67], v184 offset:3072
	v_add_u32_e32 v218, s39, v8
	s_add_i32 s45, s3, 0xc000
	s_add_i32 s44, s3, 0xe000
	s_add_i32 s39, s40, 0x2000
	s_add_u32 s22, s4, 0x10100
	v_add_u32_e32 v212, s23, v8
	s_addc_u32 s23, s5, 0
	s_add_i32 s42, s42, s6
	s_add_i32 s41, s42, 0x2000
	s_add_u32 s20, s8, 0x40100
	s_addc_u32 s21, s9, 0
	s_add_u32 s6, s4, 0x10180
	s_addc_u32 s7, s5, 0
	s_add_u32 s4, s8, 0x40180
	s_addc_u32 s5, s9, 0
	v_add_u32_e32 v208, 0, v10
	s_cmpk_gt_u32 s43, 0xff
	s_mov_b32 m0, s45
	v_lshl_add_u64 v[8:9], s[46:47], 0, v[4:5]
	ds_read_b128 v[68:71], v208
	ds_read_b128 v[72:75], v208 offset:1024
	ds_read_b128 v[76:79], v208 offset:2048
	ds_read_b128 v[80:83], v208 offset:3072
	ds_read_b128 v[84:87], v208 offset:4096
	ds_read_b128 v[88:91], v208 offset:5120
	ds_read_b128 v[92:95], v208 offset:6144
	ds_read_b128 v[96:99], v208 offset:7168
	global_load_lds_dwordx4 v[8:9], off
	v_lshl_add_u64 v[8:9], s[46:47], 0, v[16:17]
	s_mov_b32 m0, s44
	s_nop 0
	global_load_lds_dwordx4 v[8:9], off
	s_waitcnt vmcnt(8)
	s_waitcnt lgkmcnt(0)
	s_barrier
	s_waitcnt lgkmcnt(0)
	v_mfma_f32_16x16x32_bf16 v[100:103], v[36:39], v[68:71], 0
	v_mfma_f32_16x16x32_bf16 v[104:107], v[44:47], v[68:71], 0
	v_mfma_f32_16x16x32_bf16 v[108:111], v[36:39], v[76:79], 0
	s_waitcnt vmcnt(0)
	v_mfma_f32_16x16x32_bf16 v[112:115], v[44:47], v[76:79], 0
	v_mfma_f32_16x16x32_bf16 v[116:119], v[36:39], v[84:87], 0
	v_mfma_f32_16x16x32_bf16 v[120:123], v[44:47], v[84:87], 0
	v_mfma_f32_16x16x32_bf16 v[124:127], v[36:39], v[92:95], 0
	v_mfma_f32_16x16x32_bf16 v[128:131], v[44:47], v[92:95], 0
	v_mfma_f32_16x16x32_bf16 v[100:103], v[40:43], v[72:75], v[100:103]
	v_mfma_f32_16x16x32_bf16 v[104:107], v[48:51], v[72:75], v[104:107]
	v_mfma_f32_16x16x32_bf16 v[108:111], v[40:43], v[80:83], v[108:111]
	v_mfma_f32_16x16x32_bf16 v[112:115], v[48:51], v[80:83], v[112:115]
	v_mfma_f32_16x16x32_bf16 v[116:119], v[40:43], v[88:91], v[116:119]
	v_mfma_f32_16x16x32_bf16 v[120:123], v[48:51], v[88:91], v[120:123]
	v_mfma_f32_16x16x32_bf16 v[124:127], v[40:43], v[96:99], v[124:127]
	v_mfma_f32_16x16x32_bf16 v[128:131], v[48:51], v[96:99], v[128:131]
	v_mfma_f32_16x16x32_bf16 v[132:135], v[52:55], v[68:71], 0
	v_mfma_f32_16x16x32_bf16 v[68:71], v[60:63], v[68:71], 0
	v_mfma_f32_16x16x32_bf16 v[132:135], v[56:59], v[72:75], v[132:135]
	v_mfma_f32_16x16x32_bf16 v[68:71], v[64:67], v[72:75], v[68:71]
	v_mfma_f32_16x16x32_bf16 v[72:75], v[52:55], v[76:79], 0
	v_mfma_f32_16x16x32_bf16 v[76:79], v[60:63], v[76:79], 0
	v_mfma_f32_16x16x32_bf16 v[72:75], v[56:59], v[80:83], v[72:75]
	v_mfma_f32_16x16x32_bf16 v[76:79], v[64:67], v[80:83], v[76:79]
	v_mfma_f32_16x16x32_bf16 v[80:83], v[52:55], v[84:87], 0
	v_mfma_f32_16x16x32_bf16 v[84:87], v[60:63], v[84:87], 0
	v_mfma_f32_16x16x32_bf16 v[80:83], v[56:59], v[88:91], v[80:83]
	v_mfma_f32_16x16x32_bf16 v[84:87], v[64:67], v[88:91], v[84:87]
	v_mfma_f32_16x16x32_bf16 v[88:91], v[52:55], v[92:95], 0
	v_mfma_f32_16x16x32_bf16 v[92:95], v[60:63], v[92:95], 0
	v_mfma_f32_16x16x32_bf16 v[88:91], v[56:59], v[96:99], v[88:91]
	v_mfma_f32_16x16x32_bf16 v[92:95], v[64:67], v[96:99], v[92:95]
	s_barrier
	s_mov_b64 s[8:9], 0x100
	s_mov_b32 m0, s40
	v_lshl_add_u64 v[8:9], v[2:3], 0, s[8:9]
	ds_read_b128 v[96:99], v208 offset:16384
	ds_read_b128 v[136:139], v208 offset:17408
	ds_read_b128 v[140:143], v208 offset:18432
	ds_read_b128 v[144:147], v208 offset:19456
	ds_read_b128 v[148:151], v208 offset:20480
	ds_read_b128 v[152:155], v208 offset:21504
	ds_read_b128 v[156:159], v208 offset:22528
	ds_read_b128 v[160:163], v208 offset:23552
	global_load_lds_dwordx4 v[8:9], off
	v_lshl_add_u64 v[8:9], v[6:7], 0, s[8:9]
	s_mov_b32 m0, s39
	s_nop 0
	global_load_lds_dwordx4 v[8:9], off
	v_lshl_add_u64 v[8:9], s[22:23], 0, v[0:1]
	s_mov_b32 m0, s42
	s_nop 0
	global_load_lds_dwordx4 v[8:9], off
	v_lshl_add_u64 v[8:9], s[22:23], 0, v[34:35]
	s_mov_b32 m0, s41
	s_nop 0
	global_load_lds_dwordx4 v[8:9], off
	v_lshl_add_u64 v[8:9], v[18:19], 0, s[8:9]
	s_mov_b32 m0, s3
	s_nop 0
	global_load_lds_dwordx4 v[8:9], off
	v_lshl_add_u64 v[8:9], v[28:29], 0, s[8:9]
	s_mov_b32 m0, s38
	s_nop 0
	global_load_lds_dwordx4 v[8:9], off
	s_waitcnt vmcnt(8)
	s_waitcnt lgkmcnt(0)
	s_barrier
	s_waitcnt lgkmcnt(0)
	v_mfma_f32_16x16x32_bf16 v[164:167], v[36:39], v[96:99], 0
	v_mfma_f32_16x16x32_bf16 v[172:175], v[36:39], v[140:143], 0
	v_mfma_f32_16x16x32_bf16 v[180:183], v[36:39], v[148:151], 0
	v_mfma_f32_16x16x32_bf16 v[36:39], v[36:39], v[156:159], 0
	v_mfma_f32_16x16x32_bf16 v[164:167], v[40:43], v[136:139], v[164:167]
	v_mfma_f32_16x16x32_bf16 v[172:175], v[40:43], v[144:147], v[172:175]
	v_mfma_f32_16x16x32_bf16 v[180:183], v[40:43], v[152:155], v[180:183]
	v_mfma_f32_16x16x32_bf16 v[36:39], v[40:43], v[160:163], v[36:39]
	v_mfma_f32_16x16x32_bf16 v[40:43], v[44:47], v[156:159], 0
	v_mfma_f32_16x16x32_bf16 v[168:171], v[44:47], v[96:99], 0
	v_mfma_f32_16x16x32_bf16 v[176:179], v[44:47], v[140:143], 0
	v_mfma_f32_16x16x32_bf16 v[186:189], v[44:47], v[148:151], 0
	v_mfma_f32_16x16x32_bf16 v[40:43], v[48:51], v[160:163], v[40:43]
	v_mfma_f32_16x16x32_bf16 v[168:171], v[48:51], v[136:139], v[168:171]
	v_mfma_f32_16x16x32_bf16 v[176:179], v[48:51], v[144:147], v[176:179]
	v_mfma_f32_16x16x32_bf16 v[186:189], v[48:51], v[152:155], v[186:189]
	v_mfma_f32_16x16x32_bf16 v[44:47], v[52:55], v[96:99], 0
	v_mfma_f32_16x16x32_bf16 v[48:51], v[60:63], v[96:99], 0
	v_mfma_f32_16x16x32_bf16 v[44:47], v[56:59], v[136:139], v[44:47]
	v_mfma_f32_16x16x32_bf16 v[48:51], v[64:67], v[136:139], v[48:51]
	v_mfma_f32_16x16x32_bf16 v[96:99], v[52:55], v[140:143], 0
	v_mfma_f32_16x16x32_bf16 v[136:139], v[60:63], v[140:143], 0
	v_mfma_f32_16x16x32_bf16 v[140:143], v[52:55], v[148:151], 0
	v_mfma_f32_16x16x32_bf16 v[52:55], v[52:55], v[156:159], 0
	v_mfma_f32_16x16x32_bf16 v[96:99], v[56:59], v[144:147], v[96:99]
	v_mfma_f32_16x16x32_bf16 v[140:143], v[56:59], v[152:155], v[140:143]
	v_mfma_f32_16x16x32_bf16 v[52:55], v[56:59], v[160:163], v[52:55]
	v_mfma_f32_16x16x32_bf16 v[56:59], v[60:63], v[156:159], 0
	v_mfma_f32_16x16x32_bf16 v[136:139], v[64:67], v[144:147], v[136:139]
	v_mfma_f32_16x16x32_bf16 v[144:147], v[60:63], v[148:151], 0
	v_mfma_f32_16x16x32_bf16 v[56:59], v[64:67], v[160:163], v[56:59]
	v_mfma_f32_16x16x32_bf16 v[144:147], v[64:67], v[152:155], v[144:147]
	s_barrier
	ds_read_b128 v[60:63], v212
	ds_read_b128 v[64:67], v212 offset:1024
	ds_read_b128 v[148:151], v212 offset:2048
	ds_read_b128 v[152:155], v212 offset:3072
	ds_read_b128 v[156:159], v218
	ds_read_b128 v[160:163], v218 offset:1024
	ds_read_b128 v[190:193], v218 offset:2048
	ds_read_b128 v[202:205], v218 offset:3072
	s_mov_b32 m0, s25
	v_lshl_add_u64 v[8:9], s[20:21], 0, v[4:5]
	ds_read_b128 v[214:217], v208 offset:32768
	ds_read_b128 v[224:227], v208 offset:33792
	ds_read_b128 v[228:231], v208 offset:34816
	ds_read_b128 v[232:235], v208 offset:35840
	ds_read_b128 v[236:239], v208 offset:36864
	ds_read_b128 v[240:243], v208 offset:37888
	ds_read_b128 v[244:247], v208 offset:38912
	ds_read_b128 v[248:251], v208 offset:39936
	global_load_lds_dwordx4 v[8:9], off
	v_lshl_add_u64 v[8:9], s[20:21], 0, v[16:17]
	s_mov_b32 m0, s26
	s_nop 0
	global_load_lds_dwordx4 v[8:9], off
	s_waitcnt vmcnt(8)
	s_waitcnt lgkmcnt(0)
	s_barrier
	s_waitcnt lgkmcnt(0)
	v_mfma_f32_16x16x32_bf16 v[100:103], v[60:63], v[214:217], v[100:103]
	v_mfma_f32_16x16x32_bf16 v[104:107], v[148:151], v[214:217], v[104:107]
	v_mfma_f32_16x16x32_bf16 v[108:111], v[60:63], v[228:231], v[108:111]
	v_mfma_f32_16x16x32_bf16 v[112:115], v[148:151], v[228:231], v[112:115]
	v_mfma_f32_16x16x32_bf16 v[116:119], v[60:63], v[236:239], v[116:119]
	v_mfma_f32_16x16x32_bf16 v[120:123], v[148:151], v[236:239], v[120:123]
	v_mfma_f32_16x16x32_bf16 v[124:127], v[60:63], v[244:247], v[124:127]
	v_mfma_f32_16x16x32_bf16 v[128:131], v[148:151], v[244:247], v[128:131]
	v_mfma_f32_16x16x32_bf16 v[100:103], v[64:67], v[224:227], v[100:103]
	v_mfma_f32_16x16x32_bf16 v[104:107], v[152:155], v[224:227], v[104:107]
	v_mfma_f32_16x16x32_bf16 v[108:111], v[64:67], v[232:235], v[108:111]
	v_mfma_f32_16x16x32_bf16 v[112:115], v[152:155], v[232:235], v[112:115]
	v_mfma_f32_16x16x32_bf16 v[116:119], v[64:67], v[240:243], v[116:119]
	v_mfma_f32_16x16x32_bf16 v[120:123], v[152:155], v[240:243], v[120:123]
	v_mfma_f32_16x16x32_bf16 v[124:127], v[64:67], v[248:251], v[124:127]
	v_mfma_f32_16x16x32_bf16 v[128:131], v[152:155], v[248:251], v[128:131]
	v_mfma_f32_16x16x32_bf16 v[68:71], v[190:193], v[214:217], v[68:71]
	v_mfma_f32_16x16x32_bf16 v[72:75], v[156:159], v[228:231], v[72:75]
	v_mfma_f32_16x16x32_bf16 v[80:83], v[156:159], v[236:239], v[80:83]
	v_mfma_f32_16x16x32_bf16 v[84:87], v[190:193], v[236:239], v[84:87]
	v_mfma_f32_16x16x32_bf16 v[88:91], v[156:159], v[244:247], v[88:91]
	v_mfma_f32_16x16x32_bf16 v[92:95], v[190:193], v[244:247], v[92:95]
	v_mfma_f32_16x16x32_bf16 v[132:135], v[156:159], v[214:217], v[132:135]
	v_mfma_f32_16x16x32_bf16 v[68:71], v[202:205], v[224:227], v[68:71]
	v_mfma_f32_16x16x32_bf16 v[72:75], v[160:163], v[232:235], v[72:75]
	v_mfma_f32_16x16x32_bf16 v[76:79], v[190:193], v[228:231], v[76:79]
	v_mfma_f32_16x16x32_bf16 v[80:83], v[160:163], v[240:243], v[80:83]
	v_mfma_f32_16x16x32_bf16 v[84:87], v[202:205], v[240:243], v[84:87]
	v_mfma_f32_16x16x32_bf16 v[88:91], v[160:163], v[248:251], v[88:91]
	v_mfma_f32_16x16x32_bf16 v[92:95], v[202:205], v[248:251], v[92:95]
	v_mfma_f32_16x16x32_bf16 v[132:135], v[160:163], v[224:227], v[132:135]
	v_mfma_f32_16x16x32_bf16 v[76:79], v[202:205], v[232:235], v[76:79]
	s_barrier
	s_mov_b64 s[8:9], 0x180
	s_mov_b32 m0, s28
	v_lshl_add_u64 v[8:9], v[2:3], 0, s[8:9]
	ds_read_b128 v[214:217], v208 offset:49152
	ds_read_b128 v[224:227], v208 offset:50176
	ds_read_b128 v[228:231], v208 offset:51200
	ds_read_b128 v[232:235], v208 offset:52224
	ds_read_b128 v[236:239], v208 offset:53248
	ds_read_b128 v[240:243], v208 offset:54272
	ds_read_b128 v[244:247], v208 offset:55296
	ds_read_b128 v[248:251], v208 offset:56320
	global_load_lds_dwordx4 v[8:9], off
	v_lshl_add_u64 v[8:9], v[6:7], 0, s[8:9]
	s_mov_b32 m0, s30
	s_nop 0
	global_load_lds_dwordx4 v[8:9], off
	v_lshl_add_u64 v[8:9], s[6:7], 0, v[0:1]
	s_mov_b32 m0, s36
	s_nop 0
	global_load_lds_dwordx4 v[8:9], off
	v_lshl_add_u64 v[8:9], s[6:7], 0, v[34:35]
	s_mov_b32 m0, s37
	s_nop 0
	global_load_lds_dwordx4 v[8:9], off
	v_lshl_add_u64 v[8:9], v[18:19], 0, s[8:9]
	s_mov_b32 m0, s29
	s_nop 0
	global_load_lds_dwordx4 v[8:9], off
	v_lshl_add_u64 v[8:9], v[28:29], 0, s[8:9]
	s_mov_b32 m0, s31
	s_nop 0
	global_load_lds_dwordx4 v[8:9], off
	s_waitcnt vmcnt(8)
	s_waitcnt lgkmcnt(0)
	s_barrier
	s_waitcnt lgkmcnt(0)
	v_mfma_f32_16x16x32_bf16 v[34:37], v[60:63], v[244:247], v[36:39]
	v_mfma_f32_16x16x32_bf16 v[38:41], v[148:151], v[244:247], v[40:43]
	v_mfma_f32_16x16x32_bf16 v[164:167], v[60:63], v[214:217], v[164:167]
	v_mfma_f32_16x16x32_bf16 v[168:171], v[148:151], v[214:217], v[168:171]
	v_mfma_f32_16x16x32_bf16 v[172:175], v[60:63], v[228:231], v[172:175]
	v_mfma_f32_16x16x32_bf16 v[176:179], v[148:151], v[228:231], v[176:179]
	v_mfma_f32_16x16x32_bf16 v[180:183], v[60:63], v[236:239], v[180:183]
	v_mfma_f32_16x16x32_bf16 v[186:189], v[148:151], v[236:239], v[186:189]
	v_mfma_f32_16x16x32_bf16 v[34:37], v[64:67], v[248:251], v[34:37]
	v_mfma_f32_16x16x32_bf16 v[38:41], v[152:155], v[248:251], v[38:41]
	v_mfma_f32_16x16x32_bf16 v[164:167], v[64:67], v[224:227], v[164:167]
	v_mfma_f32_16x16x32_bf16 v[168:171], v[152:155], v[224:227], v[168:171]
	v_mfma_f32_16x16x32_bf16 v[172:175], v[64:67], v[232:235], v[172:175]
	v_mfma_f32_16x16x32_bf16 v[176:179], v[152:155], v[232:235], v[176:179]
	v_mfma_f32_16x16x32_bf16 v[180:183], v[64:67], v[240:243], v[180:183]
	v_mfma_f32_16x16x32_bf16 v[186:189], v[152:155], v[240:243], v[186:189]
	v_mfma_f32_16x16x32_bf16 v[42:45], v[156:159], v[214:217], v[44:47]
	v_mfma_f32_16x16x32_bf16 v[46:49], v[190:193], v[214:217], v[48:51]
	v_mfma_f32_16x16x32_bf16 v[60:63], v[156:159], v[228:231], v[96:99]
	v_mfma_f32_16x16x32_bf16 v[64:67], v[190:193], v[228:231], v[136:139]
	v_mfma_f32_16x16x32_bf16 v[96:99], v[156:159], v[236:239], v[140:143]
	v_mfma_f32_16x16x32_bf16 v[50:53], v[156:159], v[244:247], v[52:55]
	v_mfma_f32_16x16x32_bf16 v[54:57], v[190:193], v[244:247], v[56:59]
	v_mfma_f32_16x16x32_bf16 v[42:45], v[160:163], v[224:227], v[42:45]
	v_mfma_f32_16x16x32_bf16 v[46:49], v[202:205], v[224:227], v[46:49]
	v_mfma_f32_16x16x32_bf16 v[60:63], v[160:163], v[232:235], v[60:63]
	v_mfma_f32_16x16x32_bf16 v[64:67], v[202:205], v[232:235], v[64:67]
	v_mfma_f32_16x16x32_bf16 v[96:99], v[160:163], v[240:243], v[96:99]
	v_mfma_f32_16x16x32_bf16 v[136:139], v[190:193], v[236:239], v[144:147]
	v_mfma_f32_16x16x32_bf16 v[50:53], v[160:163], v[248:251], v[50:53]
	v_mfma_f32_16x16x32_bf16 v[54:57], v[202:205], v[248:251], v[54:57]
	v_mfma_f32_16x16x32_bf16 v[136:139], v[202:205], v[240:243], v[136:139]
	s_barrier
	ds_read_b128 v[140:143], v11
	ds_read_b128 v[144:147], v11 offset:1024
	ds_read_b128 v[148:151], v11 offset:2048
	ds_read_b128 v[152:155], v11 offset:3072
	ds_read_b128 v[156:159], v184
	ds_read_b128 v[160:163], v184 offset:1024
	ds_read_b128 v[190:193], v184 offset:2048
	ds_read_b128 v[202:205], v184 offset:3072
	s_mov_b32 m0, s45
	v_lshl_add_u64 v[4:5], s[4:5], 0, v[4:5]
	ds_read_b128 v[214:217], v208
	ds_read_b128 v[224:227], v208 offset:1024
	ds_read_b128 v[228:231], v208 offset:2048
	ds_read_b128 v[232:235], v208 offset:3072
	ds_read_b128 v[236:239], v208 offset:4096
	ds_read_b128 v[240:243], v208 offset:5120
	ds_read_b128 v[244:247], v208 offset:6144
	ds_read_b128 v[248:251], v208 offset:7168
	global_load_lds_dwordx4 v[4:5], off
	v_lshl_add_u64 v[4:5], s[4:5], 0, v[16:17]
	s_mov_b32 m0, s44
	s_nop 0
	global_load_lds_dwordx4 v[4:5], off
	s_waitcnt vmcnt(8)
	s_waitcnt lgkmcnt(0)
	s_barrier
	s_waitcnt lgkmcnt(0)
	v_mfma_f32_16x16x32_bf16 v[112:115], v[148:151], v[228:231], v[112:115]
	v_mfma_f32_16x16x32_bf16 v[194:197], v[152:155], v[232:235], v[112:115]
	v_mfma_f32_16x16x32_bf16 v[112:115], v[140:143], v[236:239], v[116:119]
	v_mfma_f32_16x16x32_bf16 v[118:121], v[148:151], v[236:239], v[120:123]
	v_mfma_f32_16x16x32_bf16 v[122:125], v[140:143], v[244:247], v[124:127]
	v_mfma_f32_16x16x32_bf16 v[100:103], v[140:143], v[214:217], v[100:103]
	v_mfma_f32_16x16x32_bf16 v[104:107], v[148:151], v[214:217], v[104:107]
	v_mfma_f32_16x16x32_bf16 v[108:111], v[140:143], v[228:231], v[108:111]
	v_mfma_f32_16x16x32_bf16 v[198:201], v[144:147], v[248:251], v[122:125]
	v_mfma_f32_16x16x32_bf16 v[122:125], v[148:151], v[244:247], v[128:131]
	v_mfma_f32_16x16x32_bf16 v[100:103], v[144:147], v[224:227], v[100:103]
	v_mfma_f32_16x16x32_bf16 v[104:107], v[152:155], v[224:227], v[104:107]
	v_mfma_f32_16x16x32_bf16 v[108:111], v[144:147], v[232:235], v[108:111]
	v_mfma_f32_16x16x32_bf16 v[114:117], v[144:147], v[240:243], v[112:115]
	v_mfma_f32_16x16x32_bf16 v[118:121], v[152:155], v[240:243], v[118:121]
	v_mfma_f32_16x16x32_bf16 v[8:11], v[152:155], v[248:251], v[122:125]
	v_mfma_f32_16x16x32_bf16 v[72:75], v[156:159], v[228:231], v[72:75]
	v_mfma_f32_16x16x32_bf16 v[122:125], v[156:159], v[214:217], v[132:135]
	v_mfma_f32_16x16x32_bf16 v[68:71], v[190:193], v[214:217], v[68:71]
	v_mfma_f32_16x16x32_bf16 v[214:217], v[160:163], v[232:235], v[72:75]
	v_mfma_f32_16x16x32_bf16 v[72:75], v[190:193], v[228:231], v[76:79]
	v_mfma_f32_16x16x32_bf16 v[130:133], v[160:163], v[224:227], v[122:125]
	v_mfma_f32_16x16x32_bf16 v[68:71], v[202:205], v[224:227], v[68:71]
	v_mfma_f32_16x16x32_bf16 v[224:227], v[202:205], v[232:235], v[72:75]
	v_mfma_f32_16x16x32_bf16 v[72:75], v[156:159], v[236:239], v[80:83]
	v_mfma_f32_16x16x32_bf16 v[228:231], v[160:163], v[240:243], v[72:75]
	v_mfma_f32_16x16x32_bf16 v[72:75], v[190:193], v[236:239], v[84:87]
	v_mfma_f32_16x16x32_bf16 v[82:85], v[202:205], v[240:243], v[72:75]
	v_mfma_f32_16x16x32_bf16 v[72:75], v[156:159], v[244:247], v[88:91]
	v_mfma_f32_16x16x32_bf16 v[232:235], v[160:163], v[248:251], v[72:75]
	v_mfma_f32_16x16x32_bf16 v[72:75], v[190:193], v[244:247], v[92:95]
	v_mfma_f32_16x16x32_bf16 v[236:239], v[202:205], v[248:251], v[72:75]
	s_barrier
	s_mov_b32 m0, s40
	s_nop 3
	ds_read_b128 v[72:75], v208 offset:16384
	ds_read_b128 v[76:79], v208 offset:17408
	ds_read_b128 v[86:89], v208 offset:18432
	ds_read_b128 v[90:93], v208 offset:19456
	ds_read_b128 v[122:125], v208 offset:20480
	ds_read_b128 v[126:129], v208 offset:21504
	ds_read_b128 v[240:243], v208 offset:22528
	ds_read_b128 v[244:247], v208 offset:23552
	global_load_lds_dwordx4 v[2:3], off
	s_mov_b32 m0, s39
	s_nop 0
	global_load_lds_dwordx4 v[6:7], off
	s_mov_b32 m0, s42
	s_nop 0
	global_load_lds_dwordx4 v[12:13], off
	s_mov_b32 m0, s41
	s_nop 0
	global_load_lds_dwordx4 v[14:15], off
	s_mov_b32 m0, s3
	s_nop 0
	global_load_lds_dwordx4 v[18:19], off
	s_mov_b32 m0, s38
	s_nop 0
	global_load_lds_dwordx4 v[28:29], off
	s_waitcnt vmcnt(8)
	s_waitcnt lgkmcnt(0)
	s_barrier
	s_waitcnt lgkmcnt(0)
	v_mfma_f32_16x16x32_bf16 v[2:5], v[140:143], v[72:75], v[164:167]
	v_mfma_f32_16x16x32_bf16 v[12:15], v[148:151], v[72:75], v[168:171]
	v_mfma_f32_16x16x32_bf16 v[16:19], v[140:143], v[86:89], v[172:175]
	v_mfma_f32_16x16x32_bf16 v[34:37], v[140:143], v[240:243], v[34:37]
	v_mfma_f32_16x16x32_bf16 v[38:41], v[148:151], v[240:243], v[38:41]
	v_mfma_f32_16x16x32_bf16 v[2:5], v[144:147], v[76:79], v[2:5]
	v_mfma_f32_16x16x32_bf16 v[12:15], v[152:155], v[76:79], v[12:15]
	v_mfma_f32_16x16x32_bf16 v[16:19], v[144:147], v[90:93], v[16:19]
	v_mfma_f32_16x16x32_bf16 v[164:167], v[148:151], v[86:89], v[176:179]
	v_mfma_f32_16x16x32_bf16 v[168:171], v[140:143], v[122:125], v[180:183]
	v_mfma_f32_16x16x32_bf16 v[172:175], v[148:151], v[122:125], v[186:189]
	v_mfma_f32_16x16x32_bf16 v[34:37], v[144:147], v[244:247], v[34:37]
	v_mfma_f32_16x16x32_bf16 v[38:41], v[152:155], v[244:247], v[38:41]
	v_mfma_f32_16x16x32_bf16 v[164:167], v[152:155], v[90:93], v[164:167]
	v_mfma_f32_16x16x32_bf16 v[168:171], v[144:147], v[126:129], v[168:171]
	v_mfma_f32_16x16x32_bf16 v[172:175], v[152:155], v[126:129], v[172:175]
	v_mfma_f32_16x16x32_bf16 v[42:45], v[156:159], v[72:75], v[42:45]
	v_mfma_f32_16x16x32_bf16 v[140:143], v[160:163], v[76:79], v[42:45]
	v_mfma_f32_16x16x32_bf16 v[42:45], v[190:193], v[72:75], v[46:49]
	v_mfma_f32_16x16x32_bf16 v[144:147], v[202:205], v[76:79], v[42:45]
	v_mfma_f32_16x16x32_bf16 v[42:45], v[156:159], v[86:89], v[60:63]
	v_mfma_f32_16x16x32_bf16 v[148:151], v[160:163], v[90:93], v[42:45]
	v_mfma_f32_16x16x32_bf16 v[42:45], v[190:193], v[86:89], v[64:67]
	v_mfma_f32_16x16x32_bf16 v[152:155], v[202:205], v[90:93], v[42:45]
	v_mfma_f32_16x16x32_bf16 v[42:45], v[156:159], v[122:125], v[96:99]
	v_mfma_f32_16x16x32_bf16 v[176:179], v[160:163], v[126:129], v[42:45]
	v_mfma_f32_16x16x32_bf16 v[42:45], v[190:193], v[122:125], v[136:139]
	v_mfma_f32_16x16x32_bf16 v[134:137], v[202:205], v[126:129], v[42:45]
	v_mfma_f32_16x16x32_bf16 v[42:45], v[156:159], v[240:243], v[50:53]
	v_mfma_f32_16x16x32_bf16 v[156:159], v[160:163], v[244:247], v[42:45]
	v_mfma_f32_16x16x32_bf16 v[42:45], v[190:193], v[240:243], v[54:57]
	v_mfma_f32_16x16x32_bf16 v[160:163], v[202:205], v[244:247], v[42:45]
	s_barrier
	ds_read_b128 v[50:53], v212
	ds_read_b128 v[54:57], v212 offset:1024
	ds_read_b128 v[180:183], v212 offset:2048
	ds_read_b128 v[186:189], v212 offset:3072
	ds_read_b128 v[190:193], v218
	ds_read_b128 v[202:205], v218 offset:1024
	ds_read_b128 v[240:243], v218 offset:2048
	ds_read_b128 v[244:247], v218 offset:3072
	s_mov_b32 m0, s25
	ds_read_b128 v[42:45], v208 offset:32768
	ds_read_b128 v[46:49], v208 offset:33792
	ds_read_b128 v[58:61], v208 offset:34816
	ds_read_b128 v[62:65], v208 offset:35840
	ds_read_b128 v[248:251], v208 offset:36864
	ds_read_b128 v[72:75], v208 offset:37888
	ds_read_b128 v[76:79], v208 offset:38912
	ds_read_b128 v[86:89], v208 offset:39936
	global_load_lds_dwordx4 v[206:207], off
	s_mov_b32 m0, s26
	s_nop 0
	global_load_lds_dwordx4 v[210:211], off
	s_waitcnt vmcnt(8)
	s_waitcnt lgkmcnt(0)
	s_barrier
	s_waitcnt lgkmcnt(0)
	v_mfma_f32_16x16x32_bf16 v[90:93], v[50:53], v[42:45], v[100:103]
	v_mfma_f32_16x16x32_bf16 v[126:129], v[54:57], v[46:49], v[90:93]
	v_mfma_f32_16x16x32_bf16 v[90:93], v[180:183], v[42:45], v[104:107]
	v_mfma_f32_16x16x32_bf16 v[122:125], v[186:189], v[46:49], v[90:93]
	v_mfma_f32_16x16x32_bf16 v[90:93], v[50:53], v[58:61], v[108:111]
	v_mfma_f32_16x16x32_bf16 v[110:113], v[54:57], v[62:65], v[90:93]
	v_mfma_f32_16x16x32_bf16 v[90:93], v[180:183], v[58:61], v[194:197]
	v_mfma_f32_16x16x32_bf16 v[106:109], v[186:189], v[62:65], v[90:93]
	v_mfma_f32_16x16x32_bf16 v[90:93], v[50:53], v[248:251], v[114:117]
	v_mfma_f32_16x16x32_bf16 v[94:97], v[54:57], v[72:75], v[90:93]
	v_mfma_f32_16x16x32_bf16 v[90:93], v[180:183], v[248:251], v[118:121]
	v_mfma_f32_16x16x32_bf16 v[98:101], v[50:53], v[76:79], v[198:201]
	v_mfma_f32_16x16x32_bf16 v[6:9], v[180:183], v[76:79], v[8:11]
	v_mfma_f32_16x16x32_bf16 v[90:93], v[186:189], v[72:75], v[90:93]
	v_mfma_f32_16x16x32_bf16 v[198:201], v[54:57], v[86:89], v[98:101]
	v_mfma_f32_16x16x32_bf16 v[194:197], v[186:189], v[86:89], v[6:9]
	v_mfma_f32_16x16x32_bf16 v[6:9], v[190:193], v[42:45], v[130:133]
	v_mfma_f32_16x16x32_bf16 v[118:121], v[202:205], v[46:49], v[6:9]
	v_mfma_f32_16x16x32_bf16 v[6:9], v[240:243], v[42:45], v[68:71]
	v_mfma_f32_16x16x32_bf16 v[114:117], v[244:247], v[46:49], v[6:9]
	v_mfma_f32_16x16x32_bf16 v[6:9], v[190:193], v[58:61], v[214:217]
	v_mfma_f32_16x16x32_bf16 v[102:105], v[202:205], v[62:65], v[6:9]
	v_mfma_f32_16x16x32_bf16 v[6:9], v[240:243], v[58:61], v[224:227]
	v_mfma_f32_16x16x32_bf16 v[98:101], v[244:247], v[62:65], v[6:9]
	v_mfma_f32_16x16x32_bf16 v[6:9], v[190:193], v[248:251], v[228:231]
	v_mfma_f32_16x16x32_bf16 v[214:217], v[202:205], v[72:75], v[6:9]
	v_mfma_f32_16x16x32_bf16 v[6:9], v[240:243], v[248:251], v[82:85]
	v_mfma_f32_16x16x32_bf16 v[82:85], v[244:247], v[72:75], v[6:9]
	v_mfma_f32_16x16x32_bf16 v[6:9], v[190:193], v[76:79], v[232:235]
	v_mfma_f32_16x16x32_bf16 v[70:73], v[202:205], v[86:89], v[6:9]
	v_mfma_f32_16x16x32_bf16 v[6:9], v[240:243], v[76:79], v[236:239]
	v_mfma_f32_16x16x32_bf16 v[66:69], v[244:247], v[86:89], v[6:9]
	s_barrier
	s_mov_b32 m0, s28
	s_nop 3
	ds_read_b128 v[6:9], v208 offset:49152
	ds_read_b128 v[74:77], v208 offset:50176
	ds_read_b128 v[78:81], v208 offset:51200
	ds_read_b128 v[86:89], v208 offset:52224
	ds_read_b128 v[130:133], v208 offset:53248
	ds_read_b128 v[224:227], v208 offset:54272
	ds_read_b128 v[228:231], v208 offset:55296
	ds_read_b128 v[232:235], v208 offset:56320
	global_load_lds_dwordx4 v[22:23], off
	s_mov_b32 m0, s30
	s_nop 0
	global_load_lds_dwordx4 v[24:25], off
	s_mov_b32 m0, s36
	s_nop 0
	global_load_lds_dwordx4 v[30:31], off
	s_mov_b32 m0, s37
	s_nop 0
	global_load_lds_dwordx4 v[32:33], off
	s_mov_b32 m0, s29
	s_nop 0
	global_load_lds_dwordx4 v[20:21], off
	s_mov_b32 m0, s31
	s_nop 0
	global_load_lds_dwordx4 v[26:27], off
	s_waitcnt vmcnt(8)
	s_waitcnt lgkmcnt(0)
	s_barrier
	s_waitcnt lgkmcnt(0)
	v_mfma_f32_16x16x32_bf16 v[2:5], v[50:53], v[6:9], v[2:5]
	v_mfma_f32_16x16x32_bf16 v[62:65], v[54:57], v[74:77], v[2:5]
	v_mfma_f32_16x16x32_bf16 v[2:5], v[180:183], v[6:9], v[12:15]
	v_mfma_f32_16x16x32_bf16 v[58:61], v[186:189], v[74:77], v[2:5]
	v_mfma_f32_16x16x32_bf16 v[2:5], v[50:53], v[78:81], v[16:19]
	v_mfma_f32_16x16x32_bf16 v[46:49], v[54:57], v[86:89], v[2:5]
	v_mfma_f32_16x16x32_bf16 v[2:5], v[180:183], v[78:81], v[164:167]
	v_mfma_f32_16x16x32_bf16 v[42:45], v[186:189], v[86:89], v[2:5]
	v_mfma_f32_16x16x32_bf16 v[2:5], v[50:53], v[130:133], v[168:171]
	v_mfma_f32_16x16x32_bf16 v[30:33], v[54:57], v[224:227], v[2:5]
	v_mfma_f32_16x16x32_bf16 v[2:5], v[180:183], v[130:133], v[172:175]
	v_mfma_f32_16x16x32_bf16 v[26:29], v[186:189], v[224:227], v[2:5]
	v_mfma_f32_16x16x32_bf16 v[2:5], v[50:53], v[228:231], v[34:37]
	v_mfma_f32_16x16x32_bf16 v[14:17], v[54:57], v[232:235], v[2:5]
	v_mfma_f32_16x16x32_bf16 v[2:5], v[180:183], v[228:231], v[38:41]
	v_mfma_f32_16x16x32_bf16 v[10:13], v[186:189], v[232:235], v[2:5]
	v_mfma_f32_16x16x32_bf16 v[2:5], v[190:193], v[6:9], v[140:143]
	v_mfma_f32_16x16x32_bf16 v[54:57], v[202:205], v[74:77], v[2:5]
	v_mfma_f32_16x16x32_bf16 v[2:5], v[240:243], v[6:9], v[144:147]
	v_mfma_f32_16x16x32_bf16 v[50:53], v[244:247], v[74:77], v[2:5]
	v_mfma_f32_16x16x32_bf16 v[2:5], v[190:193], v[78:81], v[148:151]
	v_mfma_f32_16x16x32_bf16 v[38:41], v[202:205], v[86:89], v[2:5]
	v_mfma_f32_16x16x32_bf16 v[2:5], v[240:243], v[78:81], v[152:155]
	v_mfma_f32_16x16x32_bf16 v[34:37], v[244:247], v[86:89], v[2:5]
	v_mfma_f32_16x16x32_bf16 v[2:5], v[190:193], v[130:133], v[176:179]
	v_mfma_f32_16x16x32_bf16 v[22:25], v[202:205], v[224:227], v[2:5]
	v_mfma_f32_16x16x32_bf16 v[2:5], v[240:243], v[130:133], v[134:137]
	v_mfma_f32_16x16x32_bf16 v[18:21], v[244:247], v[224:227], v[2:5]
	v_mfma_f32_16x16x32_bf16 v[2:5], v[190:193], v[228:231], v[156:159]
	v_mfma_f32_16x16x32_bf16 v[6:9], v[202:205], v[232:235], v[2:5]
	v_mfma_f32_16x16x32_bf16 v[2:5], v[240:243], v[228:231], v[160:163]
	v_mfma_f32_16x16x32_bf16 v[2:5], v[244:247], v[232:235], v[2:5]
	s_barrier
	s_cbranch_scc1 .LBB0_1215
	s_barrier

.Lp3r_j0:
	s_waitcnt lgkmcnt(0)
	s_barrier
	s_waitcnt lgkmcnt(0)
	v_mfma_f32_16x16x32_bf16 v[126:129], v[144:147], v[176:179], v[126:129]
	v_mfma_f32_16x16x32_bf16 v[118:121], v[152:155], v[176:179], v[118:121]
	v_mfma_f32_16x16x32_bf16 v[110:113], v[144:147], v[184:187], v[110:113]
	v_mfma_f32_16x16x32_bf16 v[102:105], v[152:155], v[184:187], v[102:105]
	v_mfma_f32_16x16x32_bf16 v[94:97], v[144:147], v[192:195], v[94:97]
	v_mfma_f32_16x16x32_bf16 v[86:89], v[152:155], v[192:195], v[86:89]
	v_mfma_f32_16x16x32_bf16 v[78:81], v[144:147], v[200:203], v[78:81]
	v_mfma_f32_16x16x32_bf16 v[70:73], v[152:155], v[200:203], v[70:73]
	v_mfma_f32_16x16x32_bf16 v[126:129], v[148:151], v[180:183], v[126:129]
	v_mfma_f32_16x16x32_bf16 v[118:121], v[156:159], v[180:183], v[118:121]
	v_mfma_f32_16x16x32_bf16 v[110:113], v[148:151], v[188:191], v[110:113]
	v_mfma_f32_16x16x32_bf16 v[102:105], v[156:159], v[188:191], v[102:105]
	v_mfma_f32_16x16x32_bf16 v[94:97], v[148:151], v[196:199], v[94:97]
	v_mfma_f32_16x16x32_bf16 v[86:89], v[156:159], v[196:199], v[86:89]
	v_mfma_f32_16x16x32_bf16 v[78:81], v[148:151], v[204:207], v[78:81]
	v_mfma_f32_16x16x32_bf16 v[70:73], v[156:159], v[204:207], v[70:73]
	v_mfma_f32_16x16x32_bf16 v[122:125], v[160:163], v[176:179], v[122:125]
	v_mfma_f32_16x16x32_bf16 v[114:117], v[168:171], v[176:179], v[114:117]
	v_mfma_f32_16x16x32_bf16 v[106:109], v[160:163], v[184:187], v[106:109]
	v_mfma_f32_16x16x32_bf16 v[98:101], v[168:171], v[184:187], v[98:101]
	v_mfma_f32_16x16x32_bf16 v[90:93], v[160:163], v[192:195], v[90:93]
	v_mfma_f32_16x16x32_bf16 v[82:85], v[168:171], v[192:195], v[82:85]
	v_mfma_f32_16x16x32_bf16 v[74:77], v[160:163], v[200:203], v[74:77]
	v_mfma_f32_16x16x32_bf16 v[66:69], v[168:171], v[200:203], v[66:69]
	v_mfma_f32_16x16x32_bf16 v[122:125], v[164:167], v[180:183], v[122:125]
	v_mfma_f32_16x16x32_bf16 v[114:117], v[172:175], v[180:183], v[114:117]
	v_mfma_f32_16x16x32_bf16 v[106:109], v[164:167], v[188:191], v[106:109]
	v_mfma_f32_16x16x32_bf16 v[98:101], v[172:175], v[188:191], v[98:101]
	v_mfma_f32_16x16x32_bf16 v[90:93], v[164:167], v[196:199], v[90:93]
	v_mfma_f32_16x16x32_bf16 v[82:85], v[172:175], v[196:199], v[82:85]
	v_mfma_f32_16x16x32_bf16 v[74:77], v[164:167], v[204:207], v[74:77]
	v_mfma_f32_16x16x32_bf16 v[66:69], v[172:175], v[204:207], v[66:69]
	s_barrier
	s_add_i32 s52, s52, s39
	v_lshl_add_u64 v[210:211], s[28:29], 0, v[0:1]
	s_mov_b32 m0, s52
	ds_read_b128 v[176:179], v143 offset:16384
	ds_read_b128 v[180:183], v143 offset:17408
	ds_read_b128 v[184:187], v143 offset:18432
	ds_read_b128 v[188:191], v143 offset:19456
	ds_read_b128 v[192:195], v143 offset:20480
	ds_read_b128 v[196:199], v143 offset:21504
	ds_read_b128 v[200:203], v143 offset:22528
	ds_read_b128 v[204:207], v143 offset:23552
	global_load_lds_dwordx4 v[210:211], off
	s_add_i32 m0, s52, 0x2000
	s_add_u32 s52, s28, 0x40000
	v_lshl_add_u64 v[214:215], s[28:29], 0, v[130:131]
	s_addc_u32 s53, s29, 0
	s_add_i32 s54, s54, s39
	global_load_lds_dwordx4 v[214:215], off
	v_lshl_add_u64 v[216:217], s[52:53], 0, v[0:1]
	s_mov_b32 m0, s54
	v_lshl_add_u64 v[224:225], s[30:31], 0, v[132:133]
	global_load_lds_dwordx4 v[216:217], off
	v_lshl_add_u64 v[216:217], s[52:53], 0, v[130:131]
	s_add_i32 m0, s54, 0x2000
	s_nop 0
	global_load_lds_dwordx4 v[216:217], off
	v_lshl_add_u64 v[216:217], s[30:31], 0, v[134:135]
	s_mov_b32 m0, s25
	s_nop 0
	global_load_lds_dwordx4 v[216:217], off
	s_mov_b32 m0, s40
	s_nop 0
	global_load_lds_dwordx4 v[224:225], off
	s_cmp_lg_u32 s51, 12
	s_cbranch_scc1 .Lp3r_nlA
	s_lshl_b32 s54, s22, 8
	s_add_i32 s54, s54, s43
	v_and_b32_e32 v228, 15, v212
	v_lshrrev_b32_e32 v229, 4, v212
	v_or_b32_e32 v228, s54, v228
	v_lshlrev_b32_e32 v228, 6, v228
	v_lshl_add_u32 v230, v229, 4, v228
	v_mov_b32_e32 v231, 0
	v_lshl_add_u64 v[250:251], s[4:5], 0, v[230:231]
	v_mov_b32_e32 v230, 0x2000
	v_lshl_add_u64 v[248:249], v[250:251], 0, v[230:231]
	global_load_dwordx4 v[228:231], v[250:251], off
	global_load_dwordx4 v[232:235], v[250:251], off offset:1024
	global_load_dwordx4 v[236:239], v[250:251], off offset:2048
	global_load_dwordx4 v[240:243], v[250:251], off offset:3072
	global_load_dwordx4 v[244:247], v[248:249], off
	s_nop 0
	global_load_dwordx4 v[248:251], v[248:249], off offset:1024
	s_waitcnt vmcnt(14)
	s_branch .Lp3r_jA

.Lp3r_jA:
	s_waitcnt lgkmcnt(0)
	s_barrier
	s_waitcnt lgkmcnt(0)
	v_mfma_f32_16x16x32_bf16 v[62:65], v[144:147], v[176:179], v[62:65]
	v_mfma_f32_16x16x32_bf16 v[54:57], v[152:155], v[176:179], v[54:57]
	v_mfma_f32_16x16x32_bf16 v[46:49], v[144:147], v[184:187], v[46:49]
	v_mfma_f32_16x16x32_bf16 v[38:41], v[152:155], v[184:187], v[38:41]
	v_mfma_f32_16x16x32_bf16 v[30:33], v[144:147], v[192:195], v[30:33]
	v_mfma_f32_16x16x32_bf16 v[22:25], v[152:155], v[192:195], v[22:25]
	v_mfma_f32_16x16x32_bf16 v[14:17], v[144:147], v[200:203], v[14:17]
	v_mfma_f32_16x16x32_bf16 v[6:9], v[152:155], v[200:203], v[6:9]
	v_mfma_f32_16x16x32_bf16 v[62:65], v[148:151], v[180:183], v[62:65]
	v_mfma_f32_16x16x32_bf16 v[54:57], v[156:159], v[180:183], v[54:57]
	v_mfma_f32_16x16x32_bf16 v[46:49], v[148:151], v[188:191], v[46:49]
	v_mfma_f32_16x16x32_bf16 v[38:41], v[156:159], v[188:191], v[38:41]
	v_mfma_f32_16x16x32_bf16 v[30:33], v[148:151], v[196:199], v[30:33]
	v_mfma_f32_16x16x32_bf16 v[22:25], v[156:159], v[196:199], v[22:25]
	v_mfma_f32_16x16x32_bf16 v[14:17], v[148:151], v[204:207], v[14:17]
	v_mfma_f32_16x16x32_bf16 v[6:9], v[156:159], v[204:207], v[6:9]
	v_mfma_f32_16x16x32_bf16 v[58:61], v[160:163], v[176:179], v[58:61]
	v_mfma_f32_16x16x32_bf16 v[50:53], v[168:171], v[176:179], v[50:53]
	v_mfma_f32_16x16x32_bf16 v[42:45], v[160:163], v[184:187], v[42:45]
	v_mfma_f32_16x16x32_bf16 v[34:37], v[168:171], v[184:187], v[34:37]
	v_mfma_f32_16x16x32_bf16 v[26:29], v[160:163], v[192:195], v[26:29]
	v_mfma_f32_16x16x32_bf16 v[18:21], v[168:171], v[192:195], v[18:21]
	v_mfma_f32_16x16x32_bf16 v[10:13], v[160:163], v[200:203], v[10:13]
	v_mfma_f32_16x16x32_bf16 v[2:5], v[168:171], v[200:203], v[2:5]
	v_mfma_f32_16x16x32_bf16 v[58:61], v[164:167], v[180:183], v[58:61]
	v_mfma_f32_16x16x32_bf16 v[50:53], v[172:175], v[180:183], v[50:53]
	v_mfma_f32_16x16x32_bf16 v[42:45], v[164:167], v[188:191], v[42:45]
	v_mfma_f32_16x16x32_bf16 v[34:37], v[172:175], v[188:191], v[34:37]
	v_mfma_f32_16x16x32_bf16 v[26:29], v[164:167], v[196:199], v[26:29]
	v_mfma_f32_16x16x32_bf16 v[18:21], v[172:175], v[196:199], v[18:21]
	v_mfma_f32_16x16x32_bf16 v[10:13], v[164:167], v[204:207], v[10:13]
	v_mfma_f32_16x16x32_bf16 v[2:5], v[172:175], v[204:207], v[2:5]
	s_barrier
	s_add_i32 s52, 0, 0x18000
	v_add_u32_e32 v140, s52, v141
	s_add_i32 s53, 0, 0x1c000
	ds_read_b128 v[144:147], v140
	ds_read_b128 v[148:151], v140 offset:1024
	ds_read_b128 v[152:155], v140 offset:2048
	ds_read_b128 v[156:159], v140 offset:3072
	v_add_u32_e32 v140, s53, v141
	ds_read_b128 v[160:163], v140
	ds_read_b128 v[164:167], v140 offset:1024
	ds_read_b128 v[168:171], v140 offset:2048
	ds_read_b128 v[172:175], v140 offset:3072
	s_add_u32 s30, s30, 0x40000
	s_addc_u32 s31, s31, 0
	s_mov_b32 m0, s41
	v_lshl_add_u64 v[226:227], s[30:31], 0, v[134:135]
	ds_read_b128 v[176:179], v143 offset:32768
	ds_read_b128 v[180:183], v143 offset:33792
	ds_read_b128 v[184:187], v143 offset:34816
	ds_read_b128 v[188:191], v143 offset:35840
	ds_read_b128 v[192:195], v143 offset:36864
	ds_read_b128 v[196:199], v143 offset:37888
	ds_read_b128 v[200:203], v143 offset:38912
	ds_read_b128 v[204:207], v143 offset:39936
	global_load_lds_dwordx4 v[226:227], off
	v_lshl_add_u64 v[226:227], s[30:31], 0, v[132:133]
	s_mov_b32 m0, s42
	s_nop 0
	global_load_lds_dwordx4 v[226:227], off
	s_cmp_lg_u32 s51, 12
	s_cbranch_scc1 .Lp3r_nlB
	s_waitcnt vmcnt(14)
	s_branch .Lp3r_jB

.Lp3r_jB:
	s_waitcnt lgkmcnt(0)
	s_barrier
	s_waitcnt lgkmcnt(0)
	v_mfma_f32_16x16x32_bf16 v[126:129], v[144:147], v[176:179], v[126:129]
	v_mfma_f32_16x16x32_bf16 v[118:121], v[152:155], v[176:179], v[118:121]
	v_mfma_f32_16x16x32_bf16 v[110:113], v[144:147], v[184:187], v[110:113]
	v_mfma_f32_16x16x32_bf16 v[102:105], v[152:155], v[184:187], v[102:105]
	v_mfma_f32_16x16x32_bf16 v[94:97], v[144:147], v[192:195], v[94:97]
	v_mfma_f32_16x16x32_bf16 v[86:89], v[152:155], v[192:195], v[86:89]
	v_mfma_f32_16x16x32_bf16 v[78:81], v[144:147], v[200:203], v[78:81]
	v_mfma_f32_16x16x32_bf16 v[70:73], v[152:155], v[200:203], v[70:73]
	v_mfma_f32_16x16x32_bf16 v[126:129], v[148:151], v[180:183], v[126:129]
	v_mfma_f32_16x16x32_bf16 v[118:121], v[156:159], v[180:183], v[118:121]
	v_mfma_f32_16x16x32_bf16 v[110:113], v[148:151], v[188:191], v[110:113]
	v_mfma_f32_16x16x32_bf16 v[102:105], v[156:159], v[188:191], v[102:105]
	v_mfma_f32_16x16x32_bf16 v[94:97], v[148:151], v[196:199], v[94:97]
	v_mfma_f32_16x16x32_bf16 v[86:89], v[156:159], v[196:199], v[86:89]
	v_mfma_f32_16x16x32_bf16 v[78:81], v[148:151], v[204:207], v[78:81]
	v_mfma_f32_16x16x32_bf16 v[70:73], v[156:159], v[204:207], v[70:73]
	v_mfma_f32_16x16x32_bf16 v[122:125], v[160:163], v[176:179], v[122:125]
	v_mfma_f32_16x16x32_bf16 v[114:117], v[168:171], v[176:179], v[114:117]
	v_mfma_f32_16x16x32_bf16 v[106:109], v[160:163], v[184:187], v[106:109]
	v_mfma_f32_16x16x32_bf16 v[98:101], v[168:171], v[184:187], v[98:101]
	v_mfma_f32_16x16x32_bf16 v[90:93], v[160:163], v[192:195], v[90:93]
	v_mfma_f32_16x16x32_bf16 v[82:85], v[168:171], v[192:195], v[82:85]
	v_mfma_f32_16x16x32_bf16 v[74:77], v[160:163], v[200:203], v[74:77]
	v_mfma_f32_16x16x32_bf16 v[66:69], v[168:171], v[200:203], v[66:69]
	v_mfma_f32_16x16x32_bf16 v[122:125], v[164:167], v[180:183], v[122:125]
	v_mfma_f32_16x16x32_bf16 v[114:117], v[172:175], v[180:183], v[114:117]
	v_mfma_f32_16x16x32_bf16 v[106:109], v[164:167], v[188:191], v[106:109]
	v_mfma_f32_16x16x32_bf16 v[98:101], v[172:175], v[188:191], v[98:101]
	v_mfma_f32_16x16x32_bf16 v[90:93], v[164:167], v[196:199], v[90:93]
	v_mfma_f32_16x16x32_bf16 v[82:85], v[172:175], v[196:199], v[82:85]
	v_mfma_f32_16x16x32_bf16 v[74:77], v[164:167], v[204:207], v[74:77]
	v_mfma_f32_16x16x32_bf16 v[66:69], v[172:175], v[204:207], v[66:69]
	s_barrier
	s_add_i32 s30, s52, s39
	v_lshl_add_u64 v[210:211], v[210:211], 0, s[94:95]
	s_mov_b32 m0, s30
	ds_read_b128 v[176:179], v143 offset:49152
	ds_read_b128 v[180:183], v143 offset:50176
	ds_read_b128 v[184:187], v143 offset:51200
	ds_read_b128 v[188:191], v143 offset:52224
	ds_read_b128 v[192:195], v143 offset:53248
	ds_read_b128 v[196:199], v143 offset:54272
	ds_read_b128 v[200:203], v143 offset:55296
	ds_read_b128 v[204:207], v143 offset:56320
	global_load_lds_dwordx4 v[210:211], off
	s_add_i32 m0, s30, 0x2000
	s_add_u32 s28, s28, 0x40080
	v_lshl_add_u64 v[210:211], v[214:215], 0, s[94:95]
	s_addc_u32 s29, s29, 0
	s_add_i32 s30, s53, s39
	global_load_lds_dwordx4 v[210:211], off
	v_lshl_add_u64 v[210:211], s[28:29], 0, v[0:1]
	s_mov_b32 m0, s30
	s_nop 0
	global_load_lds_dwordx4 v[210:211], off
	v_lshl_add_u64 v[210:211], s[28:29], 0, v[130:131]
	s_add_i32 m0, s30, 0x2000
	s_nop 0
	global_load_lds_dwordx4 v[210:211], off
	v_lshl_add_u64 v[210:211], v[216:217], 0, s[94:95]
	s_mov_b32 m0, s45
	s_nop 0
	global_load_lds_dwordx4 v[210:211], off
	v_lshl_add_u64 v[210:211], v[224:225], 0, s[94:95]
	s_mov_b32 m0, s46
	s_nop 0
	global_load_lds_dwordx4 v[210:211], off
	s_cmp_lg_u32 s51, 12
	s_cbranch_scc1 .Lp3r_nlC
	s_lshl_b32 s54, s22, 8
	s_add_i32 s54, s54, s43
	v_and_b32_e32 v214, 15, v212
	v_lshrrev_b32_e32 v215, 4, v212
	v_or_b32_e32 v214, s54, v214
	v_lshlrev_b32_e32 v214, 6, v214
	v_lshl_add_u32 v214, v215, 4, v214
	v_add_u32_e32 v214, 0x2800, v214
	v_mov_b32_e32 v215, 0
	v_lshl_add_u64 v[210:211], s[4:5], 0, v[214:215]
	global_load_dwordx4 v[214:217], v[210:211], off
	global_load_dwordx4 v[224:227], v[210:211], off offset:1024
	s_waitcnt vmcnt(16)
	s_branch .Lp3r_jC

.Lp3r_jC:
	s_waitcnt lgkmcnt(0)
	s_barrier
	s_waitcnt lgkmcnt(0)
	v_mfma_f32_16x16x32_bf16 v[62:65], v[144:147], v[176:179], v[62:65]
	v_mfma_f32_16x16x32_bf16 v[54:57], v[152:155], v[176:179], v[54:57]
	v_mfma_f32_16x16x32_bf16 v[46:49], v[144:147], v[184:187], v[46:49]
	v_mfma_f32_16x16x32_bf16 v[38:41], v[152:155], v[184:187], v[38:41]
	v_mfma_f32_16x16x32_bf16 v[30:33], v[144:147], v[192:195], v[30:33]
	v_mfma_f32_16x16x32_bf16 v[22:25], v[152:155], v[192:195], v[22:25]
	v_mfma_f32_16x16x32_bf16 v[14:17], v[144:147], v[200:203], v[14:17]
	v_mfma_f32_16x16x32_bf16 v[6:9], v[152:155], v[200:203], v[6:9]
	v_mfma_f32_16x16x32_bf16 v[62:65], v[148:151], v[180:183], v[62:65]
	v_mfma_f32_16x16x32_bf16 v[54:57], v[156:159], v[180:183], v[54:57]
	v_mfma_f32_16x16x32_bf16 v[46:49], v[148:151], v[188:191], v[46:49]
	v_mfma_f32_16x16x32_bf16 v[38:41], v[156:159], v[188:191], v[38:41]
	v_mfma_f32_16x16x32_bf16 v[30:33], v[148:151], v[196:199], v[30:33]
	v_mfma_f32_16x16x32_bf16 v[22:25], v[156:159], v[196:199], v[22:25]
	v_mfma_f32_16x16x32_bf16 v[14:17], v[148:151], v[204:207], v[14:17]
	v_mfma_f32_16x16x32_bf16 v[6:9], v[156:159], v[204:207], v[6:9]
	v_mfma_f32_16x16x32_bf16 v[58:61], v[160:163], v[176:179], v[58:61]
	v_mfma_f32_16x16x32_bf16 v[50:53], v[168:171], v[176:179], v[50:53]
	v_mfma_f32_16x16x32_bf16 v[42:45], v[160:163], v[184:187], v[42:45]
	v_mfma_f32_16x16x32_bf16 v[34:37], v[168:171], v[184:187], v[34:37]
	v_mfma_f32_16x16x32_bf16 v[26:29], v[160:163], v[192:195], v[26:29]
	v_mfma_f32_16x16x32_bf16 v[18:21], v[168:171], v[192:195], v[18:21]
	v_mfma_f32_16x16x32_bf16 v[10:13], v[160:163], v[200:203], v[10:13]
	v_mfma_f32_16x16x32_bf16 v[2:5], v[168:171], v[200:203], v[2:5]
	v_mfma_f32_16x16x32_bf16 v[58:61], v[164:167], v[180:183], v[58:61]
	v_mfma_f32_16x16x32_bf16 v[50:53], v[172:175], v[180:183], v[50:53]
	v_mfma_f32_16x16x32_bf16 v[42:45], v[164:167], v[188:191], v[42:45]
	v_mfma_f32_16x16x32_bf16 v[34:37], v[172:175], v[188:191], v[34:37]
	v_mfma_f32_16x16x32_bf16 v[26:29], v[164:167], v[196:199], v[26:29]
	v_mfma_f32_16x16x32_bf16 v[18:21], v[172:175], v[196:199], v[18:21]
	v_mfma_f32_16x16x32_bf16 v[10:13], v[164:167], v[204:207], v[10:13]
	v_mfma_f32_16x16x32_bf16 v[2:5], v[172:175], v[204:207], v[2:5]
	s_barrier
	s_add_i32 s51, s51, 2
	s_add_u32 s26, s26, 0x100
	s_addc_u32 s27, s27, 0
	s_add_u32 s49, s49, 0x100
	s_addc_u32 s50, s50, 0
	s_cmp_gt_u32 s51, 13
	s_cbranch_scc0 .LBB0_1238
	v_mov_b32_e32 v140, v212
	s_lshl_b32 s13, s24, 7
	v_and_b32_e32 v153, 15, v140
	v_ashrrev_i32_e32 v140, 4, v140
	s_or_b32 s13, s13, s44
	v_lshl_add_u32 v152, v140, 3, s13
	s_lshl_b32 s13, s22, 8
	s_movk_i32 s15, 0x2000
	s_and_b64 vcc, exec, s[8:9]
	s_cbranch_vccz .LBB0_1241
	s_barrier

.Lp4b_j0:
	s_waitcnt lgkmcnt(0)
	s_barrier
	s_waitcnt lgkmcnt(0)
	v_mfma_f32_16x16x32_bf16 v[126:129], v[136:139], v[170:173], v[126:129]
	v_mfma_f32_16x16x32_bf16 v[122:125], v[146:149], v[170:173], v[122:125]
	v_mfma_f32_16x16x32_bf16 v[114:117], v[136:139], v[178:181], v[114:117]
	v_mfma_f32_16x16x32_bf16 v[106:109], v[146:149], v[178:181], v[106:109]
	v_mfma_f32_16x16x32_bf16 v[98:101], v[136:139], v[186:189], v[98:101]
	v_mfma_f32_16x16x32_bf16 v[90:93], v[146:149], v[186:189], v[90:93]
	v_mfma_f32_16x16x32_bf16 v[82:85], v[136:139], v[194:197], v[82:85]
	v_mfma_f32_16x16x32_bf16 v[74:77], v[146:149], v[194:197], v[74:77]
	v_mfma_f32_16x16x32_bf16 v[126:129], v[140:143], v[174:177], v[126:129]
	v_mfma_f32_16x16x32_bf16 v[122:125], v[150:153], v[174:177], v[122:125]
	v_mfma_f32_16x16x32_bf16 v[114:117], v[140:143], v[182:185], v[114:117]
	v_mfma_f32_16x16x32_bf16 v[106:109], v[150:153], v[182:185], v[106:109]
	v_mfma_f32_16x16x32_bf16 v[98:101], v[140:143], v[190:193], v[98:101]
	v_mfma_f32_16x16x32_bf16 v[90:93], v[150:153], v[190:193], v[90:93]
	v_mfma_f32_16x16x32_bf16 v[82:85], v[140:143], v[198:201], v[82:85]
	v_mfma_f32_16x16x32_bf16 v[74:77], v[150:153], v[198:201], v[74:77]
	v_mfma_f32_16x16x32_bf16 v[118:121], v[154:157], v[170:173], v[118:121]
	v_mfma_f32_16x16x32_bf16 v[110:113], v[162:165], v[170:173], v[110:113]
	v_mfma_f32_16x16x32_bf16 v[102:105], v[154:157], v[178:181], v[102:105]
	v_mfma_f32_16x16x32_bf16 v[94:97], v[162:165], v[178:181], v[94:97]
	v_mfma_f32_16x16x32_bf16 v[86:89], v[154:157], v[186:189], v[86:89]
	v_mfma_f32_16x16x32_bf16 v[78:81], v[162:165], v[186:189], v[78:81]
	v_mfma_f32_16x16x32_bf16 v[70:73], v[154:157], v[194:197], v[70:73]
	v_mfma_f32_16x16x32_bf16 v[66:69], v[162:165], v[194:197], v[66:69]
	v_mfma_f32_16x16x32_bf16 v[118:121], v[158:161], v[174:177], v[118:121]
	v_mfma_f32_16x16x32_bf16 v[110:113], v[166:169], v[174:177], v[110:113]
	v_mfma_f32_16x16x32_bf16 v[102:105], v[158:161], v[182:185], v[102:105]
	v_mfma_f32_16x16x32_bf16 v[94:97], v[166:169], v[182:185], v[94:97]
	v_mfma_f32_16x16x32_bf16 v[86:89], v[158:161], v[190:193], v[86:89]
	v_mfma_f32_16x16x32_bf16 v[78:81], v[166:169], v[190:193], v[78:81]
	v_mfma_f32_16x16x32_bf16 v[70:73], v[158:161], v[198:201], v[70:73]
	v_mfma_f32_16x16x32_bf16 v[66:69], v[166:169], v[198:201], v[66:69]
	s_barrier
	s_add_i32 s18, s51, s30
	v_lshl_add_u64 v[202:203], s[22:23], 0, v[0:1]
	s_mov_b32 m0, s18
	ds_read_b128 v[170:173], v145 offset:16384
	ds_read_b128 v[174:177], v145 offset:17408
	ds_read_b128 v[178:181], v145 offset:18432
	ds_read_b128 v[182:185], v145 offset:19456
	ds_read_b128 v[186:189], v145 offset:20480
	ds_read_b128 v[190:193], v145 offset:21504
	ds_read_b128 v[194:197], v145 offset:22528
	ds_read_b128 v[198:201], v145 offset:23552
	global_load_lds_dwordx4 v[202:203], off
	s_add_i32 m0, s18, 0x2000
	s_add_u32 s18, s22, 0xb0000
	v_lshl_add_u64 v[204:205], s[22:23], 0, v[130:131]
	s_addc_u32 s19, s23, 0
	s_add_i32 s51, s52, s30
	global_load_lds_dwordx4 v[204:205], off
	v_lshl_add_u64 v[206:207], s[18:19], 0, v[0:1]
	s_mov_b32 m0, s51
	v_lshl_add_u64 v[210:211], s[24:25], 0, v[130:131]
	global_load_lds_dwordx4 v[206:207], off
	v_lshl_add_u64 v[206:207], s[18:19], 0, v[130:131]
	s_add_i32 m0, s51, 0x2000
	s_nop 0
	global_load_lds_dwordx4 v[206:207], off
	v_lshl_add_u64 v[206:207], s[24:25], 0, v[0:1]
	s_mov_b32 m0, s31
	s_nop 0
	global_load_lds_dwordx4 v[206:207], off
	s_mov_b32 m0, s36
	s_nop 0
	global_load_lds_dwordx4 v[210:211], off
	s_cmp_eq_u32 s50, -2
	s_cbranch_scc1 .Lp4b_f1
	s_waitcnt vmcnt(8)
	s_branch .Lp4b_j1

.Lp4b_j1:
	s_waitcnt lgkmcnt(0)
	s_barrier
	s_waitcnt lgkmcnt(0)
	v_mfma_f32_16x16x32_bf16 v[62:65], v[136:139], v[170:173], v[62:65]
	v_mfma_f32_16x16x32_bf16 v[58:61], v[146:149], v[170:173], v[58:61]
	v_mfma_f32_16x16x32_bf16 v[50:53], v[136:139], v[178:181], v[50:53]
	v_mfma_f32_16x16x32_bf16 v[42:45], v[146:149], v[178:181], v[42:45]
	v_mfma_f32_16x16x32_bf16 v[34:37], v[136:139], v[186:189], v[34:37]
	v_mfma_f32_16x16x32_bf16 v[26:29], v[146:149], v[186:189], v[26:29]
	v_mfma_f32_16x16x32_bf16 v[18:21], v[136:139], v[194:197], v[18:21]
	v_mfma_f32_16x16x32_bf16 v[10:13], v[146:149], v[194:197], v[10:13]
	v_mfma_f32_16x16x32_bf16 v[62:65], v[140:143], v[174:177], v[62:65]
	v_mfma_f32_16x16x32_bf16 v[58:61], v[150:153], v[174:177], v[58:61]
	v_mfma_f32_16x16x32_bf16 v[50:53], v[140:143], v[182:185], v[50:53]
	v_mfma_f32_16x16x32_bf16 v[42:45], v[150:153], v[182:185], v[42:45]
	v_mfma_f32_16x16x32_bf16 v[34:37], v[140:143], v[190:193], v[34:37]
	v_mfma_f32_16x16x32_bf16 v[26:29], v[150:153], v[190:193], v[26:29]
	v_mfma_f32_16x16x32_bf16 v[18:21], v[140:143], v[198:201], v[18:21]
	v_mfma_f32_16x16x32_bf16 v[10:13], v[150:153], v[198:201], v[10:13]
	v_mfma_f32_16x16x32_bf16 v[54:57], v[154:157], v[170:173], v[54:57]
	v_mfma_f32_16x16x32_bf16 v[46:49], v[162:165], v[170:173], v[46:49]
	v_mfma_f32_16x16x32_bf16 v[38:41], v[154:157], v[178:181], v[38:41]
	v_mfma_f32_16x16x32_bf16 v[30:33], v[162:165], v[178:181], v[30:33]
	v_mfma_f32_16x16x32_bf16 v[22:25], v[154:157], v[186:189], v[22:25]
	v_mfma_f32_16x16x32_bf16 v[14:17], v[162:165], v[186:189], v[14:17]
	v_mfma_f32_16x16x32_bf16 v[6:9], v[154:157], v[194:197], v[6:9]
	v_mfma_f32_16x16x32_bf16 v[2:5], v[162:165], v[194:197], v[2:5]
	v_mfma_f32_16x16x32_bf16 v[54:57], v[158:161], v[174:177], v[54:57]
	v_mfma_f32_16x16x32_bf16 v[46:49], v[166:169], v[174:177], v[46:49]
	v_mfma_f32_16x16x32_bf16 v[38:41], v[158:161], v[182:185], v[38:41]
	v_mfma_f32_16x16x32_bf16 v[30:33], v[166:169], v[182:185], v[30:33]
	v_mfma_f32_16x16x32_bf16 v[22:25], v[158:161], v[190:193], v[22:25]
	v_mfma_f32_16x16x32_bf16 v[14:17], v[166:169], v[190:193], v[14:17]
	v_mfma_f32_16x16x32_bf16 v[6:9], v[158:161], v[198:201], v[6:9]
	v_mfma_f32_16x16x32_bf16 v[2:5], v[166:169], v[198:201], v[2:5]
	s_barrier
	s_add_i32 s51, 0, 0x18000
	s_add_i32 s52, 0, 0x1c000
	v_add_u32_e32 v150, s51, v144
	v_add_u32_e32 v166, s52, v144
	ds_read_b128 v[136:139], v150
	ds_read_b128 v[140:143], v150 offset:1024
	ds_read_b128 v[146:149], v150 offset:2048
	ds_read_b128 v[150:153], v150 offset:3072
	ds_read_b128 v[154:157], v166
	ds_read_b128 v[158:161], v166 offset:1024
	ds_read_b128 v[162:165], v166 offset:2048
	ds_read_b128 v[166:169], v166 offset:3072
	s_add_u32 s18, s24, 0xb0000
	s_addc_u32 s19, s25, 0
	s_mov_b32 m0, s37
	v_lshl_add_u64 v[214:215], s[18:19], 0, v[0:1]
	ds_read_b128 v[170:173], v145 offset:32768
	ds_read_b128 v[174:177], v145 offset:33792
	ds_read_b128 v[178:181], v145 offset:34816
	ds_read_b128 v[182:185], v145 offset:35840
	ds_read_b128 v[186:189], v145 offset:36864
	ds_read_b128 v[190:193], v145 offset:37888
	ds_read_b128 v[194:197], v145 offset:38912
	ds_read_b128 v[198:201], v145 offset:39936
	global_load_lds_dwordx4 v[214:215], off
	v_lshl_add_u64 v[214:215], s[18:19], 0, v[130:131]
	s_mov_b32 m0, s38
	s_nop 0
	global_load_lds_dwordx4 v[214:215], off
	s_waitcnt vmcnt(8)
	s_waitcnt lgkmcnt(0)
	s_barrier
	s_waitcnt lgkmcnt(0)
	v_mfma_f32_16x16x32_bf16 v[126:129], v[136:139], v[170:173], v[126:129]
	v_mfma_f32_16x16x32_bf16 v[122:125], v[146:149], v[170:173], v[122:125]
	v_mfma_f32_16x16x32_bf16 v[114:117], v[136:139], v[178:181], v[114:117]
	v_mfma_f32_16x16x32_bf16 v[106:109], v[146:149], v[178:181], v[106:109]
	v_mfma_f32_16x16x32_bf16 v[98:101], v[136:139], v[186:189], v[98:101]
	v_mfma_f32_16x16x32_bf16 v[90:93], v[146:149], v[186:189], v[90:93]
	v_mfma_f32_16x16x32_bf16 v[82:85], v[136:139], v[194:197], v[82:85]
	v_mfma_f32_16x16x32_bf16 v[74:77], v[146:149], v[194:197], v[74:77]
	v_mfma_f32_16x16x32_bf16 v[126:129], v[140:143], v[174:177], v[126:129]
	v_mfma_f32_16x16x32_bf16 v[122:125], v[150:153], v[174:177], v[122:125]
	v_mfma_f32_16x16x32_bf16 v[114:117], v[140:143], v[182:185], v[114:117]
	v_mfma_f32_16x16x32_bf16 v[106:109], v[150:153], v[182:185], v[106:109]
	v_mfma_f32_16x16x32_bf16 v[98:101], v[140:143], v[190:193], v[98:101]
	v_mfma_f32_16x16x32_bf16 v[90:93], v[150:153], v[190:193], v[90:93]
	v_mfma_f32_16x16x32_bf16 v[82:85], v[140:143], v[198:201], v[82:85]
	v_mfma_f32_16x16x32_bf16 v[74:77], v[150:153], v[198:201], v[74:77]
	v_mfma_f32_16x16x32_bf16 v[118:121], v[154:157], v[170:173], v[118:121]
	v_mfma_f32_16x16x32_bf16 v[110:113], v[162:165], v[170:173], v[110:113]
	v_mfma_f32_16x16x32_bf16 v[102:105], v[154:157], v[178:181], v[102:105]
	v_mfma_f32_16x16x32_bf16 v[94:97], v[162:165], v[178:181], v[94:97]
	v_mfma_f32_16x16x32_bf16 v[86:89], v[154:157], v[186:189], v[86:89]
	v_mfma_f32_16x16x32_bf16 v[78:81], v[162:165], v[186:189], v[78:81]
	v_mfma_f32_16x16x32_bf16 v[70:73], v[154:157], v[194:197], v[70:73]
	v_mfma_f32_16x16x32_bf16 v[66:69], v[162:165], v[194:197], v[66:69]
	v_mfma_f32_16x16x32_bf16 v[118:121], v[158:161], v[174:177], v[118:121]
	v_mfma_f32_16x16x32_bf16 v[110:113], v[166:169], v[174:177], v[110:113]
	v_mfma_f32_16x16x32_bf16 v[102:105], v[158:161], v[182:185], v[102:105]
	v_mfma_f32_16x16x32_bf16 v[94:97], v[166:169], v[182:185], v[94:97]
	v_mfma_f32_16x16x32_bf16 v[86:89], v[158:161], v[190:193], v[86:89]
	v_mfma_f32_16x16x32_bf16 v[78:81], v[166:169], v[190:193], v[78:81]
	v_mfma_f32_16x16x32_bf16 v[70:73], v[158:161], v[198:201], v[70:73]
	v_mfma_f32_16x16x32_bf16 v[66:69], v[166:169], v[198:201], v[66:69]
	s_barrier
	s_add_i32 s18, s51, s30
	v_lshl_add_u64 v[202:203], v[202:203], 0, s[94:95]
	s_mov_b32 m0, s18
	ds_read_b128 v[170:173], v145 offset:49152
	ds_read_b128 v[174:177], v145 offset:50176
	ds_read_b128 v[178:181], v145 offset:51200
	ds_read_b128 v[182:185], v145 offset:52224
	ds_read_b128 v[186:189], v145 offset:53248
	ds_read_b128 v[190:193], v145 offset:54272
	ds_read_b128 v[194:197], v145 offset:55296
	ds_read_b128 v[198:201], v145 offset:56320
	global_load_lds_dwordx4 v[202:203], off
	s_add_i32 m0, s18, 0x2000
	s_add_u32 s18, s22, 0xb0080
	v_lshl_add_u64 v[202:203], v[204:205], 0, s[94:95]
	s_addc_u32 s19, s23, 0
	s_add_i32 s22, s52, s30
	global_load_lds_dwordx4 v[202:203], off
	v_lshl_add_u64 v[202:203], s[18:19], 0, v[0:1]
	s_mov_b32 m0, s22
	s_nop 0
	global_load_lds_dwordx4 v[202:203], off
	v_lshl_add_u64 v[202:203], s[18:19], 0, v[130:131]
	s_add_i32 m0, s22, 0x2000
	s_nop 0
	global_load_lds_dwordx4 v[202:203], off
	v_lshl_add_u64 v[202:203], v[206:207], 0, s[94:95]
	s_mov_b32 m0, s41
	s_nop 0
	global_load_lds_dwordx4 v[202:203], off
	v_lshl_add_u64 v[202:203], v[210:211], 0, s[94:95]
	s_mov_b32 m0, s42
	s_nop 0
	global_load_lds_dwordx4 v[202:203], off
	s_waitcnt vmcnt(8)
	s_waitcnt lgkmcnt(0)
	s_barrier
	s_waitcnt lgkmcnt(0)
	v_mfma_f32_16x16x32_bf16 v[62:65], v[136:139], v[170:173], v[62:65]
	v_mfma_f32_16x16x32_bf16 v[58:61], v[146:149], v[170:173], v[58:61]
	v_mfma_f32_16x16x32_bf16 v[50:53], v[136:139], v[178:181], v[50:53]
	v_mfma_f32_16x16x32_bf16 v[42:45], v[146:149], v[178:181], v[42:45]
	v_mfma_f32_16x16x32_bf16 v[34:37], v[136:139], v[186:189], v[34:37]
	v_mfma_f32_16x16x32_bf16 v[26:29], v[146:149], v[186:189], v[26:29]
	v_mfma_f32_16x16x32_bf16 v[18:21], v[136:139], v[194:197], v[18:21]
	v_mfma_f32_16x16x32_bf16 v[10:13], v[146:149], v[194:197], v[10:13]
	v_mfma_f32_16x16x32_bf16 v[62:65], v[140:143], v[174:177], v[62:65]
	v_mfma_f32_16x16x32_bf16 v[58:61], v[150:153], v[174:177], v[58:61]
	v_mfma_f32_16x16x32_bf16 v[50:53], v[140:143], v[182:185], v[50:53]
	v_mfma_f32_16x16x32_bf16 v[42:45], v[150:153], v[182:185], v[42:45]
	v_mfma_f32_16x16x32_bf16 v[34:37], v[140:143], v[190:193], v[34:37]
	v_mfma_f32_16x16x32_bf16 v[26:29], v[150:153], v[190:193], v[26:29]
	v_mfma_f32_16x16x32_bf16 v[18:21], v[140:143], v[198:201], v[18:21]
	v_mfma_f32_16x16x32_bf16 v[10:13], v[150:153], v[198:201], v[10:13]
	v_mfma_f32_16x16x32_bf16 v[54:57], v[154:157], v[170:173], v[54:57]
	v_mfma_f32_16x16x32_bf16 v[46:49], v[162:165], v[170:173], v[46:49]
	v_mfma_f32_16x16x32_bf16 v[38:41], v[154:157], v[178:181], v[38:41]
	v_mfma_f32_16x16x32_bf16 v[30:33], v[162:165], v[178:181], v[30:33]
	v_mfma_f32_16x16x32_bf16 v[22:25], v[154:157], v[186:189], v[22:25]
	v_mfma_f32_16x16x32_bf16 v[14:17], v[162:165], v[186:189], v[14:17]
	v_mfma_f32_16x16x32_bf16 v[6:9], v[154:157], v[194:197], v[6:9]
	v_mfma_f32_16x16x32_bf16 v[2:5], v[162:165], v[194:197], v[2:5]
	v_mfma_f32_16x16x32_bf16 v[54:57], v[158:161], v[174:177], v[54:57]
	v_mfma_f32_16x16x32_bf16 v[46:49], v[166:169], v[174:177], v[46:49]
	v_mfma_f32_16x16x32_bf16 v[38:41], v[158:161], v[182:185], v[38:41]
	v_mfma_f32_16x16x32_bf16 v[30:33], v[166:169], v[182:185], v[30:33]
	v_mfma_f32_16x16x32_bf16 v[22:25], v[158:161], v[190:193], v[22:25]
	v_mfma_f32_16x16x32_bf16 v[14:17], v[166:169], v[190:193], v[14:17]
	v_mfma_f32_16x16x32_bf16 v[6:9], v[158:161], v[198:201], v[6:9]
	v_mfma_f32_16x16x32_bf16 v[2:5], v[166:169], v[198:201], v[2:5]
	s_barrier
	s_add_i32 s50, s50, 2
	s_add_u32 s48, s48, 0x100
	s_addc_u32 s49, s49, 0
	s_cmp_gt_u32 s50, 41
	s_mov_b64 s[18:19], s[20:21]
	s_cbranch_scc0 .LBB0_1316
	s_and_b64 vcc, exec, s[14:15]
	s_cbranch_vccz .LBB0_1319
	s_barrier

.Lp4a_j0:
	s_waitcnt lgkmcnt(0)
	s_barrier
	s_waitcnt lgkmcnt(0)
	v_mfma_f32_16x16x32_bf16 v[126:129], v[136:139], v[172:175], v[126:129]
	v_mfma_f32_16x16x32_bf16 v[122:125], v[144:147], v[172:175], v[122:125]
	v_mfma_f32_16x16x32_bf16 v[114:117], v[136:139], v[180:183], v[114:117]
	v_mfma_f32_16x16x32_bf16 v[106:109], v[144:147], v[180:183], v[106:109]
	v_mfma_f32_16x16x32_bf16 v[98:101], v[136:139], v[188:191], v[98:101]
	v_mfma_f32_16x16x32_bf16 v[90:93], v[144:147], v[188:191], v[90:93]
	v_mfma_f32_16x16x32_bf16 v[82:85], v[136:139], v[196:199], v[82:85]
	v_mfma_f32_16x16x32_bf16 v[74:77], v[144:147], v[196:199], v[74:77]
	v_mfma_f32_16x16x32_bf16 v[126:129], v[140:143], v[176:179], v[126:129]
	v_mfma_f32_16x16x32_bf16 v[122:125], v[148:151], v[176:179], v[122:125]
	v_mfma_f32_16x16x32_bf16 v[114:117], v[140:143], v[184:187], v[114:117]
	v_mfma_f32_16x16x32_bf16 v[106:109], v[148:151], v[184:187], v[106:109]
	v_mfma_f32_16x16x32_bf16 v[98:101], v[140:143], v[192:195], v[98:101]
	v_mfma_f32_16x16x32_bf16 v[90:93], v[148:151], v[192:195], v[90:93]
	v_mfma_f32_16x16x32_bf16 v[82:85], v[140:143], v[200:203], v[82:85]
	v_mfma_f32_16x16x32_bf16 v[74:77], v[148:151], v[200:203], v[74:77]
	v_mfma_f32_16x16x32_bf16 v[118:121], v[152:155], v[172:175], v[118:121]
	v_mfma_f32_16x16x32_bf16 v[110:113], v[160:163], v[172:175], v[110:113]
	v_mfma_f32_16x16x32_bf16 v[102:105], v[152:155], v[180:183], v[102:105]
	v_mfma_f32_16x16x32_bf16 v[94:97], v[160:163], v[180:183], v[94:97]
	v_mfma_f32_16x16x32_bf16 v[86:89], v[152:155], v[188:191], v[86:89]
	v_mfma_f32_16x16x32_bf16 v[78:81], v[160:163], v[188:191], v[78:81]
	v_mfma_f32_16x16x32_bf16 v[70:73], v[152:155], v[196:199], v[70:73]
	v_mfma_f32_16x16x32_bf16 v[66:69], v[160:163], v[196:199], v[66:69]
	v_mfma_f32_16x16x32_bf16 v[118:121], v[156:159], v[176:179], v[118:121]
	v_mfma_f32_16x16x32_bf16 v[110:113], v[168:171], v[176:179], v[110:113]
	v_mfma_f32_16x16x32_bf16 v[102:105], v[156:159], v[184:187], v[102:105]
	v_mfma_f32_16x16x32_bf16 v[94:97], v[168:171], v[184:187], v[94:97]
	v_mfma_f32_16x16x32_bf16 v[86:89], v[156:159], v[192:195], v[86:89]
	v_mfma_f32_16x16x32_bf16 v[78:81], v[168:171], v[192:195], v[78:81]
	v_mfma_f32_16x16x32_bf16 v[70:73], v[156:159], v[200:203], v[70:73]
	v_mfma_f32_16x16x32_bf16 v[66:69], v[168:171], v[200:203], v[66:69]
	s_barrier
	s_add_i32 s14, s47, s22
	v_lshl_add_u64 v[164:165], s[18:19], 0, v[0:1]
	s_mov_b32 m0, s14
	ds_read_b128 v[172:175], v167 offset:16384
	ds_read_b128 v[176:179], v167 offset:17408
	ds_read_b128 v[180:183], v167 offset:18432
	ds_read_b128 v[184:187], v167 offset:19456
	ds_read_b128 v[188:191], v167 offset:20480
	ds_read_b128 v[192:195], v167 offset:21504
	ds_read_b128 v[196:199], v167 offset:22528
	ds_read_b128 v[200:203], v167 offset:23552
	global_load_lds_dwordx4 v[164:165], off
	s_add_i32 m0, s14, 0x2000
	s_add_u32 s14, s18, 0xb0000
	v_lshl_add_u64 v[204:205], s[18:19], 0, v[130:131]
	s_addc_u32 s15, s19, 0
	s_add_i32 s47, s48, s22
	global_load_lds_dwordx4 v[204:205], off
	v_lshl_add_u64 v[206:207], s[14:15], 0, v[0:1]
	s_mov_b32 m0, s47
	v_lshl_add_u64 v[210:211], s[20:21], 0, v[130:131]
	global_load_lds_dwordx4 v[206:207], off
	v_lshl_add_u64 v[206:207], s[14:15], 0, v[130:131]
	s_add_i32 m0, s47, 0x2000
	s_nop 0
	global_load_lds_dwordx4 v[206:207], off
	v_lshl_add_u64 v[206:207], s[20:21], 0, v[0:1]
	s_mov_b32 m0, s23
	s_nop 0
	global_load_lds_dwordx4 v[206:207], off
	s_mov_b32 m0, s24
	s_nop 0
	global_load_lds_dwordx4 v[210:211], off
	s_cmp_eq_u32 s46, -2
	s_cbranch_scc1 .Lp4a_f1
	s_waitcnt vmcnt(8)
	s_branch .Lp4a_j1

.Lp4a_j1:
	s_waitcnt lgkmcnt(0)
	s_barrier
	s_waitcnt lgkmcnt(0)
	v_mfma_f32_16x16x32_bf16 v[62:65], v[136:139], v[172:175], v[62:65]
	v_mfma_f32_16x16x32_bf16 v[58:61], v[144:147], v[172:175], v[58:61]
	v_mfma_f32_16x16x32_bf16 v[50:53], v[136:139], v[180:183], v[50:53]
	v_mfma_f32_16x16x32_bf16 v[42:45], v[144:147], v[180:183], v[42:45]
	v_mfma_f32_16x16x32_bf16 v[34:37], v[136:139], v[188:191], v[34:37]
	v_mfma_f32_16x16x32_bf16 v[26:29], v[144:147], v[188:191], v[26:29]
	v_mfma_f32_16x16x32_bf16 v[18:21], v[136:139], v[196:199], v[18:21]
	v_mfma_f32_16x16x32_bf16 v[10:13], v[144:147], v[196:199], v[10:13]
	v_mfma_f32_16x16x32_bf16 v[62:65], v[140:143], v[176:179], v[62:65]
	v_mfma_f32_16x16x32_bf16 v[58:61], v[148:151], v[176:179], v[58:61]
	v_mfma_f32_16x16x32_bf16 v[50:53], v[140:143], v[184:187], v[50:53]
	v_mfma_f32_16x16x32_bf16 v[42:45], v[148:151], v[184:187], v[42:45]
	v_mfma_f32_16x16x32_bf16 v[34:37], v[140:143], v[192:195], v[34:37]
	v_mfma_f32_16x16x32_bf16 v[26:29], v[148:151], v[192:195], v[26:29]
	v_mfma_f32_16x16x32_bf16 v[18:21], v[140:143], v[200:203], v[18:21]
	v_mfma_f32_16x16x32_bf16 v[10:13], v[148:151], v[200:203], v[10:13]
	v_mfma_f32_16x16x32_bf16 v[54:57], v[152:155], v[172:175], v[54:57]
	v_mfma_f32_16x16x32_bf16 v[46:49], v[160:163], v[172:175], v[46:49]
	v_mfma_f32_16x16x32_bf16 v[38:41], v[152:155], v[180:183], v[38:41]
	v_mfma_f32_16x16x32_bf16 v[30:33], v[160:163], v[180:183], v[30:33]
	v_mfma_f32_16x16x32_bf16 v[22:25], v[152:155], v[188:191], v[22:25]
	v_mfma_f32_16x16x32_bf16 v[14:17], v[160:163], v[188:191], v[14:17]
	v_mfma_f32_16x16x32_bf16 v[6:9], v[152:155], v[196:199], v[6:9]
	v_mfma_f32_16x16x32_bf16 v[2:5], v[160:163], v[196:199], v[2:5]
	v_mfma_f32_16x16x32_bf16 v[54:57], v[156:159], v[176:179], v[54:57]
	v_mfma_f32_16x16x32_bf16 v[46:49], v[168:171], v[176:179], v[46:49]
	v_mfma_f32_16x16x32_bf16 v[38:41], v[156:159], v[184:187], v[38:41]
	v_mfma_f32_16x16x32_bf16 v[30:33], v[168:171], v[184:187], v[30:33]
	v_mfma_f32_16x16x32_bf16 v[22:25], v[156:159], v[192:195], v[22:25]
	v_mfma_f32_16x16x32_bf16 v[14:17], v[168:171], v[192:195], v[14:17]
	v_mfma_f32_16x16x32_bf16 v[6:9], v[156:159], v[200:203], v[6:9]
	v_mfma_f32_16x16x32_bf16 v[2:5], v[168:171], v[200:203], v[2:5]
	s_barrier
	s_add_i32 s47, 0, 0x18000
	s_add_i32 s48, 0, 0x1c000
	v_add_u32_e32 v148, s47, v166
	v_add_u32_e32 v168, s48, v166
	ds_read_b128 v[136:139], v148
	ds_read_b128 v[140:143], v148 offset:1024
	ds_read_b128 v[144:147], v148 offset:2048
	ds_read_b128 v[148:151], v148 offset:3072
	ds_read_b128 v[152:155], v168
	ds_read_b128 v[156:159], v168 offset:1024
	ds_read_b128 v[160:163], v168 offset:2048
	ds_read_b128 v[168:171], v168 offset:3072
	s_add_u32 s14, s20, 0xb0000
	s_addc_u32 s15, s21, 0
	s_mov_b32 m0, s25
	v_lshl_add_u64 v[214:215], s[14:15], 0, v[0:1]
	ds_read_b128 v[172:175], v167 offset:32768
	ds_read_b128 v[176:179], v167 offset:33792
	ds_read_b128 v[180:183], v167 offset:34816
	ds_read_b128 v[184:187], v167 offset:35840
	ds_read_b128 v[188:191], v167 offset:36864
	ds_read_b128 v[192:195], v167 offset:37888
	ds_read_b128 v[196:199], v167 offset:38912
	ds_read_b128 v[200:203], v167 offset:39936
	global_load_lds_dwordx4 v[214:215], off
	v_lshl_add_u64 v[214:215], s[14:15], 0, v[130:131]
	s_mov_b32 m0, s30
	s_nop 0
	global_load_lds_dwordx4 v[214:215], off
	s_waitcnt vmcnt(8)
	s_waitcnt lgkmcnt(0)
	s_barrier
	s_waitcnt lgkmcnt(0)
	v_mfma_f32_16x16x32_bf16 v[126:129], v[136:139], v[172:175], v[126:129]
	v_mfma_f32_16x16x32_bf16 v[122:125], v[144:147], v[172:175], v[122:125]
	v_mfma_f32_16x16x32_bf16 v[114:117], v[136:139], v[180:183], v[114:117]
	v_mfma_f32_16x16x32_bf16 v[106:109], v[144:147], v[180:183], v[106:109]
	v_mfma_f32_16x16x32_bf16 v[98:101], v[136:139], v[188:191], v[98:101]
	v_mfma_f32_16x16x32_bf16 v[90:93], v[144:147], v[188:191], v[90:93]
	v_mfma_f32_16x16x32_bf16 v[82:85], v[136:139], v[196:199], v[82:85]
	v_mfma_f32_16x16x32_bf16 v[74:77], v[144:147], v[196:199], v[74:77]
	v_mfma_f32_16x16x32_bf16 v[126:129], v[140:143], v[176:179], v[126:129]
	v_mfma_f32_16x16x32_bf16 v[122:125], v[148:151], v[176:179], v[122:125]
	v_mfma_f32_16x16x32_bf16 v[114:117], v[140:143], v[184:187], v[114:117]
	v_mfma_f32_16x16x32_bf16 v[106:109], v[148:151], v[184:187], v[106:109]
	v_mfma_f32_16x16x32_bf16 v[98:101], v[140:143], v[192:195], v[98:101]
	v_mfma_f32_16x16x32_bf16 v[90:93], v[148:151], v[192:195], v[90:93]
	v_mfma_f32_16x16x32_bf16 v[82:85], v[140:143], v[200:203], v[82:85]
	v_mfma_f32_16x16x32_bf16 v[74:77], v[148:151], v[200:203], v[74:77]
	v_mfma_f32_16x16x32_bf16 v[118:121], v[152:155], v[172:175], v[118:121]
	v_mfma_f32_16x16x32_bf16 v[110:113], v[160:163], v[172:175], v[110:113]
	v_mfma_f32_16x16x32_bf16 v[102:105], v[152:155], v[180:183], v[102:105]
	v_mfma_f32_16x16x32_bf16 v[94:97], v[160:163], v[180:183], v[94:97]
	v_mfma_f32_16x16x32_bf16 v[86:89], v[152:155], v[188:191], v[86:89]
	v_mfma_f32_16x16x32_bf16 v[78:81], v[160:163], v[188:191], v[78:81]
	v_mfma_f32_16x16x32_bf16 v[70:73], v[152:155], v[196:199], v[70:73]
	v_mfma_f32_16x16x32_bf16 v[66:69], v[160:163], v[196:199], v[66:69]
	v_mfma_f32_16x16x32_bf16 v[118:121], v[156:159], v[176:179], v[118:121]
	v_mfma_f32_16x16x32_bf16 v[110:113], v[168:171], v[176:179], v[110:113]
	v_mfma_f32_16x16x32_bf16 v[102:105], v[156:159], v[184:187], v[102:105]
	v_mfma_f32_16x16x32_bf16 v[94:97], v[168:171], v[184:187], v[94:97]
	v_mfma_f32_16x16x32_bf16 v[86:89], v[156:159], v[192:195], v[86:89]
	v_mfma_f32_16x16x32_bf16 v[78:81], v[168:171], v[192:195], v[78:81]
	v_mfma_f32_16x16x32_bf16 v[70:73], v[156:159], v[200:203], v[70:73]
	v_mfma_f32_16x16x32_bf16 v[66:69], v[168:171], v[200:203], v[66:69]
	s_barrier
	s_add_i32 s14, s47, s22
	v_lshl_add_u64 v[164:165], v[164:165], 0, s[94:95]
	s_mov_b32 m0, s14
	ds_read_b128 v[172:175], v167 offset:49152
	ds_read_b128 v[176:179], v167 offset:50176
	ds_read_b128 v[180:183], v167 offset:51200
	ds_read_b128 v[184:187], v167 offset:52224
	ds_read_b128 v[188:191], v167 offset:53248
	ds_read_b128 v[192:195], v167 offset:54272
	ds_read_b128 v[196:199], v167 offset:55296
	ds_read_b128 v[200:203], v167 offset:56320
	global_load_lds_dwordx4 v[164:165], off
	s_add_i32 m0, s14, 0x2000
	s_add_u32 s14, s18, 0xb0080
	v_lshl_add_u64 v[164:165], v[204:205], 0, s[94:95]
	s_addc_u32 s15, s19, 0
	s_add_i32 s18, s48, s22
	global_load_lds_dwordx4 v[164:165], off
	v_lshl_add_u64 v[164:165], s[14:15], 0, v[0:1]
	s_mov_b32 m0, s18
	s_nop 0
	global_load_lds_dwordx4 v[164:165], off
	v_lshl_add_u64 v[164:165], s[14:15], 0, v[130:131]
	s_add_i32 m0, s18, 0x2000
	s_nop 0
	global_load_lds_dwordx4 v[164:165], off
	v_lshl_add_u64 v[164:165], v[206:207], 0, s[94:95]
	s_mov_b32 m0, s37
	s_nop 0
	global_load_lds_dwordx4 v[164:165], off
	v_lshl_add_u64 v[164:165], v[210:211], 0, s[94:95]
	s_mov_b32 m0, s38
	s_nop 0
	global_load_lds_dwordx4 v[164:165], off
	s_waitcnt vmcnt(8)
	s_waitcnt lgkmcnt(0)
	s_barrier
	s_waitcnt lgkmcnt(0)
	v_mfma_f32_16x16x32_bf16 v[62:65], v[136:139], v[172:175], v[62:65]
	v_mfma_f32_16x16x32_bf16 v[58:61], v[144:147], v[172:175], v[58:61]
	v_mfma_f32_16x16x32_bf16 v[50:53], v[136:139], v[180:183], v[50:53]
	v_mfma_f32_16x16x32_bf16 v[42:45], v[144:147], v[180:183], v[42:45]
	v_mfma_f32_16x16x32_bf16 v[34:37], v[136:139], v[188:191], v[34:37]
	v_mfma_f32_16x16x32_bf16 v[26:29], v[144:147], v[188:191], v[26:29]
	v_mfma_f32_16x16x32_bf16 v[18:21], v[136:139], v[196:199], v[18:21]
	v_mfma_f32_16x16x32_bf16 v[10:13], v[144:147], v[196:199], v[10:13]
	v_mfma_f32_16x16x32_bf16 v[62:65], v[140:143], v[176:179], v[62:65]
	v_mfma_f32_16x16x32_bf16 v[58:61], v[148:151], v[176:179], v[58:61]
	v_mfma_f32_16x16x32_bf16 v[50:53], v[140:143], v[184:187], v[50:53]
	v_mfma_f32_16x16x32_bf16 v[42:45], v[148:151], v[184:187], v[42:45]
	v_mfma_f32_16x16x32_bf16 v[34:37], v[140:143], v[192:195], v[34:37]
	v_mfma_f32_16x16x32_bf16 v[26:29], v[148:151], v[192:195], v[26:29]
	v_mfma_f32_16x16x32_bf16 v[18:21], v[140:143], v[200:203], v[18:21]
	v_mfma_f32_16x16x32_bf16 v[10:13], v[148:151], v[200:203], v[10:13]
	v_mfma_f32_16x16x32_bf16 v[54:57], v[152:155], v[172:175], v[54:57]
	v_mfma_f32_16x16x32_bf16 v[46:49], v[160:163], v[172:175], v[46:49]
	v_mfma_f32_16x16x32_bf16 v[38:41], v[152:155], v[180:183], v[38:41]
	v_mfma_f32_16x16x32_bf16 v[30:33], v[160:163], v[180:183], v[30:33]
	v_mfma_f32_16x16x32_bf16 v[22:25], v[152:155], v[188:191], v[22:25]
	v_mfma_f32_16x16x32_bf16 v[14:17], v[160:163], v[188:191], v[14:17]
	v_mfma_f32_16x16x32_bf16 v[6:9], v[152:155], v[196:199], v[6:9]
	v_mfma_f32_16x16x32_bf16 v[2:5], v[160:163], v[196:199], v[2:5]
	v_mfma_f32_16x16x32_bf16 v[54:57], v[156:159], v[176:179], v[54:57]
	v_mfma_f32_16x16x32_bf16 v[46:49], v[168:171], v[176:179], v[46:49]
	v_mfma_f32_16x16x32_bf16 v[38:41], v[156:159], v[184:187], v[38:41]
	v_mfma_f32_16x16x32_bf16 v[30:33], v[168:171], v[184:187], v[30:33]
	v_mfma_f32_16x16x32_bf16 v[22:25], v[156:159], v[192:195], v[22:25]
	v_mfma_f32_16x16x32_bf16 v[14:17], v[168:171], v[192:195], v[14:17]
	v_mfma_f32_16x16x32_bf16 v[6:9], v[156:159], v[200:203], v[6:9]
	v_mfma_f32_16x16x32_bf16 v[2:5], v[168:171], v[200:203], v[2:5]
	s_barrier
	s_add_i32 s46, s46, 2
	s_add_u32 s44, s44, 0x100
	s_addc_u32 s45, s45, 0
	s_cmp_gt_u32 s46, 41
	s_mov_b64 s[14:15], s[16:17]
	s_cbranch_scc0 .LBB0_1342
	s_and_b64 vcc, exec, s[10:11]
	s_cbranch_vccz .LBB0_1345
	s_barrier
